# residual-GEMM tile epilogue (5 instances): loads of the old residual for row blocks 1..7 hoisted into the dead A/B fragment registers with counted vmcnt waits instead of a load-wait-store ladder
# baseline (speedup 1.0000x reference)
; __device__ __forceinline__ unsigned pk2(float lo, float hi) { f32x2_t v = {lo, hi}; bf16x2_t b = __builtin_convertvector(v, bf16x2_t); return __builtin_bit_cast(unsigned, b); }
;     __device__ __forceinline__ void operator()(const AccT& acc, const Unit& u, int wr, int wc, int fr, int fq) const {
;         const int row0 = rowstart(u.pm) + wr * 64 + fr, col0 = u.pn * BM + wc * 32 + 8 * fq;
;         f32x4 bv[2][2], sv[2][2];
; #pragma unroll
;         for (int bj = 0; bj < 2; ++bj)
; #pragma unroll
;             for (int n = 0; n < 2; ++n) { bv[bj][n] = bias ? *(const f32x4*)(bias + col0 + bj * HALF + n * 4) : (f32x4){0.f, 0.f, 0.f, 0.f};
;                                           sv[bj][n] = scale ? *(const f32x4*)(scale + col0 + bj * HALF + n * 4) : (f32x4){1.f, 1.f, 1.f, 1.f}; }
; #pragma unroll
;         for (int ai = 0; ai < 2; ++ai)
; #pragma unroll
;             for (int m = 0; m < 4; ++m) { const int row = row0 + ai * HALF + m * 16;
;                 { bf16_t* hbp = HB + (size_t)row * DM + col0; float sq = 0.f;
; #pragma unroll
;                     for (int bj = 0; bj < 2; ++bj) { u32x4* p = (u32x4*)(hbp + bj * HALF); const u32x4 ho = *p;
;                         const f32x4 h0 = {bflo(ho.x), bfhi(ho.x), bflo(ho.y), bfhi(ho.y)}, h1 = {bflo(ho.z), bfhi(ho.z), bflo(ho.w), bfhi(ho.w)};
;                         const f32x4 a0 = h0 + (acc[ai][bj][m][0] + bv[bj][0]) * sv[bj][0], a1 = h1 + (acc[ai][bj][m][1] + bv[bj][1]) * sv[bj][1];
;                         u32x4 w; w.x = pk2(a0[0], a0[1]); w.y = pk2(a0[2], a0[3]); w.z = pk2(a1[0], a1[1]); w.w = pk2(a1[2], a1[3]); *p = w;
;                         sq += ((a0[0] * a0[0] + a0[1] * a0[1]) + (a0[2] * a0[2] + a0[3] * a0[3])) + ((a1[0] * a1[0] + a1[1] * a1[1]) + (a1[2] * a1[2] + a1[3] * a1[3])); }
;                     sq += __shfl_xor(sq, 16); sq += __shfl_xor(sq, 32);
;                     if (fq == 0) ss_out[(size_t)row * 16 + u.pn * 4 + wc] = sq; } }
.LBB0_363:
	s_ashr_i32 s29, s55, 2
	s_lshl_b32 s28, s55, 8
	s_and_b32 s29, s29, -16
	s_add_i32 s29, s29, s28
	v_add_u32_e32 v146, s29, v150
	v_ashrrev_i32_e32 v147, 31, v146
	v_lshl_or_b32 v144, s10, 8, v149
	v_lshlrev_b64 v[156:157], 11, v[146:147]
	v_ashrrev_i32_e32 v145, 31, v144
	v_lshl_add_u64 v[156:157], s[80:81], 0, v[156:157]
	v_lshl_add_u64 v[160:161], v[144:145], 1, v[156:157]
	global_load_dwordx4 v[156:159], v[160:161], off
	global_load_dwordx4 v[170:173], v[160:161], off offset:256
	v_mov_b32_e32 v252, v160
	v_mov_b32_e32 v253, v161
	s_mov_b32 s98, 0x8000
	s_mov_b32 s99, 0
	v_lshl_add_u64 v[254:255], v[252:253], 0, s[98:99]
	global_load_dwordx4 v[182:185], v[254:255], off
	global_load_dwordx4 v[186:189], v[254:255], off offset:256
	s_mov_b32 s98, 0x10000
	s_mov_b32 s99, 0
	v_lshl_add_u64 v[254:255], v[252:253], 0, s[98:99]
	global_load_dwordx4 v[190:193], v[254:255], off
	global_load_dwordx4 v[194:197], v[254:255], off offset:256
	s_mov_b32 s98, 0x18000
	s_mov_b32 s99, 0
	v_lshl_add_u64 v[254:255], v[252:253], 0, s[98:99]
	global_load_dwordx4 v[198:201], v[254:255], off
	global_load_dwordx4 v[202:205], v[254:255], off offset:256
	s_mov_b32 s98, 0x40000
	s_mov_b32 s99, 0
	v_lshl_add_u64 v[254:255], v[252:253], 0, s[98:99]
	global_load_dwordx4 v[206:209], v[254:255], off
	global_load_dwordx4 v[210:213], v[254:255], off offset:256
	s_mov_b32 s98, 0x48000
	s_mov_b32 s99, 0
	v_lshl_add_u64 v[254:255], v[252:253], 0, s[98:99]
	global_load_dwordx4 v[214:217], v[254:255], off
	global_load_dwordx4 v[218:221], v[254:255], off offset:256
	v_and_b32_e32 v174, 64, v154
	v_xor_b32_e32 v155, 16, v154
	v_pk_add_f32 v[166:167], v[114:115], 0 op_sel_hi:[1,0]
	v_add_u32_e32 v114, 64, v174
	v_xor_b32_e32 v175, 32, v154
	v_cmp_lt_i32_e32 vcc, v155, v114
	v_pk_add_f32 v[126:127], v[126:127], 0 op_sel_hi:[1,0]
	v_pk_add_f32 v[124:125], v[124:125], 0 op_sel_hi:[1,0]
	v_cndmask_b32_e32 v115, v154, v155, vcc
	v_cmp_lt_i32_e32 vcc, v175, v114
	v_pk_add_f32 v[122:123], v[122:123], 0 op_sel_hi:[1,0]
	v_pk_add_f32 v[120:121], v[120:121], 0 op_sel_hi:[1,0]
	v_pk_add_f32 v[118:119], v[118:119], 0 op_sel_hi:[1,0]
	v_pk_add_f32 v[116:117], v[116:117], 0 op_sel_hi:[1,0]
	v_pk_add_f32 v[112:113], v[112:113], 0 op_sel_hi:[1,0]
	v_cndmask_b32_e32 v114, v154, v175, vcc
	v_lshlrev_b32_e32 v115, 2, v115
	v_lshlrev_b32_e32 v114, 2, v114
	s_lshl_b32 s28, s10, 2
	s_ashr_i32 s29, s28, 31
	s_waitcnt vmcnt(10)
	v_lshlrev_b32_e32 v174, 16, v156
	v_and_b32_e32 v175, 0xffff0000, v156
	v_lshlrev_b32_e32 v156, 16, v157
	v_and_b32_e32 v157, 0xffff0000, v157
	v_lshlrev_b32_e32 v176, 16, v158
	v_and_b32_e32 v177, 0xffff0000, v158
	v_lshlrev_b32_e32 v158, 16, v159
	v_and_b32_e32 v159, 0xffff0000, v159
	v_lshlrev_b32_e32 v178, 16, v170
	v_and_b32_e32 v179, 0xffff0000, v170
	v_lshlrev_b32_e32 v170, 16, v171
	v_and_b32_e32 v171, 0xffff0000, v171
	v_lshlrev_b32_e32 v180, 16, v172
	v_and_b32_e32 v181, 0xffff0000, v172
	v_lshlrev_b32_e32 v172, 16, v173
	v_and_b32_e32 v173, 0xffff0000, v173
	v_pk_add_f32 v[126:127], v[126:127], v[156:157]
	v_pk_add_f32 v[124:125], v[124:125], v[174:175]
	v_pk_add_f32 v[122:123], v[122:123], v[158:159]
	v_pk_add_f32 v[120:121], v[120:121], v[176:177]
	v_pk_add_f32 v[156:157], v[118:119], v[170:171]
	v_pk_add_f32 v[158:159], v[116:117], v[178:179]
	v_pk_add_f32 v[166:167], v[166:167], v[172:173]
	v_pk_add_f32 v[170:171], v[112:113], v[180:181]
	v_cvt_pk_bf16_f32 v116, v124, v125
	v_cvt_pk_bf16_f32 v117, v126, v127
	v_mul_f32_e32 v112, v125, v125
	v_mul_f32_e32 v113, v127, v127
	v_mul_f32_e32 v118, v121, v121
	v_mul_f32_e32 v119, v123, v123
	v_mul_f32_e32 v125, v159, v159
	v_mul_f32_e32 v127, v157, v157
	v_mul_f32_e32 v155, v171, v171
	v_mul_f32_e32 v172, v167, v167
	v_fmac_f32_e32 v112, v124, v124
	v_fmac_f32_e32 v113, v126, v126
	v_fmac_f32_e32 v118, v120, v120
	v_fmac_f32_e32 v119, v122, v122
	v_fmac_f32_e32 v125, v158, v158
	v_fmac_f32_e32 v127, v156, v156
	v_fmac_f32_e32 v155, v170, v170
	v_fmac_f32_e32 v172, v166, v166
	v_add_f32_e32 v112, v112, v113
	v_add_f32_e32 v113, v118, v119
	v_add_f32_e32 v118, v125, v127
	v_add_f32_e32 v119, v155, v172
	v_add_f32_e32 v112, v112, v113
	v_add_f32_e32 v113, v118, v119
	v_add_f32_e32 v112, v112, v113
	ds_bpermute_b32 v113, v115, v112
	v_cvt_pk_bf16_f32 v118, v120, v121
	v_cvt_pk_bf16_f32 v119, v122, v123
	global_store_dwordx4 v[160:161], v[116:119], off
	s_waitcnt lgkmcnt(0)
	v_add_f32_e32 v112, v112, v113
	ds_bpermute_b32 v113, v114, v112
	v_cvt_pk_bf16_f32 v116, v158, v159
	v_cvt_pk_bf16_f32 v117, v156, v157
	v_cvt_pk_bf16_f32 v118, v170, v171
	v_cvt_pk_bf16_f32 v119, v166, v167
	global_store_dwordx4 v[160:161], v[116:119], off offset:256
	s_and_saveexec_b64 s[36:37], s[4:5]
	s_cbranch_execz .LBB0_365
	s_waitcnt lgkmcnt(0)
	v_add_f32_e32 v116, v112, v113
	v_lshlrev_b64 v[112:113], 6, v[146:147]
	v_lshl_add_u64 v[112:113], s[82:83], 0, v[112:113]
	v_lshl_add_u64 v[112:113], s[28:29], 2, v[112:113]
	s_lshl_b32 s10, s45, 2
	v_lshl_add_u64 v[112:113], v[112:113], 0, s[10:11]
	global_store_dword v[112:113], v116, off
; __device__ __forceinline__ unsigned pk2(float lo, float hi) { f32x2_t v = {lo, hi}; bf16x2_t b = __builtin_convertvector(v, bf16x2_t); return __builtin_bit_cast(unsigned, b); }
;     __device__ __forceinline__ void operator()(const AccT& acc, const Unit& u, int wr, int wc, int fr, int fq) const {
;     ...
;             for (int m = 0; m < 4; ++m) { const int row = row0 + ai * HALF + m * 16;
;                 { bf16_t* hbp = HB + (size_t)row * DM + col0; float sq = 0.f;
; #pragma unroll
;                     for (int bj = 0; bj < 2; ++bj) { u32x4* p = (u32x4*)(hbp + bj * HALF); const u32x4 ho = *p;
;                         const f32x4 h0 = {bflo(ho.x), bfhi(ho.x), bflo(ho.y), bfhi(ho.y)}, h1 = {bflo(ho.z), bfhi(ho.z), bflo(ho.w), bfhi(ho.w)};
;                         const f32x4 a0 = h0 + (acc[ai][bj][m][0] + bv[bj][0]) * sv[bj][0], a1 = h1 + (acc[ai][bj][m][1] + bv[bj][1]) * sv[bj][1];
;                         u32x4 w; w.x = pk2(a0[0], a0[1]); w.y = pk2(a0[2], a0[3]); w.z = pk2(a1[0], a1[1]); w.w = pk2(a1[2], a1[3]); *p = w;
;                         sq += ((a0[0] * a0[0] + a0[1] * a0[1]) + (a0[2] * a0[2] + a0[3] * a0[3])) + ((a1[0] * a1[0] + a1[1] * a1[1]) + (a1[2] * a1[2] + a1[3] * a1[3])); }
;                     sq += __shfl_xor(sq, 16); sq += __shfl_xor(sq, 32);
;                     if (fq == 0) ss_out[(size_t)row * 16 + u.pn * 4 + wc] = sq; } }
.LBB0_365:
	s_or_b64 exec, exec, s[36:37]
	v_add_u32_e32 v112, 16, v146
	s_waitcnt lgkmcnt(0)
	v_ashrrev_i32_e32 v113, 31, v112
	v_lshlrev_b64 v[116:117], 11, v[112:113]
	v_lshl_add_u64 v[116:117], s[80:81], 0, v[116:117]
	v_lshl_add_u64 v[124:125], v[144:145], 1, v[116:117]
	v_pk_add_f32 v[110:111], v[110:111], 0 op_sel_hi:[1,0]
	v_pk_add_f32 v[108:109], v[108:109], 0 op_sel_hi:[1,0]
	v_pk_add_f32 v[106:107], v[106:107], 0 op_sel_hi:[1,0]
	v_pk_add_f32 v[104:105], v[104:105], 0 op_sel_hi:[1,0]
	v_pk_add_f32 v[102:103], v[102:103], 0 op_sel_hi:[1,0]
	v_pk_add_f32 v[100:101], v[100:101], 0 op_sel_hi:[1,0]
	v_pk_add_f32 v[98:99], v[98:99], 0 op_sel_hi:[1,0]
	v_pk_add_f32 v[96:97], v[96:97], 0 op_sel_hi:[1,0]
	s_waitcnt vmcnt(11)
	v_lshlrev_b32_e32 v126, 16, v182
	v_and_b32_e32 v127, 0xffff0000, v182
	v_lshlrev_b32_e32 v116, 16, v183
	v_and_b32_e32 v117, 0xffff0000, v183
	v_lshlrev_b32_e32 v156, 16, v184
	v_and_b32_e32 v157, 0xffff0000, v184
	v_lshlrev_b32_e32 v118, 16, v185
	v_and_b32_e32 v119, 0xffff0000, v185
	s_waitcnt vmcnt(10)
	v_lshlrev_b32_e32 v158, 16, v186
	v_and_b32_e32 v159, 0xffff0000, v186
	v_lshlrev_b32_e32 v120, 16, v187
	v_and_b32_e32 v121, 0xffff0000, v187
	v_lshlrev_b32_e32 v160, 16, v188
	v_and_b32_e32 v161, 0xffff0000, v188
	v_lshlrev_b32_e32 v122, 16, v189
	v_and_b32_e32 v123, 0xffff0000, v189
	s_mov_b32 s98, 0x50000
	s_mov_b32 s99, 0
	v_lshl_add_u64 v[254:255], v[252:253], 0, s[98:99]
	global_load_dwordx4 v[182:185], v[254:255], off
	global_load_dwordx4 v[186:189], v[254:255], off offset:256
	v_pk_add_f32 v[110:111], v[110:111], v[116:117]
	v_pk_add_f32 v[108:109], v[108:109], v[126:127]
	v_pk_add_f32 v[106:107], v[106:107], v[118:119]
	v_pk_add_f32 v[104:105], v[104:105], v[156:157]
	v_pk_add_f32 v[102:103], v[102:103], v[120:121]
	v_pk_add_f32 v[100:101], v[100:101], v[158:159]
	v_pk_add_f32 v[116:117], v[98:99], v[122:123]
	v_pk_add_f32 v[118:119], v[96:97], v[160:161]
	v_cvt_pk_bf16_f32 v96, v108, v109
	v_cvt_pk_bf16_f32 v97, v110, v111
	v_mul_f32_e32 v98, v109, v109
	v_mul_f32_e32 v99, v111, v111
	v_mul_f32_e32 v109, v105, v105
	v_mul_f32_e32 v111, v107, v107
	v_mul_f32_e32 v120, v101, v101
	v_mul_f32_e32 v121, v103, v103
	v_mul_f32_e32 v122, v119, v119
	v_mul_f32_e32 v123, v117, v117
	v_fmac_f32_e32 v98, v108, v108
	v_fmac_f32_e32 v99, v110, v110
	v_fmac_f32_e32 v109, v104, v104
	v_fmac_f32_e32 v111, v106, v106
	v_fmac_f32_e32 v120, v100, v100
	v_fmac_f32_e32 v121, v102, v102
	v_fmac_f32_e32 v122, v118, v118
	v_fmac_f32_e32 v123, v116, v116
	v_add_f32_e32 v98, v98, v99
	v_add_f32_e32 v99, v109, v111
	v_add_f32_e32 v108, v120, v121
	v_add_f32_e32 v109, v122, v123
	v_add_f32_e32 v98, v98, v99
	v_add_f32_e32 v99, v108, v109
	v_add_f32_e32 v108, v98, v99
	ds_bpermute_b32 v109, v115, v108
	v_cvt_pk_bf16_f32 v98, v104, v105
	v_cvt_pk_bf16_f32 v99, v106, v107
	global_store_dwordx4 v[124:125], v[96:99], off
	s_waitcnt lgkmcnt(0)
	s_nop 0
	v_add_f32_e32 v96, v108, v109
	ds_bpermute_b32 v97, v114, v96
	v_cvt_pk_bf16_f32 v98, v100, v101
	v_cvt_pk_bf16_f32 v99, v102, v103
	v_cvt_pk_bf16_f32 v100, v118, v119
	v_cvt_pk_bf16_f32 v101, v116, v117
	global_store_dwordx4 v[124:125], v[98:101], off offset:256
	s_and_saveexec_b64 s[36:37], s[4:5]
	s_cbranch_execz .LBB0_367
	s_waitcnt lgkmcnt(0)
	v_add_f32_e32 v98, v96, v97
	v_lshlrev_b64 v[96:97], 6, v[112:113]
	v_lshl_add_u64 v[96:97], s[82:83], 0, v[96:97]
	v_lshl_add_u64 v[96:97], s[28:29], 2, v[96:97]
	s_lshl_b32 s10, s45, 2
	v_lshl_add_u64 v[96:97], v[96:97], 0, s[10:11]
	global_store_dword v[96:97], v98, off
.LBB0_367:
	s_or_b64 exec, exec, s[36:37]
	v_add_u32_e32 v96, 32, v146
	s_waitcnt lgkmcnt(0)
	v_ashrrev_i32_e32 v97, 31, v96
	v_lshlrev_b64 v[98:99], 11, v[96:97]
	v_lshl_add_u64 v[98:99], s[80:81], 0, v[98:99]
	v_lshl_add_u64 v[106:107], v[144:145], 1, v[98:99]
	v_pk_add_f32 v[94:95], v[94:95], 0 op_sel_hi:[1,0]
	v_pk_add_f32 v[92:93], v[92:93], 0 op_sel_hi:[1,0]
	v_pk_add_f32 v[90:91], v[90:91], 0 op_sel_hi:[1,0]
	v_pk_add_f32 v[88:89], v[88:89], 0 op_sel_hi:[1,0]
	v_pk_add_f32 v[86:87], v[86:87], 0 op_sel_hi:[1,0]
	v_pk_add_f32 v[84:85], v[84:85], 0 op_sel_hi:[1,0]
	v_pk_add_f32 v[82:83], v[82:83], 0 op_sel_hi:[1,0]
	v_pk_add_f32 v[80:81], v[80:81], 0 op_sel_hi:[1,0]
	s_waitcnt vmcnt(13)
	v_lshlrev_b32_e32 v108, 16, v190
	v_and_b32_e32 v109, 0xffff0000, v190
	v_lshlrev_b32_e32 v98, 16, v191
	v_and_b32_e32 v99, 0xffff0000, v191
	v_lshlrev_b32_e32 v110, 16, v192
	v_and_b32_e32 v111, 0xffff0000, v192
	v_lshlrev_b32_e32 v100, 16, v193
	v_and_b32_e32 v101, 0xffff0000, v193
	s_waitcnt vmcnt(12)
	v_lshlrev_b32_e32 v112, 16, v194
	v_and_b32_e32 v113, 0xffff0000, v194
	v_lshlrev_b32_e32 v102, 16, v195
	v_and_b32_e32 v103, 0xffff0000, v195
	v_lshlrev_b32_e32 v116, 16, v196
	v_and_b32_e32 v117, 0xffff0000, v196
	v_lshlrev_b32_e32 v104, 16, v197
	v_and_b32_e32 v105, 0xffff0000, v197
	s_mov_b32 s98, 0x58000
	s_mov_b32 s99, 0
	v_lshl_add_u64 v[254:255], v[252:253], 0, s[98:99]
	global_load_dwordx4 v[190:193], v[254:255], off
	global_load_dwordx4 v[194:197], v[254:255], off offset:256
	v_pk_add_f32 v[94:95], v[94:95], v[98:99]
	v_pk_add_f32 v[92:93], v[92:93], v[108:109]
	v_pk_add_f32 v[90:91], v[90:91], v[100:101]
	v_pk_add_f32 v[88:89], v[88:89], v[110:111]
	v_pk_add_f32 v[86:87], v[86:87], v[102:103]
	v_pk_add_f32 v[84:85], v[84:85], v[112:113]
	v_pk_add_f32 v[98:99], v[82:83], v[104:105]
	v_pk_add_f32 v[100:101], v[80:81], v[116:117]
	v_cvt_pk_bf16_f32 v80, v92, v93
	v_cvt_pk_bf16_f32 v81, v94, v95
	v_mul_f32_e32 v82, v93, v93
	v_mul_f32_e32 v83, v95, v95
	v_mul_f32_e32 v93, v89, v89
	v_mul_f32_e32 v95, v91, v91
	v_mul_f32_e32 v102, v85, v85
	v_mul_f32_e32 v103, v87, v87
	v_mul_f32_e32 v104, v101, v101
	v_mul_f32_e32 v105, v99, v99
	v_fmac_f32_e32 v82, v92, v92
	v_fmac_f32_e32 v83, v94, v94
	v_fmac_f32_e32 v93, v88, v88
	v_fmac_f32_e32 v95, v90, v90
	v_fmac_f32_e32 v102, v84, v84
	v_fmac_f32_e32 v103, v86, v86
	v_fmac_f32_e32 v104, v100, v100
	v_fmac_f32_e32 v105, v98, v98
	v_add_f32_e32 v82, v82, v83
	v_add_f32_e32 v83, v93, v95
	v_add_f32_e32 v92, v102, v103
	v_add_f32_e32 v93, v104, v105
	v_add_f32_e32 v82, v82, v83
	v_add_f32_e32 v83, v92, v93
	v_add_f32_e32 v92, v82, v83
	ds_bpermute_b32 v93, v115, v92
	v_cvt_pk_bf16_f32 v82, v88, v89
	v_cvt_pk_bf16_f32 v83, v90, v91
	global_store_dwordx4 v[106:107], v[80:83], off
	s_waitcnt lgkmcnt(0)
	s_nop 0
	v_add_f32_e32 v80, v92, v93
	ds_bpermute_b32 v81, v114, v80
	v_cvt_pk_bf16_f32 v82, v84, v85
	v_cvt_pk_bf16_f32 v83, v86, v87
	v_cvt_pk_bf16_f32 v84, v100, v101
	v_cvt_pk_bf16_f32 v85, v98, v99
	global_store_dwordx4 v[106:107], v[82:85], off offset:256
	s_and_saveexec_b64 s[36:37], s[4:5]
	s_cbranch_execz .LBB0_369
	s_waitcnt lgkmcnt(0)
	v_add_f32_e32 v82, v80, v81
	v_lshlrev_b64 v[80:81], 6, v[96:97]
	v_lshl_add_u64 v[80:81], s[82:83], 0, v[80:81]
	v_lshl_add_u64 v[80:81], s[28:29], 2, v[80:81]
	s_lshl_b32 s10, s45, 2
	v_lshl_add_u64 v[80:81], v[80:81], 0, s[10:11]
	global_store_dword v[80:81], v82, off
; __device__ __forceinline__ unsigned pk2(float lo, float hi) { f32x2_t v = {lo, hi}; bf16x2_t b = __builtin_convertvector(v, bf16x2_t); return __builtin_bit_cast(unsigned, b); }
;     __device__ __forceinline__ void operator()(const AccT& acc, const Unit& u, int wr, int wc, int fr, int fq) const {
;     ...
;             for (int m = 0; m < 4; ++m) { const int row = row0 + ai * HALF + m * 16;
;                 { bf16_t* hbp = HB + (size_t)row * DM + col0; float sq = 0.f;
; #pragma unroll
;                     for (int bj = 0; bj < 2; ++bj) { u32x4* p = (u32x4*)(hbp + bj * HALF); const u32x4 ho = *p;
;                         const f32x4 h0 = {bflo(ho.x), bfhi(ho.x), bflo(ho.y), bfhi(ho.y)}, h1 = {bflo(ho.z), bfhi(ho.z), bflo(ho.w), bfhi(ho.w)};
;                         const f32x4 a0 = h0 + (acc[ai][bj][m][0] + bv[bj][0]) * sv[bj][0], a1 = h1 + (acc[ai][bj][m][1] + bv[bj][1]) * sv[bj][1];
;                         u32x4 w; w.x = pk2(a0[0], a0[1]); w.y = pk2(a0[2], a0[3]); w.z = pk2(a1[0], a1[1]); w.w = pk2(a1[2], a1[3]); *p = w;
;                         sq += ((a0[0] * a0[0] + a0[1] * a0[1]) + (a0[2] * a0[2] + a0[3] * a0[3])) + ((a1[0] * a1[0] + a1[1] * a1[1]) + (a1[2] * a1[2] + a1[3] * a1[3])); }
;                     sq += __shfl_xor(sq, 16); sq += __shfl_xor(sq, 32);
;                     if (fq == 0) ss_out[(size_t)row * 16 + u.pn * 4 + wc] = sq; } }
.LBB0_369:
	s_or_b64 exec, exec, s[36:37]
	v_add_u32_e32 v80, 48, v146
	s_waitcnt lgkmcnt(0)
	v_ashrrev_i32_e32 v81, 31, v80
	v_lshlrev_b64 v[82:83], 11, v[80:81]
	v_lshl_add_u64 v[82:83], s[80:81], 0, v[82:83]
	v_lshl_add_u64 v[90:91], v[144:145], 1, v[82:83]
	v_pk_add_f32 v[78:79], v[78:79], 0 op_sel_hi:[1,0]
	v_pk_add_f32 v[76:77], v[76:77], 0 op_sel_hi:[1,0]
	v_pk_add_f32 v[74:75], v[74:75], 0 op_sel_hi:[1,0]
	v_pk_add_f32 v[72:73], v[72:73], 0 op_sel_hi:[1,0]
	v_pk_add_f32 v[70:71], v[70:71], 0 op_sel_hi:[1,0]
	v_pk_add_f32 v[68:69], v[68:69], 0 op_sel_hi:[1,0]
	v_pk_add_f32 v[66:67], v[66:67], 0 op_sel_hi:[1,0]
	v_pk_add_f32 v[64:65], v[64:65], 0 op_sel_hi:[1,0]
	s_waitcnt vmcnt(15)
	v_lshlrev_b32_e32 v92, 16, v198
	v_and_b32_e32 v93, 0xffff0000, v198
	v_lshlrev_b32_e32 v82, 16, v199
	v_and_b32_e32 v83, 0xffff0000, v199
	v_lshlrev_b32_e32 v94, 16, v200
	v_and_b32_e32 v95, 0xffff0000, v200
	v_lshlrev_b32_e32 v84, 16, v201
	v_and_b32_e32 v85, 0xffff0000, v201
	s_waitcnt vmcnt(14)
	v_lshlrev_b32_e32 v96, 16, v202
	v_and_b32_e32 v97, 0xffff0000, v202
	v_lshlrev_b32_e32 v86, 16, v203
	v_and_b32_e32 v87, 0xffff0000, v203
	v_lshlrev_b32_e32 v98, 16, v204
	v_and_b32_e32 v99, 0xffff0000, v204
	v_lshlrev_b32_e32 v88, 16, v205
	v_and_b32_e32 v89, 0xffff0000, v205
	v_pk_add_f32 v[78:79], v[78:79], v[82:83]
	v_pk_add_f32 v[76:77], v[76:77], v[92:93]
	v_pk_add_f32 v[74:75], v[74:75], v[84:85]
	v_pk_add_f32 v[72:73], v[72:73], v[94:95]
	v_pk_add_f32 v[70:71], v[70:71], v[86:87]
	v_pk_add_f32 v[68:69], v[68:69], v[96:97]
	v_pk_add_f32 v[82:83], v[66:67], v[88:89]
	v_pk_add_f32 v[84:85], v[64:65], v[98:99]
	v_cvt_pk_bf16_f32 v64, v76, v77
	v_cvt_pk_bf16_f32 v65, v78, v79
	v_mul_f32_e32 v66, v77, v77
	v_mul_f32_e32 v67, v79, v79
	v_mul_f32_e32 v77, v73, v73
	v_mul_f32_e32 v79, v75, v75
	v_mul_f32_e32 v86, v69, v69
	v_mul_f32_e32 v87, v71, v71
	v_mul_f32_e32 v88, v85, v85
	v_mul_f32_e32 v89, v83, v83
	v_fmac_f32_e32 v66, v76, v76
	v_fmac_f32_e32 v67, v78, v78
	v_fmac_f32_e32 v77, v72, v72
	v_fmac_f32_e32 v79, v74, v74
	v_fmac_f32_e32 v86, v68, v68
	v_fmac_f32_e32 v87, v70, v70
	v_fmac_f32_e32 v88, v84, v84
	v_fmac_f32_e32 v89, v82, v82
	v_add_f32_e32 v66, v66, v67
	v_add_f32_e32 v67, v77, v79
	v_add_f32_e32 v76, v86, v87
	v_add_f32_e32 v77, v88, v89
	v_add_f32_e32 v66, v66, v67
	v_add_f32_e32 v67, v76, v77
	v_add_f32_e32 v76, v66, v67
	ds_bpermute_b32 v77, v115, v76
	v_cvt_pk_bf16_f32 v66, v72, v73
	v_cvt_pk_bf16_f32 v67, v74, v75
	global_store_dwordx4 v[90:91], v[64:67], off
	s_waitcnt lgkmcnt(0)
	s_nop 0
	v_add_f32_e32 v64, v76, v77
	ds_bpermute_b32 v65, v114, v64
	v_cvt_pk_bf16_f32 v66, v68, v69
	v_cvt_pk_bf16_f32 v67, v70, v71
	v_cvt_pk_bf16_f32 v68, v84, v85
	v_cvt_pk_bf16_f32 v69, v82, v83
	global_store_dwordx4 v[90:91], v[66:69], off offset:256
	s_and_saveexec_b64 s[36:37], s[4:5]
	s_cbranch_execz .LBB0_371
	s_waitcnt lgkmcnt(0)
	v_add_f32_e32 v66, v64, v65
	v_lshlrev_b64 v[64:65], 6, v[80:81]
	v_lshl_add_u64 v[64:65], s[82:83], 0, v[64:65]
	v_lshl_add_u64 v[64:65], s[28:29], 2, v[64:65]
	s_lshl_b32 s10, s45, 2
	v_lshl_add_u64 v[64:65], v[64:65], 0, s[10:11]
	global_store_dword v[64:65], v66, off
.LBB0_371:
	s_or_b64 exec, exec, s[36:37]
	v_add_u32_e32 v64, 0x80, v146
	s_waitcnt lgkmcnt(0)
	v_ashrrev_i32_e32 v65, 31, v64
	v_lshlrev_b64 v[66:67], 11, v[64:65]
	v_lshl_add_u64 v[66:67], s[80:81], 0, v[66:67]
	v_lshl_add_u64 v[74:75], v[144:145], 1, v[66:67]
	v_pk_add_f32 v[62:63], v[62:63], 0 op_sel_hi:[1,0]
	v_pk_add_f32 v[60:61], v[60:61], 0 op_sel_hi:[1,0]
	v_pk_add_f32 v[58:59], v[58:59], 0 op_sel_hi:[1,0]
	v_pk_add_f32 v[56:57], v[56:57], 0 op_sel_hi:[1,0]
	v_pk_add_f32 v[54:55], v[54:55], 0 op_sel_hi:[1,0]
	v_pk_add_f32 v[52:53], v[52:53], 0 op_sel_hi:[1,0]
	v_pk_add_f32 v[50:51], v[50:51], 0 op_sel_hi:[1,0]
	v_pk_add_f32 v[48:49], v[48:49], 0 op_sel_hi:[1,0]
	s_waitcnt vmcnt(15)
	v_lshlrev_b32_e32 v76, 16, v206
	v_and_b32_e32 v77, 0xffff0000, v206
	v_lshlrev_b32_e32 v66, 16, v207
	v_and_b32_e32 v67, 0xffff0000, v207
	v_lshlrev_b32_e32 v78, 16, v208
	v_and_b32_e32 v79, 0xffff0000, v208
	v_lshlrev_b32_e32 v68, 16, v209
	v_and_b32_e32 v69, 0xffff0000, v209
	s_waitcnt vmcnt(14)
	v_lshlrev_b32_e32 v80, 16, v210
	v_and_b32_e32 v81, 0xffff0000, v210
	v_lshlrev_b32_e32 v70, 16, v211
	v_and_b32_e32 v71, 0xffff0000, v211
	v_lshlrev_b32_e32 v82, 16, v212
	v_and_b32_e32 v83, 0xffff0000, v212
	v_lshlrev_b32_e32 v72, 16, v213
	v_and_b32_e32 v73, 0xffff0000, v213
	v_pk_add_f32 v[62:63], v[62:63], v[66:67]
	v_pk_add_f32 v[60:61], v[60:61], v[76:77]
	v_pk_add_f32 v[58:59], v[58:59], v[68:69]
	v_pk_add_f32 v[56:57], v[56:57], v[78:79]
	v_pk_add_f32 v[54:55], v[54:55], v[70:71]
	v_pk_add_f32 v[52:53], v[52:53], v[80:81]
	v_pk_add_f32 v[66:67], v[50:51], v[72:73]
	v_pk_add_f32 v[68:69], v[48:49], v[82:83]
	v_cvt_pk_bf16_f32 v48, v60, v61
	v_cvt_pk_bf16_f32 v49, v62, v63
	v_mul_f32_e32 v50, v61, v61
	v_mul_f32_e32 v51, v63, v63
	v_mul_f32_e32 v61, v57, v57
	v_mul_f32_e32 v63, v59, v59
	v_mul_f32_e32 v70, v53, v53
	v_mul_f32_e32 v71, v55, v55
	v_mul_f32_e32 v72, v69, v69
	v_mul_f32_e32 v73, v67, v67
	v_fmac_f32_e32 v50, v60, v60
	v_fmac_f32_e32 v51, v62, v62
	v_fmac_f32_e32 v61, v56, v56
	v_fmac_f32_e32 v63, v58, v58
	v_fmac_f32_e32 v70, v52, v52
	v_fmac_f32_e32 v71, v54, v54
	v_fmac_f32_e32 v72, v68, v68
	v_fmac_f32_e32 v73, v66, v66
	v_add_f32_e32 v50, v50, v51
	v_add_f32_e32 v51, v61, v63
	v_add_f32_e32 v60, v70, v71
	v_add_f32_e32 v61, v72, v73
	v_add_f32_e32 v50, v50, v51
	v_add_f32_e32 v51, v60, v61
	v_add_f32_e32 v60, v50, v51
	ds_bpermute_b32 v61, v115, v60
	v_cvt_pk_bf16_f32 v50, v56, v57
	v_cvt_pk_bf16_f32 v51, v58, v59
	global_store_dwordx4 v[74:75], v[48:51], off
	s_waitcnt lgkmcnt(0)
	s_nop 0
	v_add_f32_e32 v48, v60, v61
	ds_bpermute_b32 v49, v114, v48
	v_cvt_pk_bf16_f32 v50, v52, v53
	v_cvt_pk_bf16_f32 v51, v54, v55
	v_cvt_pk_bf16_f32 v52, v68, v69
	v_cvt_pk_bf16_f32 v53, v66, v67
	global_store_dwordx4 v[74:75], v[50:53], off offset:256
	s_and_saveexec_b64 s[36:37], s[4:5]
	s_cbranch_execz .LBB0_373
	s_waitcnt lgkmcnt(0)
	v_add_f32_e32 v50, v48, v49
	v_lshlrev_b64 v[48:49], 6, v[64:65]
	v_lshl_add_u64 v[48:49], s[82:83], 0, v[48:49]
	v_lshl_add_u64 v[48:49], s[28:29], 2, v[48:49]
	s_lshl_b32 s10, s45, 2
	v_lshl_add_u64 v[48:49], v[48:49], 0, s[10:11]
	global_store_dword v[48:49], v50, off
; __device__ __forceinline__ unsigned pk2(float lo, float hi) { f32x2_t v = {lo, hi}; bf16x2_t b = __builtin_convertvector(v, bf16x2_t); return __builtin_bit_cast(unsigned, b); }
;     __device__ __forceinline__ void operator()(const AccT& acc, const Unit& u, int wr, int wc, int fr, int fq) const {
;     ...
;             for (int m = 0; m < 4; ++m) { const int row = row0 + ai * HALF + m * 16;
;                 { bf16_t* hbp = HB + (size_t)row * DM + col0; float sq = 0.f;
; #pragma unroll
;                     for (int bj = 0; bj < 2; ++bj) { u32x4* p = (u32x4*)(hbp + bj * HALF); const u32x4 ho = *p;
;                         const f32x4 h0 = {bflo(ho.x), bfhi(ho.x), bflo(ho.y), bfhi(ho.y)}, h1 = {bflo(ho.z), bfhi(ho.z), bflo(ho.w), bfhi(ho.w)};
;                         const f32x4 a0 = h0 + (acc[ai][bj][m][0] + bv[bj][0]) * sv[bj][0], a1 = h1 + (acc[ai][bj][m][1] + bv[bj][1]) * sv[bj][1];
;                         u32x4 w; w.x = pk2(a0[0], a0[1]); w.y = pk2(a0[2], a0[3]); w.z = pk2(a1[0], a1[1]); w.w = pk2(a1[2], a1[3]); *p = w;
;                         sq += ((a0[0] * a0[0] + a0[1] * a0[1]) + (a0[2] * a0[2] + a0[3] * a0[3])) + ((a1[0] * a1[0] + a1[1] * a1[1]) + (a1[2] * a1[2] + a1[3] * a1[3])); }
;                     sq += __shfl_xor(sq, 16); sq += __shfl_xor(sq, 32);
;                     if (fq == 0) ss_out[(size_t)row * 16 + u.pn * 4 + wc] = sq; } }
.LBB0_373:
	s_or_b64 exec, exec, s[36:37]
	v_add_u32_e32 v48, 0x90, v146
	s_waitcnt lgkmcnt(0)
	v_ashrrev_i32_e32 v49, 31, v48
	v_lshlrev_b64 v[50:51], 11, v[48:49]
	v_lshl_add_u64 v[50:51], s[80:81], 0, v[50:51]
	v_lshl_add_u64 v[58:59], v[144:145], 1, v[50:51]
	v_pk_add_f32 v[46:47], v[46:47], 0 op_sel_hi:[1,0]
	v_pk_add_f32 v[44:45], v[44:45], 0 op_sel_hi:[1,0]
	v_pk_add_f32 v[42:43], v[42:43], 0 op_sel_hi:[1,0]
	v_pk_add_f32 v[40:41], v[40:41], 0 op_sel_hi:[1,0]
	v_pk_add_f32 v[38:39], v[38:39], 0 op_sel_hi:[1,0]
	v_pk_add_f32 v[36:37], v[36:37], 0 op_sel_hi:[1,0]
	v_pk_add_f32 v[34:35], v[34:35], 0 op_sel_hi:[1,0]
	v_pk_add_f32 v[32:33], v[32:33], 0 op_sel_hi:[1,0]
	s_waitcnt vmcnt(15)
	v_lshlrev_b32_e32 v60, 16, v214
	v_and_b32_e32 v61, 0xffff0000, v214
	v_lshlrev_b32_e32 v50, 16, v215
	v_and_b32_e32 v51, 0xffff0000, v215
	v_lshlrev_b32_e32 v62, 16, v216
	v_and_b32_e32 v63, 0xffff0000, v216
	v_lshlrev_b32_e32 v52, 16, v217
	v_and_b32_e32 v53, 0xffff0000, v217
	s_waitcnt vmcnt(14)
	v_lshlrev_b32_e32 v64, 16, v218
	v_and_b32_e32 v65, 0xffff0000, v218
	v_lshlrev_b32_e32 v54, 16, v219
	v_and_b32_e32 v55, 0xffff0000, v219
	v_lshlrev_b32_e32 v66, 16, v220
	v_and_b32_e32 v67, 0xffff0000, v220
	v_lshlrev_b32_e32 v56, 16, v221
	v_and_b32_e32 v57, 0xffff0000, v221
	v_pk_add_f32 v[46:47], v[46:47], v[50:51]
	v_pk_add_f32 v[44:45], v[44:45], v[60:61]
	v_pk_add_f32 v[42:43], v[42:43], v[52:53]
	v_pk_add_f32 v[40:41], v[40:41], v[62:63]
	v_pk_add_f32 v[38:39], v[38:39], v[54:55]
	v_pk_add_f32 v[36:37], v[36:37], v[64:65]
	v_pk_add_f32 v[50:51], v[34:35], v[56:57]
	v_pk_add_f32 v[52:53], v[32:33], v[66:67]
	v_cvt_pk_bf16_f32 v32, v44, v45
	v_cvt_pk_bf16_f32 v33, v46, v47
	v_mul_f32_e32 v34, v45, v45
	v_mul_f32_e32 v35, v47, v47
	v_mul_f32_e32 v45, v41, v41
	v_mul_f32_e32 v47, v43, v43
	v_mul_f32_e32 v54, v37, v37
	v_mul_f32_e32 v55, v39, v39
	v_mul_f32_e32 v56, v53, v53
	v_mul_f32_e32 v57, v51, v51
	v_fmac_f32_e32 v34, v44, v44
	v_fmac_f32_e32 v35, v46, v46
	v_fmac_f32_e32 v45, v40, v40
	v_fmac_f32_e32 v47, v42, v42
	v_fmac_f32_e32 v54, v36, v36
	v_fmac_f32_e32 v55, v38, v38
	v_fmac_f32_e32 v56, v52, v52
	v_fmac_f32_e32 v57, v50, v50
	v_add_f32_e32 v34, v34, v35
	v_add_f32_e32 v35, v45, v47
	v_add_f32_e32 v44, v54, v55
	v_add_f32_e32 v45, v56, v57
	v_add_f32_e32 v34, v34, v35
	v_add_f32_e32 v35, v44, v45
	v_add_f32_e32 v44, v34, v35
	ds_bpermute_b32 v45, v115, v44
	v_cvt_pk_bf16_f32 v34, v40, v41
	v_cvt_pk_bf16_f32 v35, v42, v43
	global_store_dwordx4 v[58:59], v[32:35], off
	s_waitcnt lgkmcnt(0)
	s_nop 0
	v_add_f32_e32 v32, v44, v45
	ds_bpermute_b32 v33, v114, v32
	v_cvt_pk_bf16_f32 v34, v36, v37
	v_cvt_pk_bf16_f32 v35, v38, v39
	v_cvt_pk_bf16_f32 v36, v52, v53
	v_cvt_pk_bf16_f32 v37, v50, v51
	global_store_dwordx4 v[58:59], v[34:37], off offset:256
	s_and_saveexec_b64 s[36:37], s[4:5]
	s_cbranch_execz .LBB0_375
	s_waitcnt lgkmcnt(0)
	v_add_f32_e32 v34, v32, v33
	v_lshlrev_b64 v[32:33], 6, v[48:49]
	v_lshl_add_u64 v[32:33], s[82:83], 0, v[32:33]
	v_lshl_add_u64 v[32:33], s[28:29], 2, v[32:33]
	s_lshl_b32 s10, s45, 2
	v_lshl_add_u64 v[32:33], v[32:33], 0, s[10:11]
	global_store_dword v[32:33], v34, off
; __device__ __forceinline__ unsigned pk2(float lo, float hi) { f32x2_t v = {lo, hi}; bf16x2_t b = __builtin_convertvector(v, bf16x2_t); return __builtin_bit_cast(unsigned, b); }
;     __device__ __forceinline__ void operator()(const AccT& acc, const Unit& u, int wr, int wc, int fr, int fq) const {
;     ...
;             for (int m = 0; m < 4; ++m) { const int row = row0 + ai * HALF + m * 16;
;                 { bf16_t* hbp = HB + (size_t)row * DM + col0; float sq = 0.f;
; #pragma unroll
;                     for (int bj = 0; bj < 2; ++bj) { u32x4* p = (u32x4*)(hbp + bj * HALF); const u32x4 ho = *p;
;                         const f32x4 h0 = {bflo(ho.x), bfhi(ho.x), bflo(ho.y), bfhi(ho.y)}, h1 = {bflo(ho.z), bfhi(ho.z), bflo(ho.w), bfhi(ho.w)};
;                         const f32x4 a0 = h0 + (acc[ai][bj][m][0] + bv[bj][0]) * sv[bj][0], a1 = h1 + (acc[ai][bj][m][1] + bv[bj][1]) * sv[bj][1];
;                         u32x4 w; w.x = pk2(a0[0], a0[1]); w.y = pk2(a0[2], a0[3]); w.z = pk2(a1[0], a1[1]); w.w = pk2(a1[2], a1[3]); *p = w;
;                         sq += ((a0[0] * a0[0] + a0[1] * a0[1]) + (a0[2] * a0[2] + a0[3] * a0[3])) + ((a1[0] * a1[0] + a1[1] * a1[1]) + (a1[2] * a1[2] + a1[3] * a1[3])); }
;                     sq += __shfl_xor(sq, 16); sq += __shfl_xor(sq, 32);
;                     if (fq == 0) ss_out[(size_t)row * 16 + u.pn * 4 + wc] = sq; } }
.LBB0_375:
	s_or_b64 exec, exec, s[36:37]
	v_add_u32_e32 v32, 0xa0, v146
	s_waitcnt lgkmcnt(0)
	v_ashrrev_i32_e32 v33, 31, v32
	v_lshlrev_b64 v[34:35], 11, v[32:33]
	v_lshl_add_u64 v[34:35], s[80:81], 0, v[34:35]
	v_lshl_add_u64 v[42:43], v[144:145], 1, v[34:35]
	v_pk_add_f32 v[30:31], v[30:31], 0 op_sel_hi:[1,0]
	v_pk_add_f32 v[28:29], v[28:29], 0 op_sel_hi:[1,0]
	v_pk_add_f32 v[26:27], v[26:27], 0 op_sel_hi:[1,0]
	v_pk_add_f32 v[24:25], v[24:25], 0 op_sel_hi:[1,0]
	v_pk_add_f32 v[22:23], v[22:23], 0 op_sel_hi:[1,0]
	v_pk_add_f32 v[20:21], v[20:21], 0 op_sel_hi:[1,0]
	v_pk_add_f32 v[18:19], v[18:19], 0 op_sel_hi:[1,0]
	v_pk_add_f32 v[16:17], v[16:17], 0 op_sel_hi:[1,0]
	s_waitcnt vmcnt(13)
	v_lshlrev_b32_e32 v44, 16, v182
	v_and_b32_e32 v45, 0xffff0000, v182
	v_lshlrev_b32_e32 v34, 16, v183
	v_and_b32_e32 v35, 0xffff0000, v183
	v_lshlrev_b32_e32 v46, 16, v184
	v_and_b32_e32 v47, 0xffff0000, v184
	v_lshlrev_b32_e32 v36, 16, v185
	v_and_b32_e32 v37, 0xffff0000, v185
	s_waitcnt vmcnt(12)
	v_lshlrev_b32_e32 v48, 16, v186
	v_and_b32_e32 v49, 0xffff0000, v186
	v_lshlrev_b32_e32 v38, 16, v187
	v_and_b32_e32 v39, 0xffff0000, v187
	v_lshlrev_b32_e32 v50, 16, v188
	v_and_b32_e32 v51, 0xffff0000, v188
	v_lshlrev_b32_e32 v40, 16, v189
	v_and_b32_e32 v41, 0xffff0000, v189
	v_pk_add_f32 v[30:31], v[30:31], v[34:35]
	v_pk_add_f32 v[28:29], v[28:29], v[44:45]
	v_pk_add_f32 v[26:27], v[26:27], v[36:37]
	v_pk_add_f32 v[24:25], v[24:25], v[46:47]
	v_pk_add_f32 v[22:23], v[22:23], v[38:39]
	v_pk_add_f32 v[20:21], v[20:21], v[48:49]
	v_pk_add_f32 v[34:35], v[18:19], v[40:41]
	v_pk_add_f32 v[36:37], v[16:17], v[50:51]
	v_cvt_pk_bf16_f32 v16, v28, v29
	v_cvt_pk_bf16_f32 v17, v30, v31
	v_mul_f32_e32 v18, v29, v29
	v_mul_f32_e32 v19, v31, v31
	v_mul_f32_e32 v29, v25, v25
	v_mul_f32_e32 v31, v27, v27
	v_mul_f32_e32 v38, v21, v21
	v_mul_f32_e32 v39, v23, v23
	v_mul_f32_e32 v40, v37, v37
	v_mul_f32_e32 v41, v35, v35
	v_fmac_f32_e32 v18, v28, v28
	v_fmac_f32_e32 v19, v30, v30
	v_fmac_f32_e32 v29, v24, v24
	v_fmac_f32_e32 v31, v26, v26
	v_fmac_f32_e32 v38, v20, v20
	v_fmac_f32_e32 v39, v22, v22
	v_fmac_f32_e32 v40, v36, v36
	v_fmac_f32_e32 v41, v34, v34
	v_add_f32_e32 v18, v18, v19
	v_add_f32_e32 v19, v29, v31
	v_add_f32_e32 v28, v38, v39
	v_add_f32_e32 v29, v40, v41
	v_add_f32_e32 v18, v18, v19
	v_add_f32_e32 v19, v28, v29
	v_add_f32_e32 v28, v18, v19
	ds_bpermute_b32 v29, v115, v28
	v_cvt_pk_bf16_f32 v18, v24, v25
	v_cvt_pk_bf16_f32 v19, v26, v27
	global_store_dwordx4 v[42:43], v[16:19], off
	s_waitcnt lgkmcnt(0)
	s_nop 0
	v_add_f32_e32 v16, v28, v29
	ds_bpermute_b32 v17, v114, v16
	v_cvt_pk_bf16_f32 v18, v20, v21
	v_cvt_pk_bf16_f32 v19, v22, v23
	v_cvt_pk_bf16_f32 v20, v36, v37
	v_cvt_pk_bf16_f32 v21, v34, v35
	global_store_dwordx4 v[42:43], v[18:21], off offset:256
	s_and_saveexec_b64 s[36:37], s[4:5]
	s_cbranch_execz .LBB0_377
	s_waitcnt lgkmcnt(0)
	v_add_f32_e32 v18, v16, v17
	v_lshlrev_b64 v[16:17], 6, v[32:33]
	v_lshl_add_u64 v[16:17], s[82:83], 0, v[16:17]
	v_lshl_add_u64 v[16:17], s[28:29], 2, v[16:17]
	s_lshl_b32 s10, s45, 2
	v_lshl_add_u64 v[16:17], v[16:17], 0, s[10:11]
	global_store_dword v[16:17], v18, off
.LBB0_377:
	s_or_b64 exec, exec, s[36:37]
	v_add_u32_e32 v16, 0xb0, v146
	s_waitcnt lgkmcnt(0)
	v_ashrrev_i32_e32 v17, 31, v16
	v_lshlrev_b64 v[18:19], 11, v[16:17]
	v_lshl_add_u64 v[18:19], s[80:81], 0, v[18:19]
	v_lshl_add_u64 v[26:27], v[144:145], 1, v[18:19]
	v_pk_add_f32 v[14:15], v[14:15], 0 op_sel_hi:[1,0]
	v_pk_add_f32 v[12:13], v[12:13], 0 op_sel_hi:[1,0]
	v_pk_add_f32 v[10:11], v[10:11], 0 op_sel_hi:[1,0]
	v_pk_add_f32 v[8:9], v[8:9], 0 op_sel_hi:[1,0]
	v_pk_add_f32 v[6:7], v[6:7], 0 op_sel_hi:[1,0]
	v_pk_add_f32 v[4:5], v[4:5], 0 op_sel_hi:[1,0]
	v_pk_add_f32 v[2:3], v[2:3], 0 op_sel_hi:[1,0]
	v_pk_add_f32 v[0:1], v[0:1], 0 op_sel_hi:[1,0]
	s_waitcnt vmcnt(11)
	v_lshlrev_b32_e32 v28, 16, v190
	v_and_b32_e32 v29, 0xffff0000, v190
	v_lshlrev_b32_e32 v18, 16, v191
	v_and_b32_e32 v19, 0xffff0000, v191
	v_lshlrev_b32_e32 v30, 16, v192
	v_and_b32_e32 v31, 0xffff0000, v192
	v_lshlrev_b32_e32 v20, 16, v193
	v_and_b32_e32 v21, 0xffff0000, v193
	s_waitcnt vmcnt(10)
	v_lshlrev_b32_e32 v32, 16, v194
	v_and_b32_e32 v33, 0xffff0000, v194
	v_lshlrev_b32_e32 v22, 16, v195
	v_and_b32_e32 v23, 0xffff0000, v195
	v_lshlrev_b32_e32 v34, 16, v196
	v_and_b32_e32 v35, 0xffff0000, v196
	v_lshlrev_b32_e32 v24, 16, v197
	v_and_b32_e32 v25, 0xffff0000, v197
	v_pk_add_f32 v[14:15], v[14:15], v[18:19]
	v_pk_add_f32 v[12:13], v[12:13], v[28:29]
	v_pk_add_f32 v[10:11], v[10:11], v[20:21]
	v_pk_add_f32 v[8:9], v[8:9], v[30:31]
	v_pk_add_f32 v[6:7], v[6:7], v[22:23]
	v_pk_add_f32 v[4:5], v[4:5], v[32:33]
	v_pk_add_f32 v[18:19], v[2:3], v[24:25]
	v_pk_add_f32 v[20:21], v[0:1], v[34:35]
	v_cvt_pk_bf16_f32 v0, v12, v13
	v_cvt_pk_bf16_f32 v1, v14, v15
	v_mul_f32_e32 v2, v13, v13
	v_mul_f32_e32 v3, v15, v15
	v_mul_f32_e32 v13, v9, v9
	v_mul_f32_e32 v15, v11, v11
	v_mul_f32_e32 v22, v5, v5
	v_mul_f32_e32 v23, v7, v7
	v_mul_f32_e32 v24, v21, v21
	v_mul_f32_e32 v25, v19, v19
	v_fmac_f32_e32 v2, v12, v12
	v_fmac_f32_e32 v3, v14, v14
	v_fmac_f32_e32 v13, v8, v8
	v_fmac_f32_e32 v15, v10, v10
	v_fmac_f32_e32 v22, v4, v4
	v_fmac_f32_e32 v23, v6, v6
	v_fmac_f32_e32 v24, v20, v20
	v_fmac_f32_e32 v25, v18, v18
	v_add_f32_e32 v2, v2, v3
	v_add_f32_e32 v3, v13, v15
	v_add_f32_e32 v12, v22, v23
	v_add_f32_e32 v13, v24, v25
	v_add_f32_e32 v2, v2, v3
	v_add_f32_e32 v3, v12, v13
	v_add_f32_e32 v12, v2, v3
	ds_bpermute_b32 v13, v115, v12
	v_cvt_pk_bf16_f32 v2, v8, v9
	v_cvt_pk_bf16_f32 v3, v10, v11
	global_store_dwordx4 v[26:27], v[0:3], off
	s_waitcnt lgkmcnt(0)
	s_nop 0
	v_add_f32_e32 v0, v12, v13
	ds_bpermute_b32 v1, v114, v0
	v_cvt_pk_bf16_f32 v2, v4, v5
	v_cvt_pk_bf16_f32 v3, v6, v7
	v_cvt_pk_bf16_f32 v4, v20, v21
	v_cvt_pk_bf16_f32 v5, v18, v19
	global_store_dwordx4 v[26:27], v[2:5], off offset:256
	s_and_saveexec_b64 s[36:37], s[4:5]
	s_cbranch_execz .LBB0_379
	s_waitcnt lgkmcnt(0)
	v_add_f32_e32 v2, v0, v1
	v_lshlrev_b64 v[0:1], 6, v[16:17]
	v_lshl_add_u64 v[0:1], s[82:83], 0, v[0:1]
	v_lshl_add_u64 v[0:1], s[28:29], 2, v[0:1]
	s_lshl_b32 s10, s45, 2
	v_lshl_add_u64 v[0:1], v[0:1], 0, s[10:11]
	global_store_dword v[0:1], v2, off

; __device__ __forceinline__ unsigned pk2(float lo, float hi) { f32x2_t v = {lo, hi}; bf16x2_t b = __builtin_convertvector(v, bf16x2_t); return __builtin_bit_cast(unsigned, b); }
;     __device__ __forceinline__ void operator()(const AccT& acc, const Unit& u, int wr, int wc, int fr, int fq) const {
;         const int row0 = rowstart(u.pm) + wr * 64 + fr, col0 = u.pn * BM + wc * 32 + 8 * fq;
;         f32x4 bv[2][2], sv[2][2];
; #pragma unroll
;         for (int bj = 0; bj < 2; ++bj)
; #pragma unroll
;             for (int n = 0; n < 2; ++n) { bv[bj][n] = bias ? *(const f32x4*)(bias + col0 + bj * HALF + n * 4) : (f32x4){0.f, 0.f, 0.f, 0.f};
;                                           sv[bj][n] = scale ? *(const f32x4*)(scale + col0 + bj * HALF + n * 4) : (f32x4){1.f, 1.f, 1.f, 1.f}; }
; #pragma unroll
;         for (int ai = 0; ai < 2; ++ai)
; #pragma unroll
;             for (int m = 0; m < 4; ++m) { const int row = row0 + ai * HALF + m * 16;
;                 { bf16_t* hbp = HB + (size_t)row * DM + col0; float sq = 0.f;
; #pragma unroll
;                     for (int bj = 0; bj < 2; ++bj) { u32x4* p = (u32x4*)(hbp + bj * HALF); const u32x4 ho = *p;
;                         const f32x4 h0 = {bflo(ho.x), bfhi(ho.x), bflo(ho.y), bfhi(ho.y)}, h1 = {bflo(ho.z), bfhi(ho.z), bflo(ho.w), bfhi(ho.w)};
;                         const f32x4 a0 = h0 + (acc[ai][bj][m][0] + bv[bj][0]) * sv[bj][0], a1 = h1 + (acc[ai][bj][m][1] + bv[bj][1]) * sv[bj][1];
;                         u32x4 w; w.x = pk2(a0[0], a0[1]); w.y = pk2(a0[2], a0[3]); w.z = pk2(a1[0], a1[1]); w.w = pk2(a1[2], a1[3]); *p = w;
;                         sq += ((a0[0] * a0[0] + a0[1] * a0[1]) + (a0[2] * a0[2] + a0[3] * a0[3])) + ((a1[0] * a1[0] + a1[1] * a1[1]) + (a1[2] * a1[2] + a1[3] * a1[3])); }
;                     sq += __shfl_xor(sq, 16); sq += __shfl_xor(sq, 32);
;                     if (fq == 0) ss_out[(size_t)row * 16 + u.pn * 4 + wc] = sq; } }
.LBB0_805:
	s_ashr_i32 s1, s54, 2
	s_lshl_b32 s0, s54, 8
	s_and_b32 s1, s1, -16
	s_add_i32 s1, s1, s0
	v_add_u32_e32 v146, s1, v150
	v_ashrrev_i32_e32 v147, 31, v146
	v_lshl_or_b32 v144, s10, 8, v149
	v_lshlrev_b64 v[156:157], 11, v[146:147]
	v_ashrrev_i32_e32 v145, 31, v144
	v_lshl_add_u64 v[156:157], s[80:81], 0, v[156:157]
	v_lshl_add_u64 v[160:161], v[144:145], 1, v[156:157]
	global_load_dwordx4 v[156:159], v[160:161], off
	global_load_dwordx4 v[168:171], v[160:161], off offset:256
	v_mov_b32_e32 v252, v160
	v_mov_b32_e32 v253, v161
	s_mov_b32 s98, 0x8000
	s_mov_b32 s99, 0
	v_lshl_add_u64 v[254:255], v[252:253], 0, s[98:99]
	global_load_dwordx4 v[184:187], v[254:255], off
	global_load_dwordx4 v[188:191], v[254:255], off offset:256
	s_mov_b32 s98, 0x10000
	s_mov_b32 s99, 0
	v_lshl_add_u64 v[254:255], v[252:253], 0, s[98:99]
	global_load_dwordx4 v[192:195], v[254:255], off
	global_load_dwordx4 v[196:199], v[254:255], off offset:256
	s_mov_b32 s98, 0x18000
	s_mov_b32 s99, 0
	v_lshl_add_u64 v[254:255], v[252:253], 0, s[98:99]
	global_load_dwordx4 v[200:203], v[254:255], off
	global_load_dwordx4 v[204:207], v[254:255], off offset:256
	s_mov_b32 s98, 0x40000
	s_mov_b32 s99, 0
	v_lshl_add_u64 v[254:255], v[252:253], 0, s[98:99]
	global_load_dwordx4 v[208:211], v[254:255], off
	global_load_dwordx4 v[212:215], v[254:255], off offset:256
	s_mov_b32 s98, 0x48000
	s_mov_b32 s99, 0
	v_lshl_add_u64 v[254:255], v[252:253], 0, s[98:99]
	global_load_dwordx4 v[216:219], v[254:255], off
	global_load_dwordx4 v[220:223], v[254:255], off offset:256
	v_and_b32_e32 v167, 64, v154
	v_xor_b32_e32 v155, 16, v154
	v_pk_add_f32 v[172:173], v[114:115], 0 op_sel_hi:[1,0]
	v_add_u32_e32 v114, 64, v167
	v_xor_b32_e32 v174, 32, v154
	v_cmp_lt_i32_e32 vcc, v155, v114
	v_pk_add_f32 v[126:127], v[126:127], 0 op_sel_hi:[1,0]
	v_pk_add_f32 v[124:125], v[124:125], 0 op_sel_hi:[1,0]
	v_cndmask_b32_e32 v115, v154, v155, vcc
	v_cmp_lt_i32_e32 vcc, v174, v114
	v_pk_add_f32 v[122:123], v[122:123], 0 op_sel_hi:[1,0]
	v_pk_add_f32 v[120:121], v[120:121], 0 op_sel_hi:[1,0]
	v_pk_add_f32 v[118:119], v[118:119], 0 op_sel_hi:[1,0]
	v_pk_add_f32 v[116:117], v[116:117], 0 op_sel_hi:[1,0]
	v_pk_add_f32 v[112:113], v[112:113], 0 op_sel_hi:[1,0]
	v_cndmask_b32_e32 v114, v154, v174, vcc
	v_lshlrev_b32_e32 v115, 2, v115
	v_lshlrev_b32_e32 v114, 2, v114
	s_lshl_b32 s0, s10, 2
	s_ashr_i32 s1, s0, 31
	s_waitcnt vmcnt(10)
	v_lshlrev_b32_e32 v174, 16, v156
	v_and_b32_e32 v175, 0xffff0000, v156
	v_lshlrev_b32_e32 v156, 16, v157
	v_and_b32_e32 v157, 0xffff0000, v157
	v_lshlrev_b32_e32 v176, 16, v158
	v_and_b32_e32 v177, 0xffff0000, v158
	v_lshlrev_b32_e32 v158, 16, v159
	v_and_b32_e32 v159, 0xffff0000, v159
	v_lshlrev_b32_e32 v178, 16, v168
	v_and_b32_e32 v179, 0xffff0000, v168
	v_lshlrev_b32_e32 v168, 16, v169
	v_and_b32_e32 v169, 0xffff0000, v169
	v_lshlrev_b32_e32 v180, 16, v170
	v_and_b32_e32 v181, 0xffff0000, v170
	v_lshlrev_b32_e32 v170, 16, v171
	v_and_b32_e32 v171, 0xffff0000, v171
	v_pk_add_f32 v[126:127], v[126:127], v[156:157]
	v_pk_add_f32 v[124:125], v[124:125], v[174:175]
	v_pk_add_f32 v[122:123], v[122:123], v[158:159]
	v_pk_add_f32 v[120:121], v[120:121], v[176:177]
	v_pk_add_f32 v[156:157], v[118:119], v[168:169]
	v_pk_add_f32 v[158:159], v[116:117], v[178:179]
	v_pk_add_f32 v[168:169], v[172:173], v[170:171]
	v_pk_add_f32 v[170:171], v[112:113], v[180:181]
	v_cvt_pk_bf16_f32 v116, v124, v125
	v_cvt_pk_bf16_f32 v117, v126, v127
	v_mul_f32_e32 v112, v125, v125
	v_mul_f32_e32 v113, v127, v127
	v_mul_f32_e32 v118, v121, v121
	v_mul_f32_e32 v119, v123, v123
	v_mul_f32_e32 v125, v159, v159
	v_mul_f32_e32 v127, v157, v157
	v_mul_f32_e32 v155, v171, v171
	v_mul_f32_e32 v167, v169, v169
	v_fmac_f32_e32 v112, v124, v124
	v_fmac_f32_e32 v113, v126, v126
	v_fmac_f32_e32 v118, v120, v120
	v_fmac_f32_e32 v119, v122, v122
	v_fmac_f32_e32 v125, v158, v158
	v_fmac_f32_e32 v127, v156, v156
	v_fmac_f32_e32 v155, v170, v170
	v_fmac_f32_e32 v167, v168, v168
	v_add_f32_e32 v112, v112, v113
	v_add_f32_e32 v113, v118, v119
	v_add_f32_e32 v118, v125, v127
	v_add_f32_e32 v119, v155, v167
	v_add_f32_e32 v112, v112, v113
	v_add_f32_e32 v113, v118, v119
	v_add_f32_e32 v112, v112, v113
	ds_bpermute_b32 v113, v115, v112
	v_cvt_pk_bf16_f32 v118, v120, v121
	v_cvt_pk_bf16_f32 v119, v122, v123
	global_store_dwordx4 v[160:161], v[116:119], off
	s_waitcnt lgkmcnt(0)
	v_add_f32_e32 v112, v112, v113
	ds_bpermute_b32 v113, v114, v112
	v_cvt_pk_bf16_f32 v116, v158, v159
	v_cvt_pk_bf16_f32 v117, v156, v157
	v_cvt_pk_bf16_f32 v118, v170, v171
	v_cvt_pk_bf16_f32 v119, v168, v169
	global_store_dwordx4 v[160:161], v[116:119], off offset:256
	s_and_saveexec_b64 s[36:37], s[4:5]
	s_cbranch_execz .LBB0_807
	s_waitcnt lgkmcnt(0)
	v_add_f32_e32 v116, v112, v113
	v_lshlrev_b64 v[112:113], 6, v[146:147]
	v_lshl_add_u64 v[112:113], s[82:83], 0, v[112:113]
	v_lshl_add_u64 v[112:113], s[0:1], 2, v[112:113]
	s_lshl_b32 s10, s45, 2
	v_lshl_add_u64 v[112:113], v[112:113], 0, s[10:11]
	global_store_dword v[112:113], v116, off
; __device__ __forceinline__ unsigned pk2(float lo, float hi) { f32x2_t v = {lo, hi}; bf16x2_t b = __builtin_convertvector(v, bf16x2_t); return __builtin_bit_cast(unsigned, b); }
;     __device__ __forceinline__ void operator()(const AccT& acc, const Unit& u, int wr, int wc, int fr, int fq) const {
;     ...
;             for (int m = 0; m < 4; ++m) { const int row = row0 + ai * HALF + m * 16;
;                 { bf16_t* hbp = HB + (size_t)row * DM + col0; float sq = 0.f;
; #pragma unroll
;                     for (int bj = 0; bj < 2; ++bj) { u32x4* p = (u32x4*)(hbp + bj * HALF); const u32x4 ho = *p;
;                         const f32x4 h0 = {bflo(ho.x), bfhi(ho.x), bflo(ho.y), bfhi(ho.y)}, h1 = {bflo(ho.z), bfhi(ho.z), bflo(ho.w), bfhi(ho.w)};
;                         const f32x4 a0 = h0 + (acc[ai][bj][m][0] + bv[bj][0]) * sv[bj][0], a1 = h1 + (acc[ai][bj][m][1] + bv[bj][1]) * sv[bj][1];
;                         u32x4 w; w.x = pk2(a0[0], a0[1]); w.y = pk2(a0[2], a0[3]); w.z = pk2(a1[0], a1[1]); w.w = pk2(a1[2], a1[3]); *p = w;
;                         sq += ((a0[0] * a0[0] + a0[1] * a0[1]) + (a0[2] * a0[2] + a0[3] * a0[3])) + ((a1[0] * a1[0] + a1[1] * a1[1]) + (a1[2] * a1[2] + a1[3] * a1[3])); }
;                     sq += __shfl_xor(sq, 16); sq += __shfl_xor(sq, 32);
;                     if (fq == 0) ss_out[(size_t)row * 16 + u.pn * 4 + wc] = sq; } }
.LBB0_807:
	s_or_b64 exec, exec, s[36:37]
	v_add_u32_e32 v112, 16, v146
	s_waitcnt lgkmcnt(0)
	v_ashrrev_i32_e32 v113, 31, v112
	v_lshlrev_b64 v[116:117], 11, v[112:113]
	v_lshl_add_u64 v[116:117], s[80:81], 0, v[116:117]
	v_lshl_add_u64 v[124:125], v[144:145], 1, v[116:117]
	v_pk_add_f32 v[110:111], v[110:111], 0 op_sel_hi:[1,0]
	v_pk_add_f32 v[108:109], v[108:109], 0 op_sel_hi:[1,0]
	v_pk_add_f32 v[106:107], v[106:107], 0 op_sel_hi:[1,0]
	v_pk_add_f32 v[104:105], v[104:105], 0 op_sel_hi:[1,0]
	v_pk_add_f32 v[102:103], v[102:103], 0 op_sel_hi:[1,0]
	v_pk_add_f32 v[100:101], v[100:101], 0 op_sel_hi:[1,0]
	v_pk_add_f32 v[98:99], v[98:99], 0 op_sel_hi:[1,0]
	v_pk_add_f32 v[96:97], v[96:97], 0 op_sel_hi:[1,0]
	s_waitcnt vmcnt(11)
	v_lshlrev_b32_e32 v126, 16, v184
	v_and_b32_e32 v127, 0xffff0000, v184
	v_lshlrev_b32_e32 v116, 16, v185
	v_and_b32_e32 v117, 0xffff0000, v185
	v_lshlrev_b32_e32 v156, 16, v186
	v_and_b32_e32 v157, 0xffff0000, v186
	v_lshlrev_b32_e32 v118, 16, v187
	v_and_b32_e32 v119, 0xffff0000, v187
	s_waitcnt vmcnt(10)
	v_lshlrev_b32_e32 v158, 16, v188
	v_and_b32_e32 v159, 0xffff0000, v188
	v_lshlrev_b32_e32 v120, 16, v189
	v_and_b32_e32 v121, 0xffff0000, v189
	v_lshlrev_b32_e32 v160, 16, v190
	v_and_b32_e32 v161, 0xffff0000, v190
	v_lshlrev_b32_e32 v122, 16, v191
	v_and_b32_e32 v123, 0xffff0000, v191
	s_mov_b32 s98, 0x50000
	s_mov_b32 s99, 0
	v_lshl_add_u64 v[254:255], v[252:253], 0, s[98:99]
	global_load_dwordx4 v[184:187], v[254:255], off
	global_load_dwordx4 v[188:191], v[254:255], off offset:256
	v_pk_add_f32 v[110:111], v[110:111], v[116:117]
	v_pk_add_f32 v[108:109], v[108:109], v[126:127]
	v_pk_add_f32 v[106:107], v[106:107], v[118:119]
	v_pk_add_f32 v[104:105], v[104:105], v[156:157]
	v_pk_add_f32 v[102:103], v[102:103], v[120:121]
	v_pk_add_f32 v[100:101], v[100:101], v[158:159]
	v_pk_add_f32 v[116:117], v[98:99], v[122:123]
	v_pk_add_f32 v[118:119], v[96:97], v[160:161]
	v_cvt_pk_bf16_f32 v96, v108, v109
	v_cvt_pk_bf16_f32 v97, v110, v111
	v_mul_f32_e32 v98, v109, v109
	v_mul_f32_e32 v99, v111, v111
	v_mul_f32_e32 v109, v105, v105
	v_mul_f32_e32 v111, v107, v107
	v_mul_f32_e32 v120, v101, v101
	v_mul_f32_e32 v121, v103, v103
	v_mul_f32_e32 v122, v119, v119
	v_mul_f32_e32 v123, v117, v117
	v_fmac_f32_e32 v98, v108, v108
	v_fmac_f32_e32 v99, v110, v110
	v_fmac_f32_e32 v109, v104, v104
	v_fmac_f32_e32 v111, v106, v106
	v_fmac_f32_e32 v120, v100, v100
	v_fmac_f32_e32 v121, v102, v102
	v_fmac_f32_e32 v122, v118, v118
	v_fmac_f32_e32 v123, v116, v116
	v_add_f32_e32 v98, v98, v99
	v_add_f32_e32 v99, v109, v111
	v_add_f32_e32 v108, v120, v121
	v_add_f32_e32 v109, v122, v123
	v_add_f32_e32 v98, v98, v99
	v_add_f32_e32 v99, v108, v109
	v_add_f32_e32 v108, v98, v99
	ds_bpermute_b32 v109, v115, v108
	v_cvt_pk_bf16_f32 v98, v104, v105
	v_cvt_pk_bf16_f32 v99, v106, v107
	global_store_dwordx4 v[124:125], v[96:99], off
	s_waitcnt lgkmcnt(0)
	s_nop 0
	v_add_f32_e32 v96, v108, v109
	ds_bpermute_b32 v97, v114, v96
	v_cvt_pk_bf16_f32 v98, v100, v101
	v_cvt_pk_bf16_f32 v99, v102, v103
	v_cvt_pk_bf16_f32 v100, v118, v119
	v_cvt_pk_bf16_f32 v101, v116, v117
	global_store_dwordx4 v[124:125], v[98:101], off offset:256
	s_and_saveexec_b64 s[36:37], s[4:5]
	s_cbranch_execz .LBB0_809
	s_waitcnt lgkmcnt(0)
	v_add_f32_e32 v98, v96, v97
	v_lshlrev_b64 v[96:97], 6, v[112:113]
	v_lshl_add_u64 v[96:97], s[82:83], 0, v[96:97]
	v_lshl_add_u64 v[96:97], s[0:1], 2, v[96:97]
	s_lshl_b32 s10, s45, 2
	v_lshl_add_u64 v[96:97], v[96:97], 0, s[10:11]
	global_store_dword v[96:97], v98, off
.LBB0_809:
	s_or_b64 exec, exec, s[36:37]
	v_add_u32_e32 v96, 32, v146
	s_waitcnt lgkmcnt(0)
	v_ashrrev_i32_e32 v97, 31, v96
	v_lshlrev_b64 v[98:99], 11, v[96:97]
	v_lshl_add_u64 v[98:99], s[80:81], 0, v[98:99]
	v_lshl_add_u64 v[106:107], v[144:145], 1, v[98:99]
	v_pk_add_f32 v[94:95], v[94:95], 0 op_sel_hi:[1,0]
	v_pk_add_f32 v[92:93], v[92:93], 0 op_sel_hi:[1,0]
	v_pk_add_f32 v[90:91], v[90:91], 0 op_sel_hi:[1,0]
	v_pk_add_f32 v[88:89], v[88:89], 0 op_sel_hi:[1,0]
	v_pk_add_f32 v[86:87], v[86:87], 0 op_sel_hi:[1,0]
	v_pk_add_f32 v[84:85], v[84:85], 0 op_sel_hi:[1,0]
	v_pk_add_f32 v[82:83], v[82:83], 0 op_sel_hi:[1,0]
	v_pk_add_f32 v[80:81], v[80:81], 0 op_sel_hi:[1,0]
	s_waitcnt vmcnt(13)
	v_lshlrev_b32_e32 v108, 16, v192
	v_and_b32_e32 v109, 0xffff0000, v192
	v_lshlrev_b32_e32 v98, 16, v193
	v_and_b32_e32 v99, 0xffff0000, v193
	v_lshlrev_b32_e32 v110, 16, v194
	v_and_b32_e32 v111, 0xffff0000, v194
	v_lshlrev_b32_e32 v100, 16, v195
	v_and_b32_e32 v101, 0xffff0000, v195
	s_waitcnt vmcnt(12)
	v_lshlrev_b32_e32 v112, 16, v196
	v_and_b32_e32 v113, 0xffff0000, v196
	v_lshlrev_b32_e32 v102, 16, v197
	v_and_b32_e32 v103, 0xffff0000, v197
	v_lshlrev_b32_e32 v116, 16, v198
	v_and_b32_e32 v117, 0xffff0000, v198
	v_lshlrev_b32_e32 v104, 16, v199
	v_and_b32_e32 v105, 0xffff0000, v199
	s_mov_b32 s98, 0x58000
	s_mov_b32 s99, 0
	v_lshl_add_u64 v[254:255], v[252:253], 0, s[98:99]
	global_load_dwordx4 v[192:195], v[254:255], off
	global_load_dwordx4 v[196:199], v[254:255], off offset:256
	v_pk_add_f32 v[94:95], v[94:95], v[98:99]
	v_pk_add_f32 v[92:93], v[92:93], v[108:109]
	v_pk_add_f32 v[90:91], v[90:91], v[100:101]
	v_pk_add_f32 v[88:89], v[88:89], v[110:111]
	v_pk_add_f32 v[86:87], v[86:87], v[102:103]
	v_pk_add_f32 v[84:85], v[84:85], v[112:113]
	v_pk_add_f32 v[98:99], v[82:83], v[104:105]
	v_pk_add_f32 v[100:101], v[80:81], v[116:117]
	v_cvt_pk_bf16_f32 v80, v92, v93
	v_cvt_pk_bf16_f32 v81, v94, v95
	v_mul_f32_e32 v82, v93, v93
	v_mul_f32_e32 v83, v95, v95
	v_mul_f32_e32 v93, v89, v89
	v_mul_f32_e32 v95, v91, v91
	v_mul_f32_e32 v102, v85, v85
	v_mul_f32_e32 v103, v87, v87
	v_mul_f32_e32 v104, v101, v101
	v_mul_f32_e32 v105, v99, v99
	v_fmac_f32_e32 v82, v92, v92
	v_fmac_f32_e32 v83, v94, v94
	v_fmac_f32_e32 v93, v88, v88
	v_fmac_f32_e32 v95, v90, v90
	v_fmac_f32_e32 v102, v84, v84
	v_fmac_f32_e32 v103, v86, v86
	v_fmac_f32_e32 v104, v100, v100
	v_fmac_f32_e32 v105, v98, v98
	v_add_f32_e32 v82, v82, v83
	v_add_f32_e32 v83, v93, v95
	v_add_f32_e32 v92, v102, v103
	v_add_f32_e32 v93, v104, v105
	v_add_f32_e32 v82, v82, v83
	v_add_f32_e32 v83, v92, v93
	v_add_f32_e32 v92, v82, v83
	ds_bpermute_b32 v93, v115, v92
	v_cvt_pk_bf16_f32 v82, v88, v89
	v_cvt_pk_bf16_f32 v83, v90, v91
	global_store_dwordx4 v[106:107], v[80:83], off
	s_waitcnt lgkmcnt(0)
	s_nop 0
	v_add_f32_e32 v80, v92, v93
	ds_bpermute_b32 v81, v114, v80
	v_cvt_pk_bf16_f32 v82, v84, v85
	v_cvt_pk_bf16_f32 v83, v86, v87
	v_cvt_pk_bf16_f32 v84, v100, v101
	v_cvt_pk_bf16_f32 v85, v98, v99
	global_store_dwordx4 v[106:107], v[82:85], off offset:256
	s_and_saveexec_b64 s[36:37], s[4:5]
	s_cbranch_execz .LBB0_811
	s_waitcnt lgkmcnt(0)
	v_add_f32_e32 v82, v80, v81
	v_lshlrev_b64 v[80:81], 6, v[96:97]
	v_lshl_add_u64 v[80:81], s[82:83], 0, v[80:81]
	v_lshl_add_u64 v[80:81], s[0:1], 2, v[80:81]
	s_lshl_b32 s10, s45, 2
	v_lshl_add_u64 v[80:81], v[80:81], 0, s[10:11]
	global_store_dword v[80:81], v82, off
; __device__ __forceinline__ unsigned pk2(float lo, float hi) { f32x2_t v = {lo, hi}; bf16x2_t b = __builtin_convertvector(v, bf16x2_t); return __builtin_bit_cast(unsigned, b); }
;     __device__ __forceinline__ void operator()(const AccT& acc, const Unit& u, int wr, int wc, int fr, int fq) const {
;     ...
;             for (int m = 0; m < 4; ++m) { const int row = row0 + ai * HALF + m * 16;
;                 { bf16_t* hbp = HB + (size_t)row * DM + col0; float sq = 0.f;
; #pragma unroll
;                     for (int bj = 0; bj < 2; ++bj) { u32x4* p = (u32x4*)(hbp + bj * HALF); const u32x4 ho = *p;
;                         const f32x4 h0 = {bflo(ho.x), bfhi(ho.x), bflo(ho.y), bfhi(ho.y)}, h1 = {bflo(ho.z), bfhi(ho.z), bflo(ho.w), bfhi(ho.w)};
;                         const f32x4 a0 = h0 + (acc[ai][bj][m][0] + bv[bj][0]) * sv[bj][0], a1 = h1 + (acc[ai][bj][m][1] + bv[bj][1]) * sv[bj][1];
;                         u32x4 w; w.x = pk2(a0[0], a0[1]); w.y = pk2(a0[2], a0[3]); w.z = pk2(a1[0], a1[1]); w.w = pk2(a1[2], a1[3]); *p = w;
;                         sq += ((a0[0] * a0[0] + a0[1] * a0[1]) + (a0[2] * a0[2] + a0[3] * a0[3])) + ((a1[0] * a1[0] + a1[1] * a1[1]) + (a1[2] * a1[2] + a1[3] * a1[3])); }
;                     sq += __shfl_xor(sq, 16); sq += __shfl_xor(sq, 32);
;                     if (fq == 0) ss_out[(size_t)row * 16 + u.pn * 4 + wc] = sq; } }
.LBB0_811:
	s_or_b64 exec, exec, s[36:37]
	v_add_u32_e32 v80, 48, v146
	s_waitcnt lgkmcnt(0)
	v_ashrrev_i32_e32 v81, 31, v80
	v_lshlrev_b64 v[82:83], 11, v[80:81]
	v_lshl_add_u64 v[82:83], s[80:81], 0, v[82:83]
	v_lshl_add_u64 v[90:91], v[144:145], 1, v[82:83]
	v_pk_add_f32 v[78:79], v[78:79], 0 op_sel_hi:[1,0]
	v_pk_add_f32 v[76:77], v[76:77], 0 op_sel_hi:[1,0]
	v_pk_add_f32 v[74:75], v[74:75], 0 op_sel_hi:[1,0]
	v_pk_add_f32 v[72:73], v[72:73], 0 op_sel_hi:[1,0]
	v_pk_add_f32 v[70:71], v[70:71], 0 op_sel_hi:[1,0]
	v_pk_add_f32 v[68:69], v[68:69], 0 op_sel_hi:[1,0]
	v_pk_add_f32 v[66:67], v[66:67], 0 op_sel_hi:[1,0]
	v_pk_add_f32 v[64:65], v[64:65], 0 op_sel_hi:[1,0]
	s_waitcnt vmcnt(15)
	v_lshlrev_b32_e32 v92, 16, v200
	v_and_b32_e32 v93, 0xffff0000, v200
	v_lshlrev_b32_e32 v82, 16, v201
	v_and_b32_e32 v83, 0xffff0000, v201
	v_lshlrev_b32_e32 v94, 16, v202
	v_and_b32_e32 v95, 0xffff0000, v202
	v_lshlrev_b32_e32 v84, 16, v203
	v_and_b32_e32 v85, 0xffff0000, v203
	s_waitcnt vmcnt(14)
	v_lshlrev_b32_e32 v96, 16, v204
	v_and_b32_e32 v97, 0xffff0000, v204
	v_lshlrev_b32_e32 v86, 16, v205
	v_and_b32_e32 v87, 0xffff0000, v205
	v_lshlrev_b32_e32 v98, 16, v206
	v_and_b32_e32 v99, 0xffff0000, v206
	v_lshlrev_b32_e32 v88, 16, v207
	v_and_b32_e32 v89, 0xffff0000, v207
	v_pk_add_f32 v[78:79], v[78:79], v[82:83]
	v_pk_add_f32 v[76:77], v[76:77], v[92:93]
	v_pk_add_f32 v[74:75], v[74:75], v[84:85]
	v_pk_add_f32 v[72:73], v[72:73], v[94:95]
	v_pk_add_f32 v[70:71], v[70:71], v[86:87]
	v_pk_add_f32 v[68:69], v[68:69], v[96:97]
	v_pk_add_f32 v[82:83], v[66:67], v[88:89]
	v_pk_add_f32 v[84:85], v[64:65], v[98:99]
	v_cvt_pk_bf16_f32 v64, v76, v77
	v_cvt_pk_bf16_f32 v65, v78, v79
	v_mul_f32_e32 v66, v77, v77
	v_mul_f32_e32 v67, v79, v79
	v_mul_f32_e32 v77, v73, v73
	v_mul_f32_e32 v79, v75, v75
	v_mul_f32_e32 v86, v69, v69
	v_mul_f32_e32 v87, v71, v71
	v_mul_f32_e32 v88, v85, v85
	v_mul_f32_e32 v89, v83, v83
	v_fmac_f32_e32 v66, v76, v76
	v_fmac_f32_e32 v67, v78, v78
	v_fmac_f32_e32 v77, v72, v72
	v_fmac_f32_e32 v79, v74, v74
	v_fmac_f32_e32 v86, v68, v68
	v_fmac_f32_e32 v87, v70, v70
	v_fmac_f32_e32 v88, v84, v84
	v_fmac_f32_e32 v89, v82, v82
	v_add_f32_e32 v66, v66, v67
	v_add_f32_e32 v67, v77, v79
	v_add_f32_e32 v76, v86, v87
	v_add_f32_e32 v77, v88, v89
	v_add_f32_e32 v66, v66, v67
	v_add_f32_e32 v67, v76, v77
	v_add_f32_e32 v76, v66, v67
	ds_bpermute_b32 v77, v115, v76
	v_cvt_pk_bf16_f32 v66, v72, v73
	v_cvt_pk_bf16_f32 v67, v74, v75
	global_store_dwordx4 v[90:91], v[64:67], off
	s_waitcnt lgkmcnt(0)
	s_nop 0
	v_add_f32_e32 v64, v76, v77
	ds_bpermute_b32 v65, v114, v64
	v_cvt_pk_bf16_f32 v66, v68, v69
	v_cvt_pk_bf16_f32 v67, v70, v71
	v_cvt_pk_bf16_f32 v68, v84, v85
	v_cvt_pk_bf16_f32 v69, v82, v83
	global_store_dwordx4 v[90:91], v[66:69], off offset:256
	s_and_saveexec_b64 s[36:37], s[4:5]
	s_cbranch_execz .LBB0_813
	s_waitcnt lgkmcnt(0)
	v_add_f32_e32 v66, v64, v65
	v_lshlrev_b64 v[64:65], 6, v[80:81]
	v_lshl_add_u64 v[64:65], s[82:83], 0, v[64:65]
	v_lshl_add_u64 v[64:65], s[0:1], 2, v[64:65]
	s_lshl_b32 s10, s45, 2
	v_lshl_add_u64 v[64:65], v[64:65], 0, s[10:11]
	global_store_dword v[64:65], v66, off
.LBB0_813:
	s_or_b64 exec, exec, s[36:37]
	v_add_u32_e32 v64, 0x80, v146
	s_waitcnt lgkmcnt(0)
	v_ashrrev_i32_e32 v65, 31, v64
	v_lshlrev_b64 v[66:67], 11, v[64:65]
	v_lshl_add_u64 v[66:67], s[80:81], 0, v[66:67]
	v_lshl_add_u64 v[74:75], v[144:145], 1, v[66:67]
	v_pk_add_f32 v[62:63], v[62:63], 0 op_sel_hi:[1,0]
	v_pk_add_f32 v[60:61], v[60:61], 0 op_sel_hi:[1,0]
	v_pk_add_f32 v[58:59], v[58:59], 0 op_sel_hi:[1,0]
	v_pk_add_f32 v[56:57], v[56:57], 0 op_sel_hi:[1,0]
	v_pk_add_f32 v[54:55], v[54:55], 0 op_sel_hi:[1,0]
	v_pk_add_f32 v[52:53], v[52:53], 0 op_sel_hi:[1,0]
	v_pk_add_f32 v[50:51], v[50:51], 0 op_sel_hi:[1,0]
	v_pk_add_f32 v[48:49], v[48:49], 0 op_sel_hi:[1,0]
	s_waitcnt vmcnt(15)
	v_lshlrev_b32_e32 v76, 16, v208
	v_and_b32_e32 v77, 0xffff0000, v208
	v_lshlrev_b32_e32 v66, 16, v209
	v_and_b32_e32 v67, 0xffff0000, v209
	v_lshlrev_b32_e32 v78, 16, v210
	v_and_b32_e32 v79, 0xffff0000, v210
	v_lshlrev_b32_e32 v68, 16, v211
	v_and_b32_e32 v69, 0xffff0000, v211
	s_waitcnt vmcnt(14)
	v_lshlrev_b32_e32 v80, 16, v212
	v_and_b32_e32 v81, 0xffff0000, v212
	v_lshlrev_b32_e32 v70, 16, v213
	v_and_b32_e32 v71, 0xffff0000, v213
	v_lshlrev_b32_e32 v82, 16, v214
	v_and_b32_e32 v83, 0xffff0000, v214
	v_lshlrev_b32_e32 v72, 16, v215
	v_and_b32_e32 v73, 0xffff0000, v215
	v_pk_add_f32 v[62:63], v[62:63], v[66:67]
	v_pk_add_f32 v[60:61], v[60:61], v[76:77]
	v_pk_add_f32 v[58:59], v[58:59], v[68:69]
	v_pk_add_f32 v[56:57], v[56:57], v[78:79]
	v_pk_add_f32 v[54:55], v[54:55], v[70:71]
	v_pk_add_f32 v[52:53], v[52:53], v[80:81]
	v_pk_add_f32 v[66:67], v[50:51], v[72:73]
	v_pk_add_f32 v[68:69], v[48:49], v[82:83]
	v_cvt_pk_bf16_f32 v48, v60, v61
	v_cvt_pk_bf16_f32 v49, v62, v63
	v_mul_f32_e32 v50, v61, v61
	v_mul_f32_e32 v51, v63, v63
	v_mul_f32_e32 v61, v57, v57
	v_mul_f32_e32 v63, v59, v59
	v_mul_f32_e32 v70, v53, v53
	v_mul_f32_e32 v71, v55, v55
	v_mul_f32_e32 v72, v69, v69
	v_mul_f32_e32 v73, v67, v67
	v_fmac_f32_e32 v50, v60, v60
	v_fmac_f32_e32 v51, v62, v62
	v_fmac_f32_e32 v61, v56, v56
	v_fmac_f32_e32 v63, v58, v58
	v_fmac_f32_e32 v70, v52, v52
	v_fmac_f32_e32 v71, v54, v54
	v_fmac_f32_e32 v72, v68, v68
	v_fmac_f32_e32 v73, v66, v66
	v_add_f32_e32 v50, v50, v51
	v_add_f32_e32 v51, v61, v63
	v_add_f32_e32 v60, v70, v71
	v_add_f32_e32 v61, v72, v73
	v_add_f32_e32 v50, v50, v51
	v_add_f32_e32 v51, v60, v61
	v_add_f32_e32 v60, v50, v51
	ds_bpermute_b32 v61, v115, v60
	v_cvt_pk_bf16_f32 v50, v56, v57
	v_cvt_pk_bf16_f32 v51, v58, v59
	global_store_dwordx4 v[74:75], v[48:51], off
	s_waitcnt lgkmcnt(0)
	s_nop 0
	v_add_f32_e32 v48, v60, v61
	ds_bpermute_b32 v49, v114, v48
	v_cvt_pk_bf16_f32 v50, v52, v53
	v_cvt_pk_bf16_f32 v51, v54, v55
	v_cvt_pk_bf16_f32 v52, v68, v69
	v_cvt_pk_bf16_f32 v53, v66, v67
	global_store_dwordx4 v[74:75], v[50:53], off offset:256
	s_and_saveexec_b64 s[36:37], s[4:5]
	s_cbranch_execz .LBB0_815
	s_waitcnt lgkmcnt(0)
	v_add_f32_e32 v50, v48, v49
	v_lshlrev_b64 v[48:49], 6, v[64:65]
	v_lshl_add_u64 v[48:49], s[82:83], 0, v[48:49]
	v_lshl_add_u64 v[48:49], s[0:1], 2, v[48:49]
	s_lshl_b32 s10, s45, 2
	v_lshl_add_u64 v[48:49], v[48:49], 0, s[10:11]
	global_store_dword v[48:49], v50, off
; __device__ __forceinline__ unsigned pk2(float lo, float hi) { f32x2_t v = {lo, hi}; bf16x2_t b = __builtin_convertvector(v, bf16x2_t); return __builtin_bit_cast(unsigned, b); }
;     __device__ __forceinline__ void operator()(const AccT& acc, const Unit& u, int wr, int wc, int fr, int fq) const {
;     ...
;             for (int m = 0; m < 4; ++m) { const int row = row0 + ai * HALF + m * 16;
;                 { bf16_t* hbp = HB + (size_t)row * DM + col0; float sq = 0.f;
; #pragma unroll
;                     for (int bj = 0; bj < 2; ++bj) { u32x4* p = (u32x4*)(hbp + bj * HALF); const u32x4 ho = *p;
;                         const f32x4 h0 = {bflo(ho.x), bfhi(ho.x), bflo(ho.y), bfhi(ho.y)}, h1 = {bflo(ho.z), bfhi(ho.z), bflo(ho.w), bfhi(ho.w)};
;                         const f32x4 a0 = h0 + (acc[ai][bj][m][0] + bv[bj][0]) * sv[bj][0], a1 = h1 + (acc[ai][bj][m][1] + bv[bj][1]) * sv[bj][1];
;                         u32x4 w; w.x = pk2(a0[0], a0[1]); w.y = pk2(a0[2], a0[3]); w.z = pk2(a1[0], a1[1]); w.w = pk2(a1[2], a1[3]); *p = w;
;                         sq += ((a0[0] * a0[0] + a0[1] * a0[1]) + (a0[2] * a0[2] + a0[3] * a0[3])) + ((a1[0] * a1[0] + a1[1] * a1[1]) + (a1[2] * a1[2] + a1[3] * a1[3])); }
;                     sq += __shfl_xor(sq, 16); sq += __shfl_xor(sq, 32);
;                     if (fq == 0) ss_out[(size_t)row * 16 + u.pn * 4 + wc] = sq; } }
.LBB0_815:
	s_or_b64 exec, exec, s[36:37]
	v_add_u32_e32 v48, 0x90, v146
	s_waitcnt lgkmcnt(0)
	v_ashrrev_i32_e32 v49, 31, v48
	v_lshlrev_b64 v[50:51], 11, v[48:49]
	v_lshl_add_u64 v[50:51], s[80:81], 0, v[50:51]
	v_lshl_add_u64 v[58:59], v[144:145], 1, v[50:51]
	v_pk_add_f32 v[46:47], v[46:47], 0 op_sel_hi:[1,0]
	v_pk_add_f32 v[44:45], v[44:45], 0 op_sel_hi:[1,0]
	v_pk_add_f32 v[42:43], v[42:43], 0 op_sel_hi:[1,0]
	v_pk_add_f32 v[40:41], v[40:41], 0 op_sel_hi:[1,0]
	v_pk_add_f32 v[38:39], v[38:39], 0 op_sel_hi:[1,0]
	v_pk_add_f32 v[36:37], v[36:37], 0 op_sel_hi:[1,0]
	v_pk_add_f32 v[34:35], v[34:35], 0 op_sel_hi:[1,0]
	v_pk_add_f32 v[32:33], v[32:33], 0 op_sel_hi:[1,0]
	s_waitcnt vmcnt(15)
	v_lshlrev_b32_e32 v60, 16, v216
	v_and_b32_e32 v61, 0xffff0000, v216
	v_lshlrev_b32_e32 v50, 16, v217
	v_and_b32_e32 v51, 0xffff0000, v217
	v_lshlrev_b32_e32 v62, 16, v218
	v_and_b32_e32 v63, 0xffff0000, v218
	v_lshlrev_b32_e32 v52, 16, v219
	v_and_b32_e32 v53, 0xffff0000, v219
	s_waitcnt vmcnt(14)
	v_lshlrev_b32_e32 v64, 16, v220
	v_and_b32_e32 v65, 0xffff0000, v220
	v_lshlrev_b32_e32 v54, 16, v221
	v_and_b32_e32 v55, 0xffff0000, v221
	v_lshlrev_b32_e32 v66, 16, v222
	v_and_b32_e32 v67, 0xffff0000, v222
	v_lshlrev_b32_e32 v56, 16, v223
	v_and_b32_e32 v57, 0xffff0000, v223
	v_pk_add_f32 v[46:47], v[46:47], v[50:51]
	v_pk_add_f32 v[44:45], v[44:45], v[60:61]
	v_pk_add_f32 v[42:43], v[42:43], v[52:53]
	v_pk_add_f32 v[40:41], v[40:41], v[62:63]
	v_pk_add_f32 v[38:39], v[38:39], v[54:55]
	v_pk_add_f32 v[36:37], v[36:37], v[64:65]
	v_pk_add_f32 v[50:51], v[34:35], v[56:57]
	v_pk_add_f32 v[52:53], v[32:33], v[66:67]
	v_cvt_pk_bf16_f32 v32, v44, v45
	v_cvt_pk_bf16_f32 v33, v46, v47
	v_mul_f32_e32 v34, v45, v45
	v_mul_f32_e32 v35, v47, v47
	v_mul_f32_e32 v45, v41, v41
	v_mul_f32_e32 v47, v43, v43
	v_mul_f32_e32 v54, v37, v37
	v_mul_f32_e32 v55, v39, v39
	v_mul_f32_e32 v56, v53, v53
	v_mul_f32_e32 v57, v51, v51
	v_fmac_f32_e32 v34, v44, v44
	v_fmac_f32_e32 v35, v46, v46
	v_fmac_f32_e32 v45, v40, v40
	v_fmac_f32_e32 v47, v42, v42
	v_fmac_f32_e32 v54, v36, v36
	v_fmac_f32_e32 v55, v38, v38
	v_fmac_f32_e32 v56, v52, v52
	v_fmac_f32_e32 v57, v50, v50
	v_add_f32_e32 v34, v34, v35
	v_add_f32_e32 v35, v45, v47
	v_add_f32_e32 v44, v54, v55
	v_add_f32_e32 v45, v56, v57
	v_add_f32_e32 v34, v34, v35
	v_add_f32_e32 v35, v44, v45
	v_add_f32_e32 v44, v34, v35
	ds_bpermute_b32 v45, v115, v44
	v_cvt_pk_bf16_f32 v34, v40, v41
	v_cvt_pk_bf16_f32 v35, v42, v43
	global_store_dwordx4 v[58:59], v[32:35], off
	s_waitcnt lgkmcnt(0)
	s_nop 0
	v_add_f32_e32 v32, v44, v45
	ds_bpermute_b32 v33, v114, v32
	v_cvt_pk_bf16_f32 v34, v36, v37
	v_cvt_pk_bf16_f32 v35, v38, v39
	v_cvt_pk_bf16_f32 v36, v52, v53
	v_cvt_pk_bf16_f32 v37, v50, v51
	global_store_dwordx4 v[58:59], v[34:37], off offset:256
	s_and_saveexec_b64 s[36:37], s[4:5]
	s_cbranch_execz .LBB0_817
	s_waitcnt lgkmcnt(0)
	v_add_f32_e32 v34, v32, v33
	v_lshlrev_b64 v[32:33], 6, v[48:49]
	v_lshl_add_u64 v[32:33], s[82:83], 0, v[32:33]
	v_lshl_add_u64 v[32:33], s[0:1], 2, v[32:33]
	s_lshl_b32 s10, s45, 2
	v_lshl_add_u64 v[32:33], v[32:33], 0, s[10:11]
	global_store_dword v[32:33], v34, off
; __device__ __forceinline__ unsigned pk2(float lo, float hi) { f32x2_t v = {lo, hi}; bf16x2_t b = __builtin_convertvector(v, bf16x2_t); return __builtin_bit_cast(unsigned, b); }
;     __device__ __forceinline__ void operator()(const AccT& acc, const Unit& u, int wr, int wc, int fr, int fq) const {
;     ...
;             for (int m = 0; m < 4; ++m) { const int row = row0 + ai * HALF + m * 16;
;                 { bf16_t* hbp = HB + (size_t)row * DM + col0; float sq = 0.f;
; #pragma unroll
;                     for (int bj = 0; bj < 2; ++bj) { u32x4* p = (u32x4*)(hbp + bj * HALF); const u32x4 ho = *p;
;                         const f32x4 h0 = {bflo(ho.x), bfhi(ho.x), bflo(ho.y), bfhi(ho.y)}, h1 = {bflo(ho.z), bfhi(ho.z), bflo(ho.w), bfhi(ho.w)};
;                         const f32x4 a0 = h0 + (acc[ai][bj][m][0] + bv[bj][0]) * sv[bj][0], a1 = h1 + (acc[ai][bj][m][1] + bv[bj][1]) * sv[bj][1];
;                         u32x4 w; w.x = pk2(a0[0], a0[1]); w.y = pk2(a0[2], a0[3]); w.z = pk2(a1[0], a1[1]); w.w = pk2(a1[2], a1[3]); *p = w;
;                         sq += ((a0[0] * a0[0] + a0[1] * a0[1]) + (a0[2] * a0[2] + a0[3] * a0[3])) + ((a1[0] * a1[0] + a1[1] * a1[1]) + (a1[2] * a1[2] + a1[3] * a1[3])); }
;                     sq += __shfl_xor(sq, 16); sq += __shfl_xor(sq, 32);
;                     if (fq == 0) ss_out[(size_t)row * 16 + u.pn * 4 + wc] = sq; } }
.LBB0_817:
	s_or_b64 exec, exec, s[36:37]
	v_add_u32_e32 v32, 0xa0, v146
	s_waitcnt lgkmcnt(0)
	v_ashrrev_i32_e32 v33, 31, v32
	v_lshlrev_b64 v[34:35], 11, v[32:33]
	v_lshl_add_u64 v[34:35], s[80:81], 0, v[34:35]
	v_lshl_add_u64 v[42:43], v[144:145], 1, v[34:35]
	v_pk_add_f32 v[30:31], v[30:31], 0 op_sel_hi:[1,0]
	v_pk_add_f32 v[28:29], v[28:29], 0 op_sel_hi:[1,0]
	v_pk_add_f32 v[26:27], v[26:27], 0 op_sel_hi:[1,0]
	v_pk_add_f32 v[24:25], v[24:25], 0 op_sel_hi:[1,0]
	v_pk_add_f32 v[22:23], v[22:23], 0 op_sel_hi:[1,0]
	v_pk_add_f32 v[20:21], v[20:21], 0 op_sel_hi:[1,0]
	v_pk_add_f32 v[18:19], v[18:19], 0 op_sel_hi:[1,0]
	v_pk_add_f32 v[16:17], v[16:17], 0 op_sel_hi:[1,0]
	s_waitcnt vmcnt(13)
	v_lshlrev_b32_e32 v44, 16, v184
	v_and_b32_e32 v45, 0xffff0000, v184
	v_lshlrev_b32_e32 v34, 16, v185
	v_and_b32_e32 v35, 0xffff0000, v185
	v_lshlrev_b32_e32 v46, 16, v186
	v_and_b32_e32 v47, 0xffff0000, v186
	v_lshlrev_b32_e32 v36, 16, v187
	v_and_b32_e32 v37, 0xffff0000, v187
	s_waitcnt vmcnt(12)
	v_lshlrev_b32_e32 v48, 16, v188
	v_and_b32_e32 v49, 0xffff0000, v188
	v_lshlrev_b32_e32 v38, 16, v189
	v_and_b32_e32 v39, 0xffff0000, v189
	v_lshlrev_b32_e32 v50, 16, v190
	v_and_b32_e32 v51, 0xffff0000, v190
	v_lshlrev_b32_e32 v40, 16, v191
	v_and_b32_e32 v41, 0xffff0000, v191
	v_pk_add_f32 v[30:31], v[30:31], v[34:35]
	v_pk_add_f32 v[28:29], v[28:29], v[44:45]
	v_pk_add_f32 v[26:27], v[26:27], v[36:37]
	v_pk_add_f32 v[24:25], v[24:25], v[46:47]
	v_pk_add_f32 v[22:23], v[22:23], v[38:39]
	v_pk_add_f32 v[20:21], v[20:21], v[48:49]
	v_pk_add_f32 v[34:35], v[18:19], v[40:41]
	v_pk_add_f32 v[36:37], v[16:17], v[50:51]
	v_cvt_pk_bf16_f32 v16, v28, v29
	v_cvt_pk_bf16_f32 v17, v30, v31
	v_mul_f32_e32 v18, v29, v29
	v_mul_f32_e32 v19, v31, v31
	v_mul_f32_e32 v29, v25, v25
	v_mul_f32_e32 v31, v27, v27
	v_mul_f32_e32 v38, v21, v21
	v_mul_f32_e32 v39, v23, v23
	v_mul_f32_e32 v40, v37, v37
	v_mul_f32_e32 v41, v35, v35
	v_fmac_f32_e32 v18, v28, v28
	v_fmac_f32_e32 v19, v30, v30
	v_fmac_f32_e32 v29, v24, v24
	v_fmac_f32_e32 v31, v26, v26
	v_fmac_f32_e32 v38, v20, v20
	v_fmac_f32_e32 v39, v22, v22
	v_fmac_f32_e32 v40, v36, v36
	v_fmac_f32_e32 v41, v34, v34
	v_add_f32_e32 v18, v18, v19
	v_add_f32_e32 v19, v29, v31
	v_add_f32_e32 v28, v38, v39
	v_add_f32_e32 v29, v40, v41
	v_add_f32_e32 v18, v18, v19
	v_add_f32_e32 v19, v28, v29
	v_add_f32_e32 v28, v18, v19
	ds_bpermute_b32 v29, v115, v28
	v_cvt_pk_bf16_f32 v18, v24, v25
	v_cvt_pk_bf16_f32 v19, v26, v27
	global_store_dwordx4 v[42:43], v[16:19], off
	s_waitcnt lgkmcnt(0)
	s_nop 0
	v_add_f32_e32 v16, v28, v29
	ds_bpermute_b32 v17, v114, v16
	v_cvt_pk_bf16_f32 v18, v20, v21
	v_cvt_pk_bf16_f32 v19, v22, v23
	v_cvt_pk_bf16_f32 v20, v36, v37
	v_cvt_pk_bf16_f32 v21, v34, v35
	global_store_dwordx4 v[42:43], v[18:21], off offset:256
	s_and_saveexec_b64 s[36:37], s[4:5]
	s_cbranch_execz .LBB0_819
	s_waitcnt lgkmcnt(0)
	v_add_f32_e32 v18, v16, v17
	v_lshlrev_b64 v[16:17], 6, v[32:33]
	v_lshl_add_u64 v[16:17], s[82:83], 0, v[16:17]
	v_lshl_add_u64 v[16:17], s[0:1], 2, v[16:17]
	s_lshl_b32 s10, s45, 2
	v_lshl_add_u64 v[16:17], v[16:17], 0, s[10:11]
	global_store_dword v[16:17], v18, off
.LBB0_819:
	s_or_b64 exec, exec, s[36:37]
	v_add_u32_e32 v16, 0xb0, v146
	s_waitcnt lgkmcnt(0)
	v_ashrrev_i32_e32 v17, 31, v16
	v_lshlrev_b64 v[18:19], 11, v[16:17]
	v_lshl_add_u64 v[18:19], s[80:81], 0, v[18:19]
	v_lshl_add_u64 v[26:27], v[144:145], 1, v[18:19]
	v_pk_add_f32 v[14:15], v[14:15], 0 op_sel_hi:[1,0]
	v_pk_add_f32 v[12:13], v[12:13], 0 op_sel_hi:[1,0]
	v_pk_add_f32 v[10:11], v[10:11], 0 op_sel_hi:[1,0]
	v_pk_add_f32 v[8:9], v[8:9], 0 op_sel_hi:[1,0]
	v_pk_add_f32 v[6:7], v[6:7], 0 op_sel_hi:[1,0]
	v_pk_add_f32 v[4:5], v[4:5], 0 op_sel_hi:[1,0]
	v_pk_add_f32 v[2:3], v[2:3], 0 op_sel_hi:[1,0]
	v_pk_add_f32 v[0:1], v[0:1], 0 op_sel_hi:[1,0]
	s_waitcnt vmcnt(11)
	v_lshlrev_b32_e32 v28, 16, v192
	v_and_b32_e32 v29, 0xffff0000, v192
	v_lshlrev_b32_e32 v18, 16, v193
	v_and_b32_e32 v19, 0xffff0000, v193
	v_lshlrev_b32_e32 v30, 16, v194
	v_and_b32_e32 v31, 0xffff0000, v194
	v_lshlrev_b32_e32 v20, 16, v195
	v_and_b32_e32 v21, 0xffff0000, v195
	s_waitcnt vmcnt(10)
	v_lshlrev_b32_e32 v32, 16, v196
	v_and_b32_e32 v33, 0xffff0000, v196
	v_lshlrev_b32_e32 v22, 16, v197
	v_and_b32_e32 v23, 0xffff0000, v197
	v_lshlrev_b32_e32 v34, 16, v198
	v_and_b32_e32 v35, 0xffff0000, v198
	v_lshlrev_b32_e32 v24, 16, v199
	v_and_b32_e32 v25, 0xffff0000, v199
	v_pk_add_f32 v[14:15], v[14:15], v[18:19]
	v_pk_add_f32 v[12:13], v[12:13], v[28:29]
	v_pk_add_f32 v[10:11], v[10:11], v[20:21]
	v_pk_add_f32 v[8:9], v[8:9], v[30:31]
	v_pk_add_f32 v[6:7], v[6:7], v[22:23]
	v_pk_add_f32 v[4:5], v[4:5], v[32:33]
	v_pk_add_f32 v[18:19], v[2:3], v[24:25]
	v_pk_add_f32 v[20:21], v[0:1], v[34:35]
	v_cvt_pk_bf16_f32 v0, v12, v13
	v_cvt_pk_bf16_f32 v1, v14, v15
	v_mul_f32_e32 v2, v13, v13
	v_mul_f32_e32 v3, v15, v15
	v_mul_f32_e32 v13, v9, v9
	v_mul_f32_e32 v15, v11, v11
	v_mul_f32_e32 v22, v5, v5
	v_mul_f32_e32 v23, v7, v7
	v_mul_f32_e32 v24, v21, v21
	v_mul_f32_e32 v25, v19, v19
	v_fmac_f32_e32 v2, v12, v12
	v_fmac_f32_e32 v3, v14, v14
	v_fmac_f32_e32 v13, v8, v8
	v_fmac_f32_e32 v15, v10, v10
	v_fmac_f32_e32 v22, v4, v4
	v_fmac_f32_e32 v23, v6, v6
	v_fmac_f32_e32 v24, v20, v20
	v_fmac_f32_e32 v25, v18, v18
	v_add_f32_e32 v2, v2, v3
	v_add_f32_e32 v3, v13, v15
	v_add_f32_e32 v12, v22, v23
	v_add_f32_e32 v13, v24, v25
	v_add_f32_e32 v2, v2, v3
	v_add_f32_e32 v3, v12, v13
	v_add_f32_e32 v12, v2, v3
	ds_bpermute_b32 v13, v115, v12
	v_cvt_pk_bf16_f32 v2, v8, v9
	v_cvt_pk_bf16_f32 v3, v10, v11
	global_store_dwordx4 v[26:27], v[0:3], off
	s_waitcnt lgkmcnt(0)
	s_nop 0
	v_add_f32_e32 v0, v12, v13
	ds_bpermute_b32 v1, v114, v0
	v_cvt_pk_bf16_f32 v2, v4, v5
	v_cvt_pk_bf16_f32 v3, v6, v7
	v_cvt_pk_bf16_f32 v4, v20, v21
	v_cvt_pk_bf16_f32 v5, v18, v19
	global_store_dwordx4 v[26:27], v[2:5], off offset:256
	s_and_saveexec_b64 s[36:37], s[4:5]
	s_cbranch_execz .LBB0_821
	s_waitcnt lgkmcnt(0)
	v_add_f32_e32 v2, v0, v1
	v_lshlrev_b64 v[0:1], 6, v[16:17]
	v_lshl_add_u64 v[0:1], s[82:83], 0, v[0:1]
	v_lshl_add_u64 v[0:1], s[0:1], 2, v[0:1]
	s_lshl_b32 s10, s45, 2
	v_lshl_add_u64 v[0:1], v[0:1], 0, s[10:11]
	global_store_dword v[0:1], v2, off

; __device__ __forceinline__ unsigned pk2(float lo, float hi) { f32x2_t v = {lo, hi}; bf16x2_t b = __builtin_convertvector(v, bf16x2_t); return __builtin_bit_cast(unsigned, b); }
;     __device__ __forceinline__ void operator()(const AccT& acc, const Unit& u, int wr, int wc, int fr, int fq) const {
;         const int row0 = rowstart(u.pm) + wr * 64 + fr, col0 = u.pn * BM + wc * 32 + 8 * fq;
;         f32x4 bv[2][2], sv[2][2];
; #pragma unroll
;         for (int bj = 0; bj < 2; ++bj)
; #pragma unroll
;             for (int n = 0; n < 2; ++n) { bv[bj][n] = bias ? *(const f32x4*)(bias + col0 + bj * HALF + n * 4) : (f32x4){0.f, 0.f, 0.f, 0.f};
;                                           sv[bj][n] = scale ? *(const f32x4*)(scale + col0 + bj * HALF + n * 4) : (f32x4){1.f, 1.f, 1.f, 1.f}; }
; #pragma unroll
;         for (int ai = 0; ai < 2; ++ai)
; #pragma unroll
;             for (int m = 0; m < 4; ++m) { const int row = row0 + ai * HALF + m * 16;
;                 { bf16_t* hbp = HB + (size_t)row * DM + col0; float sq = 0.f;
; #pragma unroll
;                     for (int bj = 0; bj < 2; ++bj) { u32x4* p = (u32x4*)(hbp + bj * HALF); const u32x4 ho = *p;
;                         const f32x4 h0 = {bflo(ho.x), bfhi(ho.x), bflo(ho.y), bfhi(ho.y)}, h1 = {bflo(ho.z), bfhi(ho.z), bflo(ho.w), bfhi(ho.w)};
;                         const f32x4 a0 = h0 + (acc[ai][bj][m][0] + bv[bj][0]) * sv[bj][0], a1 = h1 + (acc[ai][bj][m][1] + bv[bj][1]) * sv[bj][1];
;                         u32x4 w; w.x = pk2(a0[0], a0[1]); w.y = pk2(a0[2], a0[3]); w.z = pk2(a1[0], a1[1]); w.w = pk2(a1[2], a1[3]); *p = w;
;                         sq += ((a0[0] * a0[0] + a0[1] * a0[1]) + (a0[2] * a0[2] + a0[3] * a0[3])) + ((a1[0] * a1[0] + a1[1] * a1[1]) + (a1[2] * a1[2] + a1[3] * a1[3])); }
;                     sq += __shfl_xor(sq, 16); sq += __shfl_xor(sq, 32);
;                     if (fq == 0) ss_out[(size_t)row * 16 + u.pn * 4 + wc] = sq; } }
.LBB0_991:
	s_ashr_i32 s27, s55, 2
	s_lshl_b32 s26, s55, 8
	s_and_b32 s27, s27, -16
	s_add_i32 s27, s27, s26
	v_add_u32_e32 v146, s27, v150
	v_ashrrev_i32_e32 v147, 31, v146
	v_lshl_or_b32 v144, s10, 8, v149
	v_lshlrev_b64 v[156:157], 11, v[146:147]
	v_ashrrev_i32_e32 v145, 31, v144
	v_lshl_add_u64 v[156:157], s[80:81], 0, v[156:157]
	v_lshl_add_u64 v[160:161], v[144:145], 1, v[156:157]
	global_load_dwordx4 v[156:159], v[160:161], off
	global_load_dwordx4 v[168:171], v[160:161], off offset:256
	v_mov_b32_e32 v252, v160
	v_mov_b32_e32 v253, v161
	s_mov_b32 s98, 0x8000
	s_mov_b32 s99, 0
	v_lshl_add_u64 v[254:255], v[252:253], 0, s[98:99]
	global_load_dwordx4 v[184:187], v[254:255], off
	global_load_dwordx4 v[188:191], v[254:255], off offset:256
	s_mov_b32 s98, 0x10000
	s_mov_b32 s99, 0
	v_lshl_add_u64 v[254:255], v[252:253], 0, s[98:99]
	global_load_dwordx4 v[192:195], v[254:255], off
	global_load_dwordx4 v[196:199], v[254:255], off offset:256
	s_mov_b32 s98, 0x18000
	s_mov_b32 s99, 0
	v_lshl_add_u64 v[254:255], v[252:253], 0, s[98:99]
	global_load_dwordx4 v[200:203], v[254:255], off
	global_load_dwordx4 v[204:207], v[254:255], off offset:256
	s_mov_b32 s98, 0x40000
	s_mov_b32 s99, 0
	v_lshl_add_u64 v[254:255], v[252:253], 0, s[98:99]
	global_load_dwordx4 v[208:211], v[254:255], off
	global_load_dwordx4 v[212:215], v[254:255], off offset:256
	s_mov_b32 s98, 0x48000
	s_mov_b32 s99, 0
	v_lshl_add_u64 v[254:255], v[252:253], 0, s[98:99]
	global_load_dwordx4 v[216:219], v[254:255], off
	global_load_dwordx4 v[220:223], v[254:255], off offset:256
	v_and_b32_e32 v167, 64, v154
	v_xor_b32_e32 v155, 16, v154
	v_pk_add_f32 v[172:173], v[114:115], 0 op_sel_hi:[1,0]
	v_add_u32_e32 v114, 64, v167
	v_xor_b32_e32 v174, 32, v154
	v_cmp_lt_i32_e32 vcc, v155, v114
	v_pk_add_f32 v[126:127], v[126:127], 0 op_sel_hi:[1,0]
	v_pk_add_f32 v[124:125], v[124:125], 0 op_sel_hi:[1,0]
	v_cndmask_b32_e32 v115, v154, v155, vcc
	v_cmp_lt_i32_e32 vcc, v174, v114
	v_pk_add_f32 v[122:123], v[122:123], 0 op_sel_hi:[1,0]
	v_pk_add_f32 v[120:121], v[120:121], 0 op_sel_hi:[1,0]
	v_pk_add_f32 v[118:119], v[118:119], 0 op_sel_hi:[1,0]
	v_pk_add_f32 v[116:117], v[116:117], 0 op_sel_hi:[1,0]
	v_pk_add_f32 v[112:113], v[112:113], 0 op_sel_hi:[1,0]
	v_cndmask_b32_e32 v114, v154, v174, vcc
	v_lshlrev_b32_e32 v115, 2, v115
	v_lshlrev_b32_e32 v114, 2, v114
	s_lshl_b32 s26, s10, 2
	s_ashr_i32 s27, s26, 31
	s_waitcnt vmcnt(10)
	v_lshlrev_b32_e32 v174, 16, v156
	v_and_b32_e32 v175, 0xffff0000, v156
	v_lshlrev_b32_e32 v156, 16, v157
	v_and_b32_e32 v157, 0xffff0000, v157
	v_lshlrev_b32_e32 v176, 16, v158
	v_and_b32_e32 v177, 0xffff0000, v158
	v_lshlrev_b32_e32 v158, 16, v159
	v_and_b32_e32 v159, 0xffff0000, v159
	v_lshlrev_b32_e32 v178, 16, v168
	v_and_b32_e32 v179, 0xffff0000, v168
	v_lshlrev_b32_e32 v168, 16, v169
	v_and_b32_e32 v169, 0xffff0000, v169
	v_lshlrev_b32_e32 v180, 16, v170
	v_and_b32_e32 v181, 0xffff0000, v170
	v_lshlrev_b32_e32 v170, 16, v171
	v_and_b32_e32 v171, 0xffff0000, v171
	v_pk_add_f32 v[126:127], v[126:127], v[156:157]
	v_pk_add_f32 v[124:125], v[124:125], v[174:175]
	v_pk_add_f32 v[122:123], v[122:123], v[158:159]
	v_pk_add_f32 v[120:121], v[120:121], v[176:177]
	v_pk_add_f32 v[156:157], v[118:119], v[168:169]
	v_pk_add_f32 v[158:159], v[116:117], v[178:179]
	v_pk_add_f32 v[168:169], v[172:173], v[170:171]
	v_pk_add_f32 v[170:171], v[112:113], v[180:181]
	v_cvt_pk_bf16_f32 v116, v124, v125
	v_cvt_pk_bf16_f32 v117, v126, v127
	v_mul_f32_e32 v112, v125, v125
	v_mul_f32_e32 v113, v127, v127
	v_mul_f32_e32 v118, v121, v121
	v_mul_f32_e32 v119, v123, v123
	v_mul_f32_e32 v125, v159, v159
	v_mul_f32_e32 v127, v157, v157
	v_mul_f32_e32 v155, v171, v171
	v_mul_f32_e32 v167, v169, v169
	v_fmac_f32_e32 v112, v124, v124
	v_fmac_f32_e32 v113, v126, v126
	v_fmac_f32_e32 v118, v120, v120
	v_fmac_f32_e32 v119, v122, v122
	v_fmac_f32_e32 v125, v158, v158
	v_fmac_f32_e32 v127, v156, v156
	v_fmac_f32_e32 v155, v170, v170
	v_fmac_f32_e32 v167, v168, v168
	v_add_f32_e32 v112, v112, v113
	v_add_f32_e32 v113, v118, v119
	v_add_f32_e32 v118, v125, v127
	v_add_f32_e32 v119, v155, v167
	v_add_f32_e32 v112, v112, v113
	v_add_f32_e32 v113, v118, v119
	v_add_f32_e32 v112, v112, v113
	ds_bpermute_b32 v113, v115, v112
	v_cvt_pk_bf16_f32 v118, v120, v121
	v_cvt_pk_bf16_f32 v119, v122, v123
	global_store_dwordx4 v[160:161], v[116:119], off
	s_waitcnt lgkmcnt(0)
	v_add_f32_e32 v112, v112, v113
	ds_bpermute_b32 v113, v114, v112
	v_cvt_pk_bf16_f32 v116, v158, v159
	v_cvt_pk_bf16_f32 v117, v156, v157
	v_cvt_pk_bf16_f32 v118, v170, v171
	v_cvt_pk_bf16_f32 v119, v168, v169
	global_store_dwordx4 v[160:161], v[116:119], off offset:256
	s_and_saveexec_b64 s[28:29], s[4:5]
	s_cbranch_execz .LBB0_993
	s_waitcnt lgkmcnt(0)
	v_add_f32_e32 v116, v112, v113
	v_lshlrev_b64 v[112:113], 6, v[146:147]
	v_lshl_add_u64 v[112:113], s[82:83], 0, v[112:113]
	v_lshl_add_u64 v[112:113], s[26:27], 2, v[112:113]
	s_lshl_b32 s10, s45, 2
	v_lshl_add_u64 v[112:113], v[112:113], 0, s[10:11]
	global_store_dword v[112:113], v116, off
; __device__ __forceinline__ unsigned pk2(float lo, float hi) { f32x2_t v = {lo, hi}; bf16x2_t b = __builtin_convertvector(v, bf16x2_t); return __builtin_bit_cast(unsigned, b); }
;     __device__ __forceinline__ void operator()(const AccT& acc, const Unit& u, int wr, int wc, int fr, int fq) const {
;     ...
;             for (int m = 0; m < 4; ++m) { const int row = row0 + ai * HALF + m * 16;
;                 { bf16_t* hbp = HB + (size_t)row * DM + col0; float sq = 0.f;
; #pragma unroll
;                     for (int bj = 0; bj < 2; ++bj) { u32x4* p = (u32x4*)(hbp + bj * HALF); const u32x4 ho = *p;
;                         const f32x4 h0 = {bflo(ho.x), bfhi(ho.x), bflo(ho.y), bfhi(ho.y)}, h1 = {bflo(ho.z), bfhi(ho.z), bflo(ho.w), bfhi(ho.w)};
;                         const f32x4 a0 = h0 + (acc[ai][bj][m][0] + bv[bj][0]) * sv[bj][0], a1 = h1 + (acc[ai][bj][m][1] + bv[bj][1]) * sv[bj][1];
;                         u32x4 w; w.x = pk2(a0[0], a0[1]); w.y = pk2(a0[2], a0[3]); w.z = pk2(a1[0], a1[1]); w.w = pk2(a1[2], a1[3]); *p = w;
;                         sq += ((a0[0] * a0[0] + a0[1] * a0[1]) + (a0[2] * a0[2] + a0[3] * a0[3])) + ((a1[0] * a1[0] + a1[1] * a1[1]) + (a1[2] * a1[2] + a1[3] * a1[3])); }
;                     sq += __shfl_xor(sq, 16); sq += __shfl_xor(sq, 32);
;                     if (fq == 0) ss_out[(size_t)row * 16 + u.pn * 4 + wc] = sq; } }
.LBB0_993:
	s_or_b64 exec, exec, s[28:29]
	v_add_u32_e32 v112, 16, v146
	s_waitcnt lgkmcnt(0)
	v_ashrrev_i32_e32 v113, 31, v112
	v_lshlrev_b64 v[116:117], 11, v[112:113]
	v_lshl_add_u64 v[116:117], s[80:81], 0, v[116:117]
	v_lshl_add_u64 v[124:125], v[144:145], 1, v[116:117]
	v_pk_add_f32 v[110:111], v[110:111], 0 op_sel_hi:[1,0]
	v_pk_add_f32 v[108:109], v[108:109], 0 op_sel_hi:[1,0]
	v_pk_add_f32 v[106:107], v[106:107], 0 op_sel_hi:[1,0]
	v_pk_add_f32 v[104:105], v[104:105], 0 op_sel_hi:[1,0]
	v_pk_add_f32 v[102:103], v[102:103], 0 op_sel_hi:[1,0]
	v_pk_add_f32 v[100:101], v[100:101], 0 op_sel_hi:[1,0]
	v_pk_add_f32 v[98:99], v[98:99], 0 op_sel_hi:[1,0]
	v_pk_add_f32 v[96:97], v[96:97], 0 op_sel_hi:[1,0]
	s_waitcnt vmcnt(11)
	v_lshlrev_b32_e32 v126, 16, v184
	v_and_b32_e32 v127, 0xffff0000, v184
	v_lshlrev_b32_e32 v116, 16, v185
	v_and_b32_e32 v117, 0xffff0000, v185
	v_lshlrev_b32_e32 v156, 16, v186
	v_and_b32_e32 v157, 0xffff0000, v186
	v_lshlrev_b32_e32 v118, 16, v187
	v_and_b32_e32 v119, 0xffff0000, v187
	s_waitcnt vmcnt(10)
	v_lshlrev_b32_e32 v158, 16, v188
	v_and_b32_e32 v159, 0xffff0000, v188
	v_lshlrev_b32_e32 v120, 16, v189
	v_and_b32_e32 v121, 0xffff0000, v189
	v_lshlrev_b32_e32 v160, 16, v190
	v_and_b32_e32 v161, 0xffff0000, v190
	v_lshlrev_b32_e32 v122, 16, v191
	v_and_b32_e32 v123, 0xffff0000, v191
	s_mov_b32 s98, 0x50000
	s_mov_b32 s99, 0
	v_lshl_add_u64 v[254:255], v[252:253], 0, s[98:99]
	global_load_dwordx4 v[184:187], v[254:255], off
	global_load_dwordx4 v[188:191], v[254:255], off offset:256
	v_pk_add_f32 v[110:111], v[110:111], v[116:117]
	v_pk_add_f32 v[108:109], v[108:109], v[126:127]
	v_pk_add_f32 v[106:107], v[106:107], v[118:119]
	v_pk_add_f32 v[104:105], v[104:105], v[156:157]
	v_pk_add_f32 v[102:103], v[102:103], v[120:121]
	v_pk_add_f32 v[100:101], v[100:101], v[158:159]
	v_pk_add_f32 v[116:117], v[98:99], v[122:123]
	v_pk_add_f32 v[118:119], v[96:97], v[160:161]
	v_cvt_pk_bf16_f32 v96, v108, v109
	v_cvt_pk_bf16_f32 v97, v110, v111
	v_mul_f32_e32 v98, v109, v109
	v_mul_f32_e32 v99, v111, v111
	v_mul_f32_e32 v109, v105, v105
	v_mul_f32_e32 v111, v107, v107
	v_mul_f32_e32 v120, v101, v101
	v_mul_f32_e32 v121, v103, v103
	v_mul_f32_e32 v122, v119, v119
	v_mul_f32_e32 v123, v117, v117
	v_fmac_f32_e32 v98, v108, v108
	v_fmac_f32_e32 v99, v110, v110
	v_fmac_f32_e32 v109, v104, v104
	v_fmac_f32_e32 v111, v106, v106
	v_fmac_f32_e32 v120, v100, v100
	v_fmac_f32_e32 v121, v102, v102
	v_fmac_f32_e32 v122, v118, v118
	v_fmac_f32_e32 v123, v116, v116
	v_add_f32_e32 v98, v98, v99
	v_add_f32_e32 v99, v109, v111
	v_add_f32_e32 v108, v120, v121
	v_add_f32_e32 v109, v122, v123
	v_add_f32_e32 v98, v98, v99
	v_add_f32_e32 v99, v108, v109
	v_add_f32_e32 v108, v98, v99
	ds_bpermute_b32 v109, v115, v108
	v_cvt_pk_bf16_f32 v98, v104, v105
	v_cvt_pk_bf16_f32 v99, v106, v107
	global_store_dwordx4 v[124:125], v[96:99], off
	s_waitcnt lgkmcnt(0)
	s_nop 0
	v_add_f32_e32 v96, v108, v109
	ds_bpermute_b32 v97, v114, v96
	v_cvt_pk_bf16_f32 v98, v100, v101
	v_cvt_pk_bf16_f32 v99, v102, v103
	v_cvt_pk_bf16_f32 v100, v118, v119
	v_cvt_pk_bf16_f32 v101, v116, v117
	global_store_dwordx4 v[124:125], v[98:101], off offset:256
	s_and_saveexec_b64 s[28:29], s[4:5]
	s_cbranch_execz .LBB0_995
	s_waitcnt lgkmcnt(0)
	v_add_f32_e32 v98, v96, v97
	v_lshlrev_b64 v[96:97], 6, v[112:113]
	v_lshl_add_u64 v[96:97], s[82:83], 0, v[96:97]
	v_lshl_add_u64 v[96:97], s[26:27], 2, v[96:97]
	s_lshl_b32 s10, s45, 2
	v_lshl_add_u64 v[96:97], v[96:97], 0, s[10:11]
	global_store_dword v[96:97], v98, off
.LBB0_995:
	s_or_b64 exec, exec, s[28:29]
	v_add_u32_e32 v96, 32, v146
	s_waitcnt lgkmcnt(0)
	v_ashrrev_i32_e32 v97, 31, v96
	v_lshlrev_b64 v[98:99], 11, v[96:97]
	v_lshl_add_u64 v[98:99], s[80:81], 0, v[98:99]
	v_lshl_add_u64 v[106:107], v[144:145], 1, v[98:99]
	v_pk_add_f32 v[94:95], v[94:95], 0 op_sel_hi:[1,0]
	v_pk_add_f32 v[92:93], v[92:93], 0 op_sel_hi:[1,0]
	v_pk_add_f32 v[90:91], v[90:91], 0 op_sel_hi:[1,0]
	v_pk_add_f32 v[88:89], v[88:89], 0 op_sel_hi:[1,0]
	v_pk_add_f32 v[86:87], v[86:87], 0 op_sel_hi:[1,0]
	v_pk_add_f32 v[84:85], v[84:85], 0 op_sel_hi:[1,0]
	v_pk_add_f32 v[82:83], v[82:83], 0 op_sel_hi:[1,0]
	v_pk_add_f32 v[80:81], v[80:81], 0 op_sel_hi:[1,0]
	s_waitcnt vmcnt(13)
	v_lshlrev_b32_e32 v108, 16, v192
	v_and_b32_e32 v109, 0xffff0000, v192
	v_lshlrev_b32_e32 v98, 16, v193
	v_and_b32_e32 v99, 0xffff0000, v193
	v_lshlrev_b32_e32 v110, 16, v194
	v_and_b32_e32 v111, 0xffff0000, v194
	v_lshlrev_b32_e32 v100, 16, v195
	v_and_b32_e32 v101, 0xffff0000, v195
	s_waitcnt vmcnt(12)
	v_lshlrev_b32_e32 v112, 16, v196
	v_and_b32_e32 v113, 0xffff0000, v196
	v_lshlrev_b32_e32 v102, 16, v197
	v_and_b32_e32 v103, 0xffff0000, v197
	v_lshlrev_b32_e32 v116, 16, v198
	v_and_b32_e32 v117, 0xffff0000, v198
	v_lshlrev_b32_e32 v104, 16, v199
	v_and_b32_e32 v105, 0xffff0000, v199
	s_mov_b32 s98, 0x58000
	s_mov_b32 s99, 0
	v_lshl_add_u64 v[254:255], v[252:253], 0, s[98:99]
	global_load_dwordx4 v[192:195], v[254:255], off
	global_load_dwordx4 v[196:199], v[254:255], off offset:256
	v_pk_add_f32 v[94:95], v[94:95], v[98:99]
	v_pk_add_f32 v[92:93], v[92:93], v[108:109]
	v_pk_add_f32 v[90:91], v[90:91], v[100:101]
	v_pk_add_f32 v[88:89], v[88:89], v[110:111]
	v_pk_add_f32 v[86:87], v[86:87], v[102:103]
	v_pk_add_f32 v[84:85], v[84:85], v[112:113]
	v_pk_add_f32 v[98:99], v[82:83], v[104:105]
	v_pk_add_f32 v[100:101], v[80:81], v[116:117]
	v_cvt_pk_bf16_f32 v80, v92, v93
	v_cvt_pk_bf16_f32 v81, v94, v95
	v_mul_f32_e32 v82, v93, v93
	v_mul_f32_e32 v83, v95, v95
	v_mul_f32_e32 v93, v89, v89
	v_mul_f32_e32 v95, v91, v91
	v_mul_f32_e32 v102, v85, v85
	v_mul_f32_e32 v103, v87, v87
	v_mul_f32_e32 v104, v101, v101
	v_mul_f32_e32 v105, v99, v99
	v_fmac_f32_e32 v82, v92, v92
	v_fmac_f32_e32 v83, v94, v94
	v_fmac_f32_e32 v93, v88, v88
	v_fmac_f32_e32 v95, v90, v90
	v_fmac_f32_e32 v102, v84, v84
	v_fmac_f32_e32 v103, v86, v86
	v_fmac_f32_e32 v104, v100, v100
	v_fmac_f32_e32 v105, v98, v98
	v_add_f32_e32 v82, v82, v83
	v_add_f32_e32 v83, v93, v95
	v_add_f32_e32 v92, v102, v103
	v_add_f32_e32 v93, v104, v105
	v_add_f32_e32 v82, v82, v83
	v_add_f32_e32 v83, v92, v93
	v_add_f32_e32 v92, v82, v83
	ds_bpermute_b32 v93, v115, v92
	v_cvt_pk_bf16_f32 v82, v88, v89
	v_cvt_pk_bf16_f32 v83, v90, v91
	global_store_dwordx4 v[106:107], v[80:83], off
	s_waitcnt lgkmcnt(0)
	s_nop 0
	v_add_f32_e32 v80, v92, v93
	ds_bpermute_b32 v81, v114, v80
	v_cvt_pk_bf16_f32 v82, v84, v85
	v_cvt_pk_bf16_f32 v83, v86, v87
	v_cvt_pk_bf16_f32 v84, v100, v101
	v_cvt_pk_bf16_f32 v85, v98, v99
	global_store_dwordx4 v[106:107], v[82:85], off offset:256
	s_and_saveexec_b64 s[28:29], s[4:5]
	s_cbranch_execz .LBB0_997
	s_waitcnt lgkmcnt(0)
	v_add_f32_e32 v82, v80, v81
	v_lshlrev_b64 v[80:81], 6, v[96:97]
	v_lshl_add_u64 v[80:81], s[82:83], 0, v[80:81]
	v_lshl_add_u64 v[80:81], s[26:27], 2, v[80:81]
	s_lshl_b32 s10, s45, 2
	v_lshl_add_u64 v[80:81], v[80:81], 0, s[10:11]
	global_store_dword v[80:81], v82, off
; __device__ __forceinline__ unsigned pk2(float lo, float hi) { f32x2_t v = {lo, hi}; bf16x2_t b = __builtin_convertvector(v, bf16x2_t); return __builtin_bit_cast(unsigned, b); }
;     __device__ __forceinline__ void operator()(const AccT& acc, const Unit& u, int wr, int wc, int fr, int fq) const {
;     ...
;             for (int m = 0; m < 4; ++m) { const int row = row0 + ai * HALF + m * 16;
;                 { bf16_t* hbp = HB + (size_t)row * DM + col0; float sq = 0.f;
; #pragma unroll
;                     for (int bj = 0; bj < 2; ++bj) { u32x4* p = (u32x4*)(hbp + bj * HALF); const u32x4 ho = *p;
;                         const f32x4 h0 = {bflo(ho.x), bfhi(ho.x), bflo(ho.y), bfhi(ho.y)}, h1 = {bflo(ho.z), bfhi(ho.z), bflo(ho.w), bfhi(ho.w)};
;                         const f32x4 a0 = h0 + (acc[ai][bj][m][0] + bv[bj][0]) * sv[bj][0], a1 = h1 + (acc[ai][bj][m][1] + bv[bj][1]) * sv[bj][1];
;                         u32x4 w; w.x = pk2(a0[0], a0[1]); w.y = pk2(a0[2], a0[3]); w.z = pk2(a1[0], a1[1]); w.w = pk2(a1[2], a1[3]); *p = w;
;                         sq += ((a0[0] * a0[0] + a0[1] * a0[1]) + (a0[2] * a0[2] + a0[3] * a0[3])) + ((a1[0] * a1[0] + a1[1] * a1[1]) + (a1[2] * a1[2] + a1[3] * a1[3])); }
;                     sq += __shfl_xor(sq, 16); sq += __shfl_xor(sq, 32);
;                     if (fq == 0) ss_out[(size_t)row * 16 + u.pn * 4 + wc] = sq; } }
.LBB0_997:
	s_or_b64 exec, exec, s[28:29]
	v_add_u32_e32 v80, 48, v146
	s_waitcnt lgkmcnt(0)
	v_ashrrev_i32_e32 v81, 31, v80
	v_lshlrev_b64 v[82:83], 11, v[80:81]
	v_lshl_add_u64 v[82:83], s[80:81], 0, v[82:83]
	v_lshl_add_u64 v[90:91], v[144:145], 1, v[82:83]
	v_pk_add_f32 v[78:79], v[78:79], 0 op_sel_hi:[1,0]
	v_pk_add_f32 v[76:77], v[76:77], 0 op_sel_hi:[1,0]
	v_pk_add_f32 v[74:75], v[74:75], 0 op_sel_hi:[1,0]
	v_pk_add_f32 v[72:73], v[72:73], 0 op_sel_hi:[1,0]
	v_pk_add_f32 v[70:71], v[70:71], 0 op_sel_hi:[1,0]
	v_pk_add_f32 v[68:69], v[68:69], 0 op_sel_hi:[1,0]
	v_pk_add_f32 v[66:67], v[66:67], 0 op_sel_hi:[1,0]
	v_pk_add_f32 v[64:65], v[64:65], 0 op_sel_hi:[1,0]
	s_waitcnt vmcnt(15)
	v_lshlrev_b32_e32 v92, 16, v200
	v_and_b32_e32 v93, 0xffff0000, v200
	v_lshlrev_b32_e32 v82, 16, v201
	v_and_b32_e32 v83, 0xffff0000, v201
	v_lshlrev_b32_e32 v94, 16, v202
	v_and_b32_e32 v95, 0xffff0000, v202
	v_lshlrev_b32_e32 v84, 16, v203
	v_and_b32_e32 v85, 0xffff0000, v203
	s_waitcnt vmcnt(14)
	v_lshlrev_b32_e32 v96, 16, v204
	v_and_b32_e32 v97, 0xffff0000, v204
	v_lshlrev_b32_e32 v86, 16, v205
	v_and_b32_e32 v87, 0xffff0000, v205
	v_lshlrev_b32_e32 v98, 16, v206
	v_and_b32_e32 v99, 0xffff0000, v206
	v_lshlrev_b32_e32 v88, 16, v207
	v_and_b32_e32 v89, 0xffff0000, v207
	v_pk_add_f32 v[78:79], v[78:79], v[82:83]
	v_pk_add_f32 v[76:77], v[76:77], v[92:93]
	v_pk_add_f32 v[74:75], v[74:75], v[84:85]
	v_pk_add_f32 v[72:73], v[72:73], v[94:95]
	v_pk_add_f32 v[70:71], v[70:71], v[86:87]
	v_pk_add_f32 v[68:69], v[68:69], v[96:97]
	v_pk_add_f32 v[82:83], v[66:67], v[88:89]
	v_pk_add_f32 v[84:85], v[64:65], v[98:99]
	v_cvt_pk_bf16_f32 v64, v76, v77
	v_cvt_pk_bf16_f32 v65, v78, v79
	v_mul_f32_e32 v66, v77, v77
	v_mul_f32_e32 v67, v79, v79
	v_mul_f32_e32 v77, v73, v73
	v_mul_f32_e32 v79, v75, v75
	v_mul_f32_e32 v86, v69, v69
	v_mul_f32_e32 v87, v71, v71
	v_mul_f32_e32 v88, v85, v85
	v_mul_f32_e32 v89, v83, v83
	v_fmac_f32_e32 v66, v76, v76
	v_fmac_f32_e32 v67, v78, v78
	v_fmac_f32_e32 v77, v72, v72
	v_fmac_f32_e32 v79, v74, v74
	v_fmac_f32_e32 v86, v68, v68
	v_fmac_f32_e32 v87, v70, v70
	v_fmac_f32_e32 v88, v84, v84
	v_fmac_f32_e32 v89, v82, v82
	v_add_f32_e32 v66, v66, v67
	v_add_f32_e32 v67, v77, v79
	v_add_f32_e32 v76, v86, v87
	v_add_f32_e32 v77, v88, v89
	v_add_f32_e32 v66, v66, v67
	v_add_f32_e32 v67, v76, v77
	v_add_f32_e32 v76, v66, v67
	ds_bpermute_b32 v77, v115, v76
	v_cvt_pk_bf16_f32 v66, v72, v73
	v_cvt_pk_bf16_f32 v67, v74, v75
	global_store_dwordx4 v[90:91], v[64:67], off
	s_waitcnt lgkmcnt(0)
	s_nop 0
	v_add_f32_e32 v64, v76, v77
	ds_bpermute_b32 v65, v114, v64
	v_cvt_pk_bf16_f32 v66, v68, v69
	v_cvt_pk_bf16_f32 v67, v70, v71
	v_cvt_pk_bf16_f32 v68, v84, v85
	v_cvt_pk_bf16_f32 v69, v82, v83
	global_store_dwordx4 v[90:91], v[66:69], off offset:256
	s_and_saveexec_b64 s[28:29], s[4:5]
	s_cbranch_execz .LBB0_999
	s_waitcnt lgkmcnt(0)
	v_add_f32_e32 v66, v64, v65
	v_lshlrev_b64 v[64:65], 6, v[80:81]
	v_lshl_add_u64 v[64:65], s[82:83], 0, v[64:65]
	v_lshl_add_u64 v[64:65], s[26:27], 2, v[64:65]
	s_lshl_b32 s10, s45, 2
	v_lshl_add_u64 v[64:65], v[64:65], 0, s[10:11]
	global_store_dword v[64:65], v66, off
.LBB0_999:
	s_or_b64 exec, exec, s[28:29]
	v_add_u32_e32 v64, 0x80, v146
	s_waitcnt lgkmcnt(0)
	v_ashrrev_i32_e32 v65, 31, v64
	v_lshlrev_b64 v[66:67], 11, v[64:65]
	v_lshl_add_u64 v[66:67], s[80:81], 0, v[66:67]
	v_lshl_add_u64 v[74:75], v[144:145], 1, v[66:67]
	v_pk_add_f32 v[62:63], v[62:63], 0 op_sel_hi:[1,0]
	v_pk_add_f32 v[60:61], v[60:61], 0 op_sel_hi:[1,0]
	v_pk_add_f32 v[58:59], v[58:59], 0 op_sel_hi:[1,0]
	v_pk_add_f32 v[56:57], v[56:57], 0 op_sel_hi:[1,0]
	v_pk_add_f32 v[54:55], v[54:55], 0 op_sel_hi:[1,0]
	v_pk_add_f32 v[52:53], v[52:53], 0 op_sel_hi:[1,0]
	v_pk_add_f32 v[50:51], v[50:51], 0 op_sel_hi:[1,0]
	v_pk_add_f32 v[48:49], v[48:49], 0 op_sel_hi:[1,0]
	s_waitcnt vmcnt(15)
	v_lshlrev_b32_e32 v76, 16, v208
	v_and_b32_e32 v77, 0xffff0000, v208
	v_lshlrev_b32_e32 v66, 16, v209
	v_and_b32_e32 v67, 0xffff0000, v209
	v_lshlrev_b32_e32 v78, 16, v210
	v_and_b32_e32 v79, 0xffff0000, v210
	v_lshlrev_b32_e32 v68, 16, v211
	v_and_b32_e32 v69, 0xffff0000, v211
	s_waitcnt vmcnt(14)
	v_lshlrev_b32_e32 v80, 16, v212
	v_and_b32_e32 v81, 0xffff0000, v212
	v_lshlrev_b32_e32 v70, 16, v213
	v_and_b32_e32 v71, 0xffff0000, v213
	v_lshlrev_b32_e32 v82, 16, v214
	v_and_b32_e32 v83, 0xffff0000, v214
	v_lshlrev_b32_e32 v72, 16, v215
	v_and_b32_e32 v73, 0xffff0000, v215
	v_pk_add_f32 v[62:63], v[62:63], v[66:67]
	v_pk_add_f32 v[60:61], v[60:61], v[76:77]
	v_pk_add_f32 v[58:59], v[58:59], v[68:69]
	v_pk_add_f32 v[56:57], v[56:57], v[78:79]
	v_pk_add_f32 v[54:55], v[54:55], v[70:71]
	v_pk_add_f32 v[52:53], v[52:53], v[80:81]
	v_pk_add_f32 v[66:67], v[50:51], v[72:73]
	v_pk_add_f32 v[68:69], v[48:49], v[82:83]
	v_cvt_pk_bf16_f32 v48, v60, v61
	v_cvt_pk_bf16_f32 v49, v62, v63
	v_mul_f32_e32 v50, v61, v61
	v_mul_f32_e32 v51, v63, v63
	v_mul_f32_e32 v61, v57, v57
	v_mul_f32_e32 v63, v59, v59
	v_mul_f32_e32 v70, v53, v53
	v_mul_f32_e32 v71, v55, v55
	v_mul_f32_e32 v72, v69, v69
	v_mul_f32_e32 v73, v67, v67
	v_fmac_f32_e32 v50, v60, v60
	v_fmac_f32_e32 v51, v62, v62
	v_fmac_f32_e32 v61, v56, v56
	v_fmac_f32_e32 v63, v58, v58
	v_fmac_f32_e32 v70, v52, v52
	v_fmac_f32_e32 v71, v54, v54
	v_fmac_f32_e32 v72, v68, v68
	v_fmac_f32_e32 v73, v66, v66
	v_add_f32_e32 v50, v50, v51
	v_add_f32_e32 v51, v61, v63
	v_add_f32_e32 v60, v70, v71
	v_add_f32_e32 v61, v72, v73
	v_add_f32_e32 v50, v50, v51
	v_add_f32_e32 v51, v60, v61
	v_add_f32_e32 v60, v50, v51
	ds_bpermute_b32 v61, v115, v60
	v_cvt_pk_bf16_f32 v50, v56, v57
	v_cvt_pk_bf16_f32 v51, v58, v59
	global_store_dwordx4 v[74:75], v[48:51], off
	s_waitcnt lgkmcnt(0)
	s_nop 0
	v_add_f32_e32 v48, v60, v61
	ds_bpermute_b32 v49, v114, v48
	v_cvt_pk_bf16_f32 v50, v52, v53
	v_cvt_pk_bf16_f32 v51, v54, v55
	v_cvt_pk_bf16_f32 v52, v68, v69
	v_cvt_pk_bf16_f32 v53, v66, v67
	global_store_dwordx4 v[74:75], v[50:53], off offset:256
	s_and_saveexec_b64 s[28:29], s[4:5]
	s_cbranch_execz .LBB0_1001
	s_waitcnt lgkmcnt(0)
	v_add_f32_e32 v50, v48, v49
	v_lshlrev_b64 v[48:49], 6, v[64:65]
	v_lshl_add_u64 v[48:49], s[82:83], 0, v[48:49]
	v_lshl_add_u64 v[48:49], s[26:27], 2, v[48:49]
	s_lshl_b32 s10, s45, 2
	v_lshl_add_u64 v[48:49], v[48:49], 0, s[10:11]
	global_store_dword v[48:49], v50, off
; __device__ __forceinline__ unsigned pk2(float lo, float hi) { f32x2_t v = {lo, hi}; bf16x2_t b = __builtin_convertvector(v, bf16x2_t); return __builtin_bit_cast(unsigned, b); }
;     __device__ __forceinline__ void operator()(const AccT& acc, const Unit& u, int wr, int wc, int fr, int fq) const {
;     ...
;             for (int m = 0; m < 4; ++m) { const int row = row0 + ai * HALF + m * 16;
;                 { bf16_t* hbp = HB + (size_t)row * DM + col0; float sq = 0.f;
; #pragma unroll
;                     for (int bj = 0; bj < 2; ++bj) { u32x4* p = (u32x4*)(hbp + bj * HALF); const u32x4 ho = *p;
;                         const f32x4 h0 = {bflo(ho.x), bfhi(ho.x), bflo(ho.y), bfhi(ho.y)}, h1 = {bflo(ho.z), bfhi(ho.z), bflo(ho.w), bfhi(ho.w)};
;                         const f32x4 a0 = h0 + (acc[ai][bj][m][0] + bv[bj][0]) * sv[bj][0], a1 = h1 + (acc[ai][bj][m][1] + bv[bj][1]) * sv[bj][1];
;                         u32x4 w; w.x = pk2(a0[0], a0[1]); w.y = pk2(a0[2], a0[3]); w.z = pk2(a1[0], a1[1]); w.w = pk2(a1[2], a1[3]); *p = w;
;                         sq += ((a0[0] * a0[0] + a0[1] * a0[1]) + (a0[2] * a0[2] + a0[3] * a0[3])) + ((a1[0] * a1[0] + a1[1] * a1[1]) + (a1[2] * a1[2] + a1[3] * a1[3])); }
;                     sq += __shfl_xor(sq, 16); sq += __shfl_xor(sq, 32);
;                     if (fq == 0) ss_out[(size_t)row * 16 + u.pn * 4 + wc] = sq; } }
.LBB0_1001:
	s_or_b64 exec, exec, s[28:29]
	v_add_u32_e32 v48, 0x90, v146
	s_waitcnt lgkmcnt(0)
	v_ashrrev_i32_e32 v49, 31, v48
	v_lshlrev_b64 v[50:51], 11, v[48:49]
	v_lshl_add_u64 v[50:51], s[80:81], 0, v[50:51]
	v_lshl_add_u64 v[58:59], v[144:145], 1, v[50:51]
	v_pk_add_f32 v[46:47], v[46:47], 0 op_sel_hi:[1,0]
	v_pk_add_f32 v[44:45], v[44:45], 0 op_sel_hi:[1,0]
	v_pk_add_f32 v[42:43], v[42:43], 0 op_sel_hi:[1,0]
	v_pk_add_f32 v[40:41], v[40:41], 0 op_sel_hi:[1,0]
	v_pk_add_f32 v[38:39], v[38:39], 0 op_sel_hi:[1,0]
	v_pk_add_f32 v[36:37], v[36:37], 0 op_sel_hi:[1,0]
	v_pk_add_f32 v[34:35], v[34:35], 0 op_sel_hi:[1,0]
	v_pk_add_f32 v[32:33], v[32:33], 0 op_sel_hi:[1,0]
	s_waitcnt vmcnt(15)
	v_lshlrev_b32_e32 v60, 16, v216
	v_and_b32_e32 v61, 0xffff0000, v216
	v_lshlrev_b32_e32 v50, 16, v217
	v_and_b32_e32 v51, 0xffff0000, v217
	v_lshlrev_b32_e32 v62, 16, v218
	v_and_b32_e32 v63, 0xffff0000, v218
	v_lshlrev_b32_e32 v52, 16, v219
	v_and_b32_e32 v53, 0xffff0000, v219
	s_waitcnt vmcnt(14)
	v_lshlrev_b32_e32 v64, 16, v220
	v_and_b32_e32 v65, 0xffff0000, v220
	v_lshlrev_b32_e32 v54, 16, v221
	v_and_b32_e32 v55, 0xffff0000, v221
	v_lshlrev_b32_e32 v66, 16, v222
	v_and_b32_e32 v67, 0xffff0000, v222
	v_lshlrev_b32_e32 v56, 16, v223
	v_and_b32_e32 v57, 0xffff0000, v223
	v_pk_add_f32 v[46:47], v[46:47], v[50:51]
	v_pk_add_f32 v[44:45], v[44:45], v[60:61]
	v_pk_add_f32 v[42:43], v[42:43], v[52:53]
	v_pk_add_f32 v[40:41], v[40:41], v[62:63]
	v_pk_add_f32 v[38:39], v[38:39], v[54:55]
	v_pk_add_f32 v[36:37], v[36:37], v[64:65]
	v_pk_add_f32 v[50:51], v[34:35], v[56:57]
	v_pk_add_f32 v[52:53], v[32:33], v[66:67]
	v_cvt_pk_bf16_f32 v32, v44, v45
	v_cvt_pk_bf16_f32 v33, v46, v47
	v_mul_f32_e32 v34, v45, v45
	v_mul_f32_e32 v35, v47, v47
	v_mul_f32_e32 v45, v41, v41
	v_mul_f32_e32 v47, v43, v43
	v_mul_f32_e32 v54, v37, v37
	v_mul_f32_e32 v55, v39, v39
	v_mul_f32_e32 v56, v53, v53
	v_mul_f32_e32 v57, v51, v51
	v_fmac_f32_e32 v34, v44, v44
	v_fmac_f32_e32 v35, v46, v46
	v_fmac_f32_e32 v45, v40, v40
	v_fmac_f32_e32 v47, v42, v42
	v_fmac_f32_e32 v54, v36, v36
	v_fmac_f32_e32 v55, v38, v38
	v_fmac_f32_e32 v56, v52, v52
	v_fmac_f32_e32 v57, v50, v50
	v_add_f32_e32 v34, v34, v35
	v_add_f32_e32 v35, v45, v47
	v_add_f32_e32 v44, v54, v55
	v_add_f32_e32 v45, v56, v57
	v_add_f32_e32 v34, v34, v35
	v_add_f32_e32 v35, v44, v45
	v_add_f32_e32 v44, v34, v35
	ds_bpermute_b32 v45, v115, v44
	v_cvt_pk_bf16_f32 v34, v40, v41
	v_cvt_pk_bf16_f32 v35, v42, v43
	global_store_dwordx4 v[58:59], v[32:35], off
	s_waitcnt lgkmcnt(0)
	s_nop 0
	v_add_f32_e32 v32, v44, v45
	ds_bpermute_b32 v33, v114, v32
	v_cvt_pk_bf16_f32 v34, v36, v37
	v_cvt_pk_bf16_f32 v35, v38, v39
	v_cvt_pk_bf16_f32 v36, v52, v53
	v_cvt_pk_bf16_f32 v37, v50, v51
	global_store_dwordx4 v[58:59], v[34:37], off offset:256
	s_and_saveexec_b64 s[28:29], s[4:5]
	s_cbranch_execz .LBB0_1003
	s_waitcnt lgkmcnt(0)
	v_add_f32_e32 v34, v32, v33
	v_lshlrev_b64 v[32:33], 6, v[48:49]
	v_lshl_add_u64 v[32:33], s[82:83], 0, v[32:33]
	v_lshl_add_u64 v[32:33], s[26:27], 2, v[32:33]
	s_lshl_b32 s10, s45, 2
	v_lshl_add_u64 v[32:33], v[32:33], 0, s[10:11]
	global_store_dword v[32:33], v34, off
; __device__ __forceinline__ unsigned pk2(float lo, float hi) { f32x2_t v = {lo, hi}; bf16x2_t b = __builtin_convertvector(v, bf16x2_t); return __builtin_bit_cast(unsigned, b); }
;     __device__ __forceinline__ void operator()(const AccT& acc, const Unit& u, int wr, int wc, int fr, int fq) const {
;     ...
;             for (int m = 0; m < 4; ++m) { const int row = row0 + ai * HALF + m * 16;
;                 { bf16_t* hbp = HB + (size_t)row * DM + col0; float sq = 0.f;
; #pragma unroll
;                     for (int bj = 0; bj < 2; ++bj) { u32x4* p = (u32x4*)(hbp + bj * HALF); const u32x4 ho = *p;
;                         const f32x4 h0 = {bflo(ho.x), bfhi(ho.x), bflo(ho.y), bfhi(ho.y)}, h1 = {bflo(ho.z), bfhi(ho.z), bflo(ho.w), bfhi(ho.w)};
;                         const f32x4 a0 = h0 + (acc[ai][bj][m][0] + bv[bj][0]) * sv[bj][0], a1 = h1 + (acc[ai][bj][m][1] + bv[bj][1]) * sv[bj][1];
;                         u32x4 w; w.x = pk2(a0[0], a0[1]); w.y = pk2(a0[2], a0[3]); w.z = pk2(a1[0], a1[1]); w.w = pk2(a1[2], a1[3]); *p = w;
;                         sq += ((a0[0] * a0[0] + a0[1] * a0[1]) + (a0[2] * a0[2] + a0[3] * a0[3])) + ((a1[0] * a1[0] + a1[1] * a1[1]) + (a1[2] * a1[2] + a1[3] * a1[3])); }
;                     sq += __shfl_xor(sq, 16); sq += __shfl_xor(sq, 32);
;                     if (fq == 0) ss_out[(size_t)row * 16 + u.pn * 4 + wc] = sq; } }
.LBB0_1003:
	s_or_b64 exec, exec, s[28:29]
	v_add_u32_e32 v32, 0xa0, v146
	s_waitcnt lgkmcnt(0)
	v_ashrrev_i32_e32 v33, 31, v32
	v_lshlrev_b64 v[34:35], 11, v[32:33]
	v_lshl_add_u64 v[34:35], s[80:81], 0, v[34:35]
	v_lshl_add_u64 v[42:43], v[144:145], 1, v[34:35]
	v_pk_add_f32 v[30:31], v[30:31], 0 op_sel_hi:[1,0]
	v_pk_add_f32 v[28:29], v[28:29], 0 op_sel_hi:[1,0]
	v_pk_add_f32 v[26:27], v[26:27], 0 op_sel_hi:[1,0]
	v_pk_add_f32 v[24:25], v[24:25], 0 op_sel_hi:[1,0]
	v_pk_add_f32 v[22:23], v[22:23], 0 op_sel_hi:[1,0]
	v_pk_add_f32 v[20:21], v[20:21], 0 op_sel_hi:[1,0]
	v_pk_add_f32 v[18:19], v[18:19], 0 op_sel_hi:[1,0]
	v_pk_add_f32 v[16:17], v[16:17], 0 op_sel_hi:[1,0]
	s_waitcnt vmcnt(13)
	v_lshlrev_b32_e32 v44, 16, v184
	v_and_b32_e32 v45, 0xffff0000, v184
	v_lshlrev_b32_e32 v34, 16, v185
	v_and_b32_e32 v35, 0xffff0000, v185
	v_lshlrev_b32_e32 v46, 16, v186
	v_and_b32_e32 v47, 0xffff0000, v186
	v_lshlrev_b32_e32 v36, 16, v187
	v_and_b32_e32 v37, 0xffff0000, v187
	s_waitcnt vmcnt(12)
	v_lshlrev_b32_e32 v48, 16, v188
	v_and_b32_e32 v49, 0xffff0000, v188
	v_lshlrev_b32_e32 v38, 16, v189
	v_and_b32_e32 v39, 0xffff0000, v189
	v_lshlrev_b32_e32 v50, 16, v190
	v_and_b32_e32 v51, 0xffff0000, v190
	v_lshlrev_b32_e32 v40, 16, v191
	v_and_b32_e32 v41, 0xffff0000, v191
	v_pk_add_f32 v[30:31], v[30:31], v[34:35]
	v_pk_add_f32 v[28:29], v[28:29], v[44:45]
	v_pk_add_f32 v[26:27], v[26:27], v[36:37]
	v_pk_add_f32 v[24:25], v[24:25], v[46:47]
	v_pk_add_f32 v[22:23], v[22:23], v[38:39]
	v_pk_add_f32 v[20:21], v[20:21], v[48:49]
	v_pk_add_f32 v[34:35], v[18:19], v[40:41]
	v_pk_add_f32 v[36:37], v[16:17], v[50:51]
	v_cvt_pk_bf16_f32 v16, v28, v29
	v_cvt_pk_bf16_f32 v17, v30, v31
	v_mul_f32_e32 v18, v29, v29
	v_mul_f32_e32 v19, v31, v31
	v_mul_f32_e32 v29, v25, v25
	v_mul_f32_e32 v31, v27, v27
	v_mul_f32_e32 v38, v21, v21
	v_mul_f32_e32 v39, v23, v23
	v_mul_f32_e32 v40, v37, v37
	v_mul_f32_e32 v41, v35, v35
	v_fmac_f32_e32 v18, v28, v28
	v_fmac_f32_e32 v19, v30, v30
	v_fmac_f32_e32 v29, v24, v24
	v_fmac_f32_e32 v31, v26, v26
	v_fmac_f32_e32 v38, v20, v20
	v_fmac_f32_e32 v39, v22, v22
	v_fmac_f32_e32 v40, v36, v36
	v_fmac_f32_e32 v41, v34, v34
	v_add_f32_e32 v18, v18, v19
	v_add_f32_e32 v19, v29, v31
	v_add_f32_e32 v28, v38, v39
	v_add_f32_e32 v29, v40, v41
	v_add_f32_e32 v18, v18, v19
	v_add_f32_e32 v19, v28, v29
	v_add_f32_e32 v28, v18, v19
	ds_bpermute_b32 v29, v115, v28
	v_cvt_pk_bf16_f32 v18, v24, v25
	v_cvt_pk_bf16_f32 v19, v26, v27
	global_store_dwordx4 v[42:43], v[16:19], off
	s_waitcnt lgkmcnt(0)
	s_nop 0
	v_add_f32_e32 v16, v28, v29
	ds_bpermute_b32 v17, v114, v16
	v_cvt_pk_bf16_f32 v18, v20, v21
	v_cvt_pk_bf16_f32 v19, v22, v23
	v_cvt_pk_bf16_f32 v20, v36, v37
	v_cvt_pk_bf16_f32 v21, v34, v35
	global_store_dwordx4 v[42:43], v[18:21], off offset:256
	s_and_saveexec_b64 s[28:29], s[4:5]
	s_cbranch_execz .LBB0_1005
	s_waitcnt lgkmcnt(0)
	v_add_f32_e32 v18, v16, v17
	v_lshlrev_b64 v[16:17], 6, v[32:33]
	v_lshl_add_u64 v[16:17], s[82:83], 0, v[16:17]
	v_lshl_add_u64 v[16:17], s[26:27], 2, v[16:17]
	s_lshl_b32 s10, s45, 2
	v_lshl_add_u64 v[16:17], v[16:17], 0, s[10:11]
	global_store_dword v[16:17], v18, off
.LBB0_1005:
	s_or_b64 exec, exec, s[28:29]
	v_add_u32_e32 v16, 0xb0, v146
	s_waitcnt lgkmcnt(0)
	v_ashrrev_i32_e32 v17, 31, v16
	v_lshlrev_b64 v[18:19], 11, v[16:17]
	v_lshl_add_u64 v[18:19], s[80:81], 0, v[18:19]
	v_lshl_add_u64 v[26:27], v[144:145], 1, v[18:19]
	v_pk_add_f32 v[14:15], v[14:15], 0 op_sel_hi:[1,0]
	v_pk_add_f32 v[12:13], v[12:13], 0 op_sel_hi:[1,0]
	v_pk_add_f32 v[10:11], v[10:11], 0 op_sel_hi:[1,0]
	v_pk_add_f32 v[8:9], v[8:9], 0 op_sel_hi:[1,0]
	v_pk_add_f32 v[6:7], v[6:7], 0 op_sel_hi:[1,0]
	v_pk_add_f32 v[4:5], v[4:5], 0 op_sel_hi:[1,0]
	v_pk_add_f32 v[2:3], v[2:3], 0 op_sel_hi:[1,0]
	v_pk_add_f32 v[0:1], v[0:1], 0 op_sel_hi:[1,0]
	s_waitcnt vmcnt(11)
	v_lshlrev_b32_e32 v28, 16, v192
	v_and_b32_e32 v29, 0xffff0000, v192
	v_lshlrev_b32_e32 v18, 16, v193
	v_and_b32_e32 v19, 0xffff0000, v193
	v_lshlrev_b32_e32 v30, 16, v194
	v_and_b32_e32 v31, 0xffff0000, v194
	v_lshlrev_b32_e32 v20, 16, v195
	v_and_b32_e32 v21, 0xffff0000, v195
	s_waitcnt vmcnt(10)
	v_lshlrev_b32_e32 v32, 16, v196
	v_and_b32_e32 v33, 0xffff0000, v196
	v_lshlrev_b32_e32 v22, 16, v197
	v_and_b32_e32 v23, 0xffff0000, v197
	v_lshlrev_b32_e32 v34, 16, v198
	v_and_b32_e32 v35, 0xffff0000, v198
	v_lshlrev_b32_e32 v24, 16, v199
	v_and_b32_e32 v25, 0xffff0000, v199
	v_pk_add_f32 v[14:15], v[14:15], v[18:19]
	v_pk_add_f32 v[12:13], v[12:13], v[28:29]
	v_pk_add_f32 v[10:11], v[10:11], v[20:21]
	v_pk_add_f32 v[8:9], v[8:9], v[30:31]
	v_pk_add_f32 v[6:7], v[6:7], v[22:23]
	v_pk_add_f32 v[4:5], v[4:5], v[32:33]
	v_pk_add_f32 v[18:19], v[2:3], v[24:25]
	v_pk_add_f32 v[20:21], v[0:1], v[34:35]
	v_cvt_pk_bf16_f32 v0, v12, v13
	v_cvt_pk_bf16_f32 v1, v14, v15
	v_mul_f32_e32 v2, v13, v13
	v_mul_f32_e32 v3, v15, v15
	v_mul_f32_e32 v13, v9, v9
	v_mul_f32_e32 v15, v11, v11
	v_mul_f32_e32 v22, v5, v5
	v_mul_f32_e32 v23, v7, v7
	v_mul_f32_e32 v24, v21, v21
	v_mul_f32_e32 v25, v19, v19
	v_fmac_f32_e32 v2, v12, v12
	v_fmac_f32_e32 v3, v14, v14
	v_fmac_f32_e32 v13, v8, v8
	v_fmac_f32_e32 v15, v10, v10
	v_fmac_f32_e32 v22, v4, v4
	v_fmac_f32_e32 v23, v6, v6
	v_fmac_f32_e32 v24, v20, v20
	v_fmac_f32_e32 v25, v18, v18
	v_add_f32_e32 v2, v2, v3
	v_add_f32_e32 v3, v13, v15
	v_add_f32_e32 v12, v22, v23
	v_add_f32_e32 v13, v24, v25
	v_add_f32_e32 v2, v2, v3
	v_add_f32_e32 v3, v12, v13
	v_add_f32_e32 v12, v2, v3
	ds_bpermute_b32 v13, v115, v12
	v_cvt_pk_bf16_f32 v2, v8, v9
	v_cvt_pk_bf16_f32 v3, v10, v11
	global_store_dwordx4 v[26:27], v[0:3], off
	s_waitcnt lgkmcnt(0)
	s_nop 0
	v_add_f32_e32 v0, v12, v13
	ds_bpermute_b32 v1, v114, v0
	v_cvt_pk_bf16_f32 v2, v4, v5
	v_cvt_pk_bf16_f32 v3, v6, v7
	v_cvt_pk_bf16_f32 v4, v20, v21
	v_cvt_pk_bf16_f32 v5, v18, v19
	global_store_dwordx4 v[26:27], v[2:5], off offset:256
	s_and_saveexec_b64 s[28:29], s[4:5]
	s_cbranch_execz .LBB0_1007
	s_waitcnt lgkmcnt(0)
	v_add_f32_e32 v2, v0, v1
	v_lshlrev_b64 v[0:1], 6, v[16:17]
	v_lshl_add_u64 v[0:1], s[82:83], 0, v[0:1]
	v_lshl_add_u64 v[0:1], s[26:27], 2, v[0:1]
	s_lshl_b32 s10, s45, 2
	v_lshl_add_u64 v[0:1], v[0:1], 0, s[10:11]
	global_store_dword v[0:1], v2, off

; __device__ __forceinline__ unsigned pk2(float lo, float hi) { f32x2_t v = {lo, hi}; bf16x2_t b = __builtin_convertvector(v, bf16x2_t); return __builtin_bit_cast(unsigned, b); }
;     __device__ __forceinline__ void operator()(const AccT& acc, const Unit& u, int wr, int wc, int fr, int fq) const {
;         const int row0 = rowstart(u.pm) + wr * 64 + fr, col0 = u.pn * BM + wc * 32 + 8 * fq;
;         f32x4 bv[2][2], sv[2][2];
; #pragma unroll
;         for (int bj = 0; bj < 2; ++bj)
; #pragma unroll
;             for (int n = 0; n < 2; ++n) { bv[bj][n] = bias ? *(const f32x4*)(bias + col0 + bj * HALF + n * 4) : (f32x4){0.f, 0.f, 0.f, 0.f};
;                                           sv[bj][n] = scale ? *(const f32x4*)(scale + col0 + bj * HALF + n * 4) : (f32x4){1.f, 1.f, 1.f, 1.f}; }
; #pragma unroll
;         for (int ai = 0; ai < 2; ++ai)
; #pragma unroll
;             for (int m = 0; m < 4; ++m) { const int row = row0 + ai * HALF + m * 16;
;                 { bf16_t* hbp = HB + (size_t)row * DM + col0; float sq = 0.f;
; #pragma unroll
;                     for (int bj = 0; bj < 2; ++bj) { u32x4* p = (u32x4*)(hbp + bj * HALF); const u32x4 ho = *p;
;                         const f32x4 h0 = {bflo(ho.x), bfhi(ho.x), bflo(ho.y), bfhi(ho.y)}, h1 = {bflo(ho.z), bfhi(ho.z), bflo(ho.w), bfhi(ho.w)};
;                         const f32x4 a0 = h0 + (acc[ai][bj][m][0] + bv[bj][0]) * sv[bj][0], a1 = h1 + (acc[ai][bj][m][1] + bv[bj][1]) * sv[bj][1];
;                         u32x4 w; w.x = pk2(a0[0], a0[1]); w.y = pk2(a0[2], a0[3]); w.z = pk2(a1[0], a1[1]); w.w = pk2(a1[2], a1[3]); *p = w;
;                         sq += ((a0[0] * a0[0] + a0[1] * a0[1]) + (a0[2] * a0[2] + a0[3] * a0[3])) + ((a1[0] * a1[0] + a1[1] * a1[1]) + (a1[2] * a1[2] + a1[3] * a1[3])); }
;                     sq += __shfl_xor(sq, 16); sq += __shfl_xor(sq, 32);
;                     if (fq == 0) ss_out[(size_t)row * 16 + u.pn * 4 + wc] = sq; } }
.LBB0_1445:
	s_ashr_i32 s27, s55, 2
	s_lshl_b32 s26, s55, 8
	s_and_b32 s27, s27, -16
	s_add_i32 s27, s27, s26
	v_add_u32_e32 v146, s27, v150
	v_ashrrev_i32_e32 v147, 31, v146
	v_lshl_or_b32 v144, s10, 8, v149
	v_lshlrev_b64 v[156:157], 11, v[146:147]
	v_ashrrev_i32_e32 v145, 31, v144
	v_lshl_add_u64 v[156:157], s[80:81], 0, v[156:157]
	v_lshl_add_u64 v[160:161], v[144:145], 1, v[156:157]
	global_load_dwordx4 v[156:159], v[160:161], off
	global_load_dwordx4 v[168:171], v[160:161], off offset:256
	v_mov_b32_e32 v252, v160
	v_mov_b32_e32 v253, v161
	s_mov_b32 s98, 0x8000
	s_mov_b32 s99, 0
	v_lshl_add_u64 v[254:255], v[252:253], 0, s[98:99]
	global_load_dwordx4 v[184:187], v[254:255], off
	global_load_dwordx4 v[188:191], v[254:255], off offset:256
	s_mov_b32 s98, 0x10000
	s_mov_b32 s99, 0
	v_lshl_add_u64 v[254:255], v[252:253], 0, s[98:99]
	global_load_dwordx4 v[192:195], v[254:255], off
	global_load_dwordx4 v[196:199], v[254:255], off offset:256
	s_mov_b32 s98, 0x18000
	s_mov_b32 s99, 0
	v_lshl_add_u64 v[254:255], v[252:253], 0, s[98:99]
	global_load_dwordx4 v[200:203], v[254:255], off
	global_load_dwordx4 v[204:207], v[254:255], off offset:256
	s_mov_b32 s98, 0x40000
	s_mov_b32 s99, 0
	v_lshl_add_u64 v[254:255], v[252:253], 0, s[98:99]
	global_load_dwordx4 v[208:211], v[254:255], off
	global_load_dwordx4 v[212:215], v[254:255], off offset:256
	s_mov_b32 s98, 0x48000
	s_mov_b32 s99, 0
	v_lshl_add_u64 v[254:255], v[252:253], 0, s[98:99]
	global_load_dwordx4 v[216:219], v[254:255], off
	global_load_dwordx4 v[220:223], v[254:255], off offset:256
	v_and_b32_e32 v165, 64, v154
	v_xor_b32_e32 v155, 16, v154
	v_pk_add_f32 v[126:127], v[126:127], 0 op_sel_hi:[1,0]
	v_pk_add_f32 v[124:125], v[124:125], 0 op_sel_hi:[1,0]
	v_pk_add_f32 v[122:123], v[122:123], 0 op_sel_hi:[1,0]
	v_pk_add_f32 v[120:121], v[120:121], 0 op_sel_hi:[1,0]
	v_pk_add_f32 v[118:119], v[118:119], 0 op_sel_hi:[1,0]
	v_pk_add_f32 v[116:117], v[116:117], 0 op_sel_hi:[1,0]
	v_pk_add_f32 v[172:173], v[114:115], 0 op_sel_hi:[1,0]
	v_pk_add_f32 v[112:113], v[112:113], 0 op_sel_hi:[1,0]
	v_add_u32_e32 v114, 64, v165
	v_cmp_lt_i32_e32 vcc, v155, v114
	v_xor_b32_e32 v167, 32, v154
	s_lshl_b32 s26, s10, 2
	v_cndmask_b32_e32 v115, v154, v155, vcc
	v_lshlrev_b32_e32 v115, 2, v115
	v_cmp_lt_i32_e32 vcc, v167, v114
	s_ashr_i32 s27, s26, 31
	s_waitcnt vmcnt(10)
	v_lshlrev_b32_e32 v174, 16, v156
	v_and_b32_e32 v175, 0xffff0000, v156
	v_lshlrev_b32_e32 v156, 16, v157
	v_and_b32_e32 v157, 0xffff0000, v157
	v_lshlrev_b32_e32 v176, 16, v158
	v_and_b32_e32 v177, 0xffff0000, v158
	v_lshlrev_b32_e32 v158, 16, v159
	v_and_b32_e32 v159, 0xffff0000, v159
	v_lshlrev_b32_e32 v178, 16, v168
	v_and_b32_e32 v179, 0xffff0000, v168
	v_lshlrev_b32_e32 v168, 16, v169
	v_and_b32_e32 v169, 0xffff0000, v169
	v_lshlrev_b32_e32 v180, 16, v170
	v_and_b32_e32 v181, 0xffff0000, v170
	v_lshlrev_b32_e32 v170, 16, v171
	v_and_b32_e32 v171, 0xffff0000, v171
	v_pk_add_f32 v[126:127], v[126:127], v[156:157]
	v_pk_add_f32 v[124:125], v[124:125], v[174:175]
	v_pk_add_f32 v[122:123], v[122:123], v[158:159]
	v_pk_add_f32 v[120:121], v[120:121], v[176:177]
	v_pk_add_f32 v[156:157], v[118:119], v[168:169]
	v_pk_add_f32 v[158:159], v[116:117], v[178:179]
	v_pk_add_f32 v[168:169], v[172:173], v[170:171]
	v_pk_add_f32 v[170:171], v[112:113], v[180:181]
	v_cvt_pk_bf16_f32 v116, v124, v125
	v_cvt_pk_bf16_f32 v117, v126, v127
	v_mul_f32_e32 v112, v125, v125
	v_mul_f32_e32 v113, v127, v127
	v_mul_f32_e32 v118, v121, v121
	v_mul_f32_e32 v119, v123, v123
	v_mul_f32_e32 v125, v159, v159
	v_mul_f32_e32 v127, v157, v157
	v_mul_f32_e32 v155, v171, v171
	v_mul_f32_e32 v165, v169, v169
	v_fmac_f32_e32 v112, v124, v124
	v_fmac_f32_e32 v113, v126, v126
	v_fmac_f32_e32 v118, v120, v120
	v_fmac_f32_e32 v119, v122, v122
	v_fmac_f32_e32 v125, v158, v158
	v_fmac_f32_e32 v127, v156, v156
	v_fmac_f32_e32 v155, v170, v170
	v_fmac_f32_e32 v165, v168, v168
	v_add_f32_e32 v112, v112, v113
	v_add_f32_e32 v113, v118, v119
	v_add_f32_e32 v118, v125, v127
	v_add_f32_e32 v119, v155, v165
	v_add_f32_e32 v112, v112, v113
	v_add_f32_e32 v113, v118, v119
	v_add_f32_e32 v112, v112, v113
	ds_bpermute_b32 v113, v115, v112
	v_cndmask_b32_e32 v114, v154, v167, vcc
	v_lshlrev_b32_e32 v114, 2, v114
	v_cvt_pk_bf16_f32 v118, v120, v121
	v_cvt_pk_bf16_f32 v119, v122, v123
	s_waitcnt lgkmcnt(0)
	v_add_f32_e32 v112, v112, v113
	ds_bpermute_b32 v113, v114, v112
	global_store_dwordx4 v[160:161], v[116:119], off
	s_nop 1
	v_cvt_pk_bf16_f32 v116, v158, v159
	v_cvt_pk_bf16_f32 v117, v156, v157
	v_cvt_pk_bf16_f32 v118, v170, v171
	v_cvt_pk_bf16_f32 v119, v168, v169
	global_store_dwordx4 v[160:161], v[116:119], off offset:256
	s_and_saveexec_b64 s[28:29], s[4:5]
	s_cbranch_execz .LBB0_1447
	s_waitcnt lgkmcnt(0)
	v_add_f32_e32 v116, v112, v113
	v_lshlrev_b64 v[112:113], 6, v[146:147]
	v_lshl_add_u64 v[112:113], s[82:83], 0, v[112:113]
	v_lshl_add_u64 v[112:113], s[26:27], 2, v[112:113]
	s_lshl_b32 s10, s45, 2
	v_lshl_add_u64 v[112:113], v[112:113], 0, s[10:11]
	global_store_dword v[112:113], v116, off

; __device__ __forceinline__ unsigned pk2(float lo, float hi) { f32x2_t v = {lo, hi}; bf16x2_t b = __builtin_convertvector(v, bf16x2_t); return __builtin_bit_cast(unsigned, b); }
;     __device__ __forceinline__ void operator()(const AccT& acc, const Unit& u, int wr, int wc, int fr, int fq) const {
;         const int row0 = rowstart(u.pm) + wr * 64 + fr, col0 = u.pn * BM + wc * 32 + 8 * fq;
;         f32x4 bv[2][2], sv[2][2];
; #pragma unroll
;         for (int bj = 0; bj < 2; ++bj)
; #pragma unroll
;             for (int n = 0; n < 2; ++n) { bv[bj][n] = bias ? *(const f32x4*)(bias + col0 + bj * HALF + n * 4) : (f32x4){0.f, 0.f, 0.f, 0.f};
;                                           sv[bj][n] = scale ? *(const f32x4*)(scale + col0 + bj * HALF + n * 4) : (f32x4){1.f, 1.f, 1.f, 1.f}; }
; #pragma unroll
;         for (int ai = 0; ai < 2; ++ai)
; #pragma unroll
;             for (int m = 0; m < 4; ++m) { const int row = row0 + ai * HALF + m * 16;
;                 { bf16_t* hbp = HB + (size_t)row * DM + col0; float sq = 0.f;
; #pragma unroll
;                     for (int bj = 0; bj < 2; ++bj) { u32x4* p = (u32x4*)(hbp + bj * HALF); const u32x4 ho = *p;
;                         const f32x4 h0 = {bflo(ho.x), bfhi(ho.x), bflo(ho.y), bfhi(ho.y)}, h1 = {bflo(ho.z), bfhi(ho.z), bflo(ho.w), bfhi(ho.w)};
;                         const f32x4 a0 = h0 + (acc[ai][bj][m][0] + bv[bj][0]) * sv[bj][0], a1 = h1 + (acc[ai][bj][m][1] + bv[bj][1]) * sv[bj][1];
;                         u32x4 w; w.x = pk2(a0[0], a0[1]); w.y = pk2(a0[2], a0[3]); w.z = pk2(a1[0], a1[1]); w.w = pk2(a1[2], a1[3]); *p = w;
;                         sq += ((a0[0] * a0[0] + a0[1] * a0[1]) + (a0[2] * a0[2] + a0[3] * a0[3])) + ((a1[0] * a1[0] + a1[1] * a1[1]) + (a1[2] * a1[2] + a1[3] * a1[3])); }
;                     sq += __shfl_xor(sq, 16); sq += __shfl_xor(sq, 32);
;                     if (fq == 0) ss_out[(size_t)row * 16 + u.pn * 4 + wc] = sq; } }
.LBB0_1751:
	s_ashr_i32 s23, s51, 2
	s_lshl_b32 s22, s51, 8
	s_and_b32 s23, s23, -16
	s_add_i32 s23, s23, s22
	v_add_u32_e32 v146, s23, v150
	v_ashrrev_i32_e32 v147, 31, v146
	v_lshl_or_b32 v144, s10, 8, v149
	v_lshlrev_b64 v[156:157], 11, v[146:147]
	v_ashrrev_i32_e32 v145, 31, v144
	v_lshl_add_u64 v[156:157], s[80:81], 0, v[156:157]
	v_lshl_add_u64 v[160:161], v[144:145], 1, v[156:157]
	global_load_dwordx4 v[156:159], v[160:161], off
	global_load_dwordx4 v[168:171], v[160:161], off offset:256
	v_mov_b32_e32 v252, v160
	v_mov_b32_e32 v253, v161
	s_mov_b32 s98, 0x8000
	s_mov_b32 s99, 0
	v_lshl_add_u64 v[254:255], v[252:253], 0, s[98:99]
	global_load_dwordx4 v[184:187], v[254:255], off
	global_load_dwordx4 v[188:191], v[254:255], off offset:256
	s_mov_b32 s98, 0x10000
	s_mov_b32 s99, 0
	v_lshl_add_u64 v[254:255], v[252:253], 0, s[98:99]
	global_load_dwordx4 v[192:195], v[254:255], off
	global_load_dwordx4 v[196:199], v[254:255], off offset:256
	s_mov_b32 s98, 0x18000
	s_mov_b32 s99, 0
	v_lshl_add_u64 v[254:255], v[252:253], 0, s[98:99]
	global_load_dwordx4 v[200:203], v[254:255], off
	global_load_dwordx4 v[204:207], v[254:255], off offset:256
	s_mov_b32 s98, 0x40000
	s_mov_b32 s99, 0
	v_lshl_add_u64 v[254:255], v[252:253], 0, s[98:99]
	global_load_dwordx4 v[208:211], v[254:255], off
	global_load_dwordx4 v[212:215], v[254:255], off offset:256
	s_mov_b32 s98, 0x48000
	s_mov_b32 s99, 0
	v_lshl_add_u64 v[254:255], v[252:253], 0, s[98:99]
	global_load_dwordx4 v[216:219], v[254:255], off
	global_load_dwordx4 v[220:223], v[254:255], off offset:256
	v_and_b32_e32 v163, 64, v154
	v_xor_b32_e32 v155, 16, v154
	v_pk_add_f32 v[126:127], v[126:127], 0 op_sel_hi:[1,0]
	v_pk_add_f32 v[124:125], v[124:125], 0 op_sel_hi:[1,0]
	v_pk_add_f32 v[122:123], v[122:123], 0 op_sel_hi:[1,0]
	v_pk_add_f32 v[120:121], v[120:121], 0 op_sel_hi:[1,0]
	v_pk_add_f32 v[118:119], v[118:119], 0 op_sel_hi:[1,0]
	v_pk_add_f32 v[116:117], v[116:117], 0 op_sel_hi:[1,0]
	v_pk_add_f32 v[172:173], v[114:115], 0 op_sel_hi:[1,0]
	v_pk_add_f32 v[112:113], v[112:113], 0 op_sel_hi:[1,0]
	v_add_u32_e32 v114, 64, v163
	v_cmp_lt_i32_e32 vcc, v155, v114
	v_xor_b32_e32 v165, 32, v154
	s_lshl_b32 s22, s10, 2
	v_cndmask_b32_e32 v115, v154, v155, vcc
	v_lshlrev_b32_e32 v115, 2, v115
	v_cmp_lt_i32_e32 vcc, v165, v114
	s_ashr_i32 s23, s22, 31
	s_waitcnt vmcnt(10)
	v_lshlrev_b32_e32 v174, 16, v156
	v_and_b32_e32 v175, 0xffff0000, v156
	v_lshlrev_b32_e32 v156, 16, v157
	v_and_b32_e32 v157, 0xffff0000, v157
	v_lshlrev_b32_e32 v176, 16, v158
	v_and_b32_e32 v177, 0xffff0000, v158
	v_lshlrev_b32_e32 v158, 16, v159
	v_and_b32_e32 v159, 0xffff0000, v159
	v_lshlrev_b32_e32 v178, 16, v168
	v_and_b32_e32 v179, 0xffff0000, v168
	v_lshlrev_b32_e32 v168, 16, v169
	v_and_b32_e32 v169, 0xffff0000, v169
	v_lshlrev_b32_e32 v180, 16, v170
	v_and_b32_e32 v181, 0xffff0000, v170
	v_lshlrev_b32_e32 v170, 16, v171
	v_and_b32_e32 v171, 0xffff0000, v171
	v_pk_add_f32 v[126:127], v[126:127], v[156:157]
	v_pk_add_f32 v[124:125], v[124:125], v[174:175]
	v_pk_add_f32 v[122:123], v[122:123], v[158:159]
	v_pk_add_f32 v[120:121], v[120:121], v[176:177]
	v_pk_add_f32 v[156:157], v[118:119], v[168:169]
	v_pk_add_f32 v[158:159], v[116:117], v[178:179]
	v_pk_add_f32 v[168:169], v[172:173], v[170:171]
	v_pk_add_f32 v[170:171], v[112:113], v[180:181]
	v_cvt_pk_bf16_f32 v116, v124, v125
	v_cvt_pk_bf16_f32 v117, v126, v127
	v_mul_f32_e32 v112, v125, v125
	v_mul_f32_e32 v113, v127, v127
	v_mul_f32_e32 v118, v121, v121
	v_mul_f32_e32 v119, v123, v123
	v_mul_f32_e32 v125, v159, v159
	v_mul_f32_e32 v127, v157, v157
	v_mul_f32_e32 v155, v171, v171
	v_mul_f32_e32 v163, v169, v169
	v_fmac_f32_e32 v112, v124, v124
	v_fmac_f32_e32 v113, v126, v126
	v_fmac_f32_e32 v118, v120, v120
	v_fmac_f32_e32 v119, v122, v122
	v_fmac_f32_e32 v125, v158, v158
	v_fmac_f32_e32 v127, v156, v156
	v_fmac_f32_e32 v155, v170, v170
	v_fmac_f32_e32 v163, v168, v168
	v_add_f32_e32 v112, v112, v113
	v_add_f32_e32 v113, v118, v119
	v_add_f32_e32 v118, v125, v127
	v_add_f32_e32 v119, v155, v163
	v_add_f32_e32 v112, v112, v113
	v_add_f32_e32 v113, v118, v119
	v_add_f32_e32 v112, v112, v113
	ds_bpermute_b32 v113, v115, v112
	v_cndmask_b32_e32 v114, v154, v165, vcc
	v_lshlrev_b32_e32 v114, 2, v114
	v_cvt_pk_bf16_f32 v118, v120, v121
	v_cvt_pk_bf16_f32 v119, v122, v123
	s_waitcnt lgkmcnt(0)
	v_add_f32_e32 v112, v112, v113
	ds_bpermute_b32 v113, v114, v112
	global_store_dwordx4 v[160:161], v[116:119], off
	s_nop 1
	v_cvt_pk_bf16_f32 v116, v158, v159
	v_cvt_pk_bf16_f32 v117, v156, v157
	v_cvt_pk_bf16_f32 v118, v170, v171
	v_cvt_pk_bf16_f32 v119, v168, v169
	global_store_dwordx4 v[160:161], v[116:119], off offset:256
	s_and_saveexec_b64 s[26:27], s[4:5]
	s_cbranch_execz .LBB0_1753
	s_waitcnt lgkmcnt(0)
	v_add_f32_e32 v116, v112, v113
	v_lshlrev_b64 v[112:113], 6, v[146:147]
	v_lshl_add_u64 v[112:113], s[82:83], 0, v[112:113]
	v_lshl_add_u64 v[112:113], s[22:23], 2, v[112:113]
	s_lshl_b32 s10, s41, 2
	v_lshl_add_u64 v[112:113], v[112:113], 0, s[10:11]
	global_store_dword v[112:113], v116, off
; __device__ __forceinline__ unsigned pk2(float lo, float hi) { f32x2_t v = {lo, hi}; bf16x2_t b = __builtin_convertvector(v, bf16x2_t); return __builtin_bit_cast(unsigned, b); }
;     __device__ __forceinline__ void operator()(const AccT& acc, const Unit& u, int wr, int wc, int fr, int fq) const {
;     ...
;             for (int m = 0; m < 4; ++m) { const int row = row0 + ai * HALF + m * 16;
;                 { bf16_t* hbp = HB + (size_t)row * DM + col0; float sq = 0.f;
; #pragma unroll
;                     for (int bj = 0; bj < 2; ++bj) { u32x4* p = (u32x4*)(hbp + bj * HALF); const u32x4 ho = *p;
;                         const f32x4 h0 = {bflo(ho.x), bfhi(ho.x), bflo(ho.y), bfhi(ho.y)}, h1 = {bflo(ho.z), bfhi(ho.z), bflo(ho.w), bfhi(ho.w)};
;                         const f32x4 a0 = h0 + (acc[ai][bj][m][0] + bv[bj][0]) * sv[bj][0], a1 = h1 + (acc[ai][bj][m][1] + bv[bj][1]) * sv[bj][1];
;                         u32x4 w; w.x = pk2(a0[0], a0[1]); w.y = pk2(a0[2], a0[3]); w.z = pk2(a1[0], a1[1]); w.w = pk2(a1[2], a1[3]); *p = w;
;                         sq += ((a0[0] * a0[0] + a0[1] * a0[1]) + (a0[2] * a0[2] + a0[3] * a0[3])) + ((a1[0] * a1[0] + a1[1] * a1[1]) + (a1[2] * a1[2] + a1[3] * a1[3])); }
;                     sq += __shfl_xor(sq, 16); sq += __shfl_xor(sq, 32);
;                     if (fq == 0) ss_out[(size_t)row * 16 + u.pn * 4 + wc] = sq; } }
.LBB0_1753:
	s_or_b64 exec, exec, s[26:27]
	v_add_u32_e32 v112, 16, v146
	s_waitcnt lgkmcnt(0)
	v_ashrrev_i32_e32 v113, 31, v112
	v_lshlrev_b64 v[116:117], 11, v[112:113]
	v_lshl_add_u64 v[116:117], s[80:81], 0, v[116:117]
	v_lshl_add_u64 v[124:125], v[144:145], 1, v[116:117]
	v_pk_add_f32 v[110:111], v[110:111], 0 op_sel_hi:[1,0]
	v_pk_add_f32 v[108:109], v[108:109], 0 op_sel_hi:[1,0]
	v_pk_add_f32 v[106:107], v[106:107], 0 op_sel_hi:[1,0]
	v_pk_add_f32 v[104:105], v[104:105], 0 op_sel_hi:[1,0]
	v_pk_add_f32 v[102:103], v[102:103], 0 op_sel_hi:[1,0]
	v_pk_add_f32 v[100:101], v[100:101], 0 op_sel_hi:[1,0]
	v_pk_add_f32 v[98:99], v[98:99], 0 op_sel_hi:[1,0]
	v_pk_add_f32 v[96:97], v[96:97], 0 op_sel_hi:[1,0]
	s_waitcnt vmcnt(11)
	v_lshlrev_b32_e32 v126, 16, v184
	v_and_b32_e32 v127, 0xffff0000, v184
	v_lshlrev_b32_e32 v116, 16, v185
	v_and_b32_e32 v117, 0xffff0000, v185
	v_lshlrev_b32_e32 v156, 16, v186
	v_and_b32_e32 v157, 0xffff0000, v186
	v_lshlrev_b32_e32 v118, 16, v187
	v_and_b32_e32 v119, 0xffff0000, v187
	s_waitcnt vmcnt(10)
	v_lshlrev_b32_e32 v158, 16, v188
	v_and_b32_e32 v159, 0xffff0000, v188
	v_lshlrev_b32_e32 v120, 16, v189
	v_and_b32_e32 v121, 0xffff0000, v189
	v_lshlrev_b32_e32 v160, 16, v190
	v_and_b32_e32 v161, 0xffff0000, v190
	v_lshlrev_b32_e32 v122, 16, v191
	v_and_b32_e32 v123, 0xffff0000, v191
	s_mov_b32 s98, 0x50000
	s_mov_b32 s99, 0
	v_lshl_add_u64 v[254:255], v[252:253], 0, s[98:99]
	global_load_dwordx4 v[184:187], v[254:255], off
	global_load_dwordx4 v[188:191], v[254:255], off offset:256
	v_pk_add_f32 v[110:111], v[110:111], v[116:117]
	v_pk_add_f32 v[108:109], v[108:109], v[126:127]
	v_pk_add_f32 v[106:107], v[106:107], v[118:119]
	v_pk_add_f32 v[104:105], v[104:105], v[156:157]
	v_pk_add_f32 v[102:103], v[102:103], v[120:121]
	v_pk_add_f32 v[100:101], v[100:101], v[158:159]
	v_pk_add_f32 v[116:117], v[98:99], v[122:123]
	v_pk_add_f32 v[118:119], v[96:97], v[160:161]
	v_cvt_pk_bf16_f32 v96, v108, v109
	v_cvt_pk_bf16_f32 v97, v110, v111
	v_mul_f32_e32 v98, v109, v109
	v_mul_f32_e32 v99, v111, v111
	v_mul_f32_e32 v109, v105, v105
	v_mul_f32_e32 v111, v107, v107
	v_mul_f32_e32 v120, v101, v101
	v_mul_f32_e32 v121, v103, v103
	v_mul_f32_e32 v122, v119, v119
	v_mul_f32_e32 v123, v117, v117
	v_fmac_f32_e32 v98, v108, v108
	v_fmac_f32_e32 v99, v110, v110
	v_fmac_f32_e32 v109, v104, v104
	v_fmac_f32_e32 v111, v106, v106
	v_fmac_f32_e32 v120, v100, v100
	v_fmac_f32_e32 v121, v102, v102
	v_fmac_f32_e32 v122, v118, v118
	v_fmac_f32_e32 v123, v116, v116
	v_add_f32_e32 v98, v98, v99
	v_add_f32_e32 v99, v109, v111
	v_add_f32_e32 v108, v120, v121
	v_add_f32_e32 v109, v122, v123
	v_add_f32_e32 v98, v98, v99
	v_add_f32_e32 v99, v108, v109
	v_add_f32_e32 v108, v98, v99
	ds_bpermute_b32 v109, v115, v108
	v_cvt_pk_bf16_f32 v98, v104, v105
	v_cvt_pk_bf16_f32 v99, v106, v107
	global_store_dwordx4 v[124:125], v[96:99], off
	s_waitcnt lgkmcnt(0)
	s_nop 0
	v_add_f32_e32 v96, v108, v109
	ds_bpermute_b32 v97, v114, v96
	v_cvt_pk_bf16_f32 v98, v100, v101
	v_cvt_pk_bf16_f32 v99, v102, v103
	v_cvt_pk_bf16_f32 v100, v118, v119
	v_cvt_pk_bf16_f32 v101, v116, v117
	global_store_dwordx4 v[124:125], v[98:101], off offset:256
	s_and_saveexec_b64 s[26:27], s[4:5]
	s_cbranch_execz .LBB0_1755
	s_waitcnt lgkmcnt(0)
	v_add_f32_e32 v98, v96, v97
	v_lshlrev_b64 v[96:97], 6, v[112:113]
	v_lshl_add_u64 v[96:97], s[82:83], 0, v[96:97]
	v_lshl_add_u64 v[96:97], s[22:23], 2, v[96:97]
	s_lshl_b32 s10, s41, 2
	v_lshl_add_u64 v[96:97], v[96:97], 0, s[10:11]
	global_store_dword v[96:97], v98, off
.LBB0_1755:
	s_or_b64 exec, exec, s[26:27]
	v_add_u32_e32 v96, 32, v146
	s_waitcnt lgkmcnt(0)
	v_ashrrev_i32_e32 v97, 31, v96
	v_lshlrev_b64 v[98:99], 11, v[96:97]
	v_lshl_add_u64 v[98:99], s[80:81], 0, v[98:99]
	v_lshl_add_u64 v[106:107], v[144:145], 1, v[98:99]
	v_pk_add_f32 v[94:95], v[94:95], 0 op_sel_hi:[1,0]
	v_pk_add_f32 v[92:93], v[92:93], 0 op_sel_hi:[1,0]
	v_pk_add_f32 v[90:91], v[90:91], 0 op_sel_hi:[1,0]
	v_pk_add_f32 v[88:89], v[88:89], 0 op_sel_hi:[1,0]
	v_pk_add_f32 v[86:87], v[86:87], 0 op_sel_hi:[1,0]
	v_pk_add_f32 v[84:85], v[84:85], 0 op_sel_hi:[1,0]
	v_pk_add_f32 v[82:83], v[82:83], 0 op_sel_hi:[1,0]
	v_pk_add_f32 v[80:81], v[80:81], 0 op_sel_hi:[1,0]
	s_waitcnt vmcnt(13)
	v_lshlrev_b32_e32 v108, 16, v192
	v_and_b32_e32 v109, 0xffff0000, v192
	v_lshlrev_b32_e32 v98, 16, v193
	v_and_b32_e32 v99, 0xffff0000, v193
	v_lshlrev_b32_e32 v110, 16, v194
	v_and_b32_e32 v111, 0xffff0000, v194
	v_lshlrev_b32_e32 v100, 16, v195
	v_and_b32_e32 v101, 0xffff0000, v195
	s_waitcnt vmcnt(12)
	v_lshlrev_b32_e32 v112, 16, v196
	v_and_b32_e32 v113, 0xffff0000, v196
	v_lshlrev_b32_e32 v102, 16, v197
	v_and_b32_e32 v103, 0xffff0000, v197
	v_lshlrev_b32_e32 v116, 16, v198
	v_and_b32_e32 v117, 0xffff0000, v198
	v_lshlrev_b32_e32 v104, 16, v199
	v_and_b32_e32 v105, 0xffff0000, v199
	s_mov_b32 s98, 0x58000
	s_mov_b32 s99, 0
	v_lshl_add_u64 v[254:255], v[252:253], 0, s[98:99]
	global_load_dwordx4 v[192:195], v[254:255], off
	global_load_dwordx4 v[196:199], v[254:255], off offset:256
	v_pk_add_f32 v[94:95], v[94:95], v[98:99]
	v_pk_add_f32 v[92:93], v[92:93], v[108:109]
	v_pk_add_f32 v[90:91], v[90:91], v[100:101]
	v_pk_add_f32 v[88:89], v[88:89], v[110:111]
	v_pk_add_f32 v[86:87], v[86:87], v[102:103]
	v_pk_add_f32 v[84:85], v[84:85], v[112:113]
	v_pk_add_f32 v[98:99], v[82:83], v[104:105]
	v_pk_add_f32 v[100:101], v[80:81], v[116:117]
	v_cvt_pk_bf16_f32 v80, v92, v93
	v_cvt_pk_bf16_f32 v81, v94, v95
	v_mul_f32_e32 v82, v93, v93
	v_mul_f32_e32 v83, v95, v95
	v_mul_f32_e32 v93, v89, v89
	v_mul_f32_e32 v95, v91, v91
	v_mul_f32_e32 v102, v85, v85
	v_mul_f32_e32 v103, v87, v87
	v_mul_f32_e32 v104, v101, v101
	v_mul_f32_e32 v105, v99, v99
	v_fmac_f32_e32 v82, v92, v92
	v_fmac_f32_e32 v83, v94, v94
	v_fmac_f32_e32 v93, v88, v88
	v_fmac_f32_e32 v95, v90, v90
	v_fmac_f32_e32 v102, v84, v84
	v_fmac_f32_e32 v103, v86, v86
	v_fmac_f32_e32 v104, v100, v100
	v_fmac_f32_e32 v105, v98, v98
	v_add_f32_e32 v82, v82, v83
	v_add_f32_e32 v83, v93, v95
	v_add_f32_e32 v92, v102, v103
	v_add_f32_e32 v93, v104, v105
	v_add_f32_e32 v82, v82, v83
	v_add_f32_e32 v83, v92, v93
	v_add_f32_e32 v92, v82, v83
	ds_bpermute_b32 v93, v115, v92
	v_cvt_pk_bf16_f32 v82, v88, v89
	v_cvt_pk_bf16_f32 v83, v90, v91
	global_store_dwordx4 v[106:107], v[80:83], off
	s_waitcnt lgkmcnt(0)
	s_nop 0
	v_add_f32_e32 v80, v92, v93
	ds_bpermute_b32 v81, v114, v80
	v_cvt_pk_bf16_f32 v82, v84, v85
	v_cvt_pk_bf16_f32 v83, v86, v87
	v_cvt_pk_bf16_f32 v84, v100, v101
	v_cvt_pk_bf16_f32 v85, v98, v99
	global_store_dwordx4 v[106:107], v[82:85], off offset:256
	s_and_saveexec_b64 s[26:27], s[4:5]
	s_cbranch_execz .LBB0_1757
	s_waitcnt lgkmcnt(0)
	v_add_f32_e32 v82, v80, v81
	v_lshlrev_b64 v[80:81], 6, v[96:97]
	v_lshl_add_u64 v[80:81], s[82:83], 0, v[80:81]
	v_lshl_add_u64 v[80:81], s[22:23], 2, v[80:81]
	s_lshl_b32 s10, s41, 2
	v_lshl_add_u64 v[80:81], v[80:81], 0, s[10:11]
	global_store_dword v[80:81], v82, off
; __device__ __forceinline__ unsigned pk2(float lo, float hi) { f32x2_t v = {lo, hi}; bf16x2_t b = __builtin_convertvector(v, bf16x2_t); return __builtin_bit_cast(unsigned, b); }
;     __device__ __forceinline__ void operator()(const AccT& acc, const Unit& u, int wr, int wc, int fr, int fq) const {
;     ...
;             for (int m = 0; m < 4; ++m) { const int row = row0 + ai * HALF + m * 16;
;                 { bf16_t* hbp = HB + (size_t)row * DM + col0; float sq = 0.f;
; #pragma unroll
;                     for (int bj = 0; bj < 2; ++bj) { u32x4* p = (u32x4*)(hbp + bj * HALF); const u32x4 ho = *p;
;                         const f32x4 h0 = {bflo(ho.x), bfhi(ho.x), bflo(ho.y), bfhi(ho.y)}, h1 = {bflo(ho.z), bfhi(ho.z), bflo(ho.w), bfhi(ho.w)};
;                         const f32x4 a0 = h0 + (acc[ai][bj][m][0] + bv[bj][0]) * sv[bj][0], a1 = h1 + (acc[ai][bj][m][1] + bv[bj][1]) * sv[bj][1];
;                         u32x4 w; w.x = pk2(a0[0], a0[1]); w.y = pk2(a0[2], a0[3]); w.z = pk2(a1[0], a1[1]); w.w = pk2(a1[2], a1[3]); *p = w;
;                         sq += ((a0[0] * a0[0] + a0[1] * a0[1]) + (a0[2] * a0[2] + a0[3] * a0[3])) + ((a1[0] * a1[0] + a1[1] * a1[1]) + (a1[2] * a1[2] + a1[3] * a1[3])); }
;                     sq += __shfl_xor(sq, 16); sq += __shfl_xor(sq, 32);
;                     if (fq == 0) ss_out[(size_t)row * 16 + u.pn * 4 + wc] = sq; } }
.LBB0_1757:
	s_or_b64 exec, exec, s[26:27]
	v_add_u32_e32 v80, 48, v146
	s_waitcnt lgkmcnt(0)
	v_ashrrev_i32_e32 v81, 31, v80
	v_lshlrev_b64 v[82:83], 11, v[80:81]
	v_lshl_add_u64 v[82:83], s[80:81], 0, v[82:83]
	v_lshl_add_u64 v[90:91], v[144:145], 1, v[82:83]
	v_pk_add_f32 v[78:79], v[78:79], 0 op_sel_hi:[1,0]
	v_pk_add_f32 v[76:77], v[76:77], 0 op_sel_hi:[1,0]
	v_pk_add_f32 v[74:75], v[74:75], 0 op_sel_hi:[1,0]
	v_pk_add_f32 v[72:73], v[72:73], 0 op_sel_hi:[1,0]
	v_pk_add_f32 v[70:71], v[70:71], 0 op_sel_hi:[1,0]
	v_pk_add_f32 v[68:69], v[68:69], 0 op_sel_hi:[1,0]
	v_pk_add_f32 v[66:67], v[66:67], 0 op_sel_hi:[1,0]
	v_pk_add_f32 v[64:65], v[64:65], 0 op_sel_hi:[1,0]
	s_waitcnt vmcnt(15)
	v_lshlrev_b32_e32 v92, 16, v200
	v_and_b32_e32 v93, 0xffff0000, v200
	v_lshlrev_b32_e32 v82, 16, v201
	v_and_b32_e32 v83, 0xffff0000, v201
	v_lshlrev_b32_e32 v94, 16, v202
	v_and_b32_e32 v95, 0xffff0000, v202
	v_lshlrev_b32_e32 v84, 16, v203
	v_and_b32_e32 v85, 0xffff0000, v203
	s_waitcnt vmcnt(14)
	v_lshlrev_b32_e32 v96, 16, v204
	v_and_b32_e32 v97, 0xffff0000, v204
	v_lshlrev_b32_e32 v86, 16, v205
	v_and_b32_e32 v87, 0xffff0000, v205
	v_lshlrev_b32_e32 v98, 16, v206
	v_and_b32_e32 v99, 0xffff0000, v206
	v_lshlrev_b32_e32 v88, 16, v207
	v_and_b32_e32 v89, 0xffff0000, v207
	v_pk_add_f32 v[78:79], v[78:79], v[82:83]
	v_pk_add_f32 v[76:77], v[76:77], v[92:93]
	v_pk_add_f32 v[74:75], v[74:75], v[84:85]
	v_pk_add_f32 v[72:73], v[72:73], v[94:95]
	v_pk_add_f32 v[70:71], v[70:71], v[86:87]
	v_pk_add_f32 v[68:69], v[68:69], v[96:97]
	v_pk_add_f32 v[82:83], v[66:67], v[88:89]
	v_pk_add_f32 v[84:85], v[64:65], v[98:99]
	v_cvt_pk_bf16_f32 v64, v76, v77
	v_cvt_pk_bf16_f32 v65, v78, v79
	v_mul_f32_e32 v66, v77, v77
	v_mul_f32_e32 v67, v79, v79
	v_mul_f32_e32 v77, v73, v73
	v_mul_f32_e32 v79, v75, v75
	v_mul_f32_e32 v86, v69, v69
	v_mul_f32_e32 v87, v71, v71
	v_mul_f32_e32 v88, v85, v85
	v_mul_f32_e32 v89, v83, v83
	v_fmac_f32_e32 v66, v76, v76
	v_fmac_f32_e32 v67, v78, v78
	v_fmac_f32_e32 v77, v72, v72
	v_fmac_f32_e32 v79, v74, v74
	v_fmac_f32_e32 v86, v68, v68
	v_fmac_f32_e32 v87, v70, v70
	v_fmac_f32_e32 v88, v84, v84
	v_fmac_f32_e32 v89, v82, v82
	v_add_f32_e32 v66, v66, v67
	v_add_f32_e32 v67, v77, v79
	v_add_f32_e32 v76, v86, v87
	v_add_f32_e32 v77, v88, v89
	v_add_f32_e32 v66, v66, v67
	v_add_f32_e32 v67, v76, v77
	v_add_f32_e32 v76, v66, v67
	ds_bpermute_b32 v77, v115, v76
	v_cvt_pk_bf16_f32 v66, v72, v73
	v_cvt_pk_bf16_f32 v67, v74, v75
	global_store_dwordx4 v[90:91], v[64:67], off
	s_waitcnt lgkmcnt(0)
	s_nop 0
	v_add_f32_e32 v64, v76, v77
	ds_bpermute_b32 v65, v114, v64
	v_cvt_pk_bf16_f32 v66, v68, v69
	v_cvt_pk_bf16_f32 v67, v70, v71
	v_cvt_pk_bf16_f32 v68, v84, v85
	v_cvt_pk_bf16_f32 v69, v82, v83
	global_store_dwordx4 v[90:91], v[66:69], off offset:256
	s_and_saveexec_b64 s[26:27], s[4:5]
	s_cbranch_execz .LBB0_1759
	s_waitcnt lgkmcnt(0)
	v_add_f32_e32 v66, v64, v65
	v_lshlrev_b64 v[64:65], 6, v[80:81]
	v_lshl_add_u64 v[64:65], s[82:83], 0, v[64:65]
	v_lshl_add_u64 v[64:65], s[22:23], 2, v[64:65]
	s_lshl_b32 s10, s41, 2
	v_lshl_add_u64 v[64:65], v[64:65], 0, s[10:11]
	global_store_dword v[64:65], v66, off
.LBB0_1759:
	s_or_b64 exec, exec, s[26:27]
	v_add_u32_e32 v64, 0x80, v146
	s_waitcnt lgkmcnt(0)
	v_ashrrev_i32_e32 v65, 31, v64
	v_lshlrev_b64 v[66:67], 11, v[64:65]
	v_lshl_add_u64 v[66:67], s[80:81], 0, v[66:67]
	v_lshl_add_u64 v[74:75], v[144:145], 1, v[66:67]
	v_pk_add_f32 v[62:63], v[62:63], 0 op_sel_hi:[1,0]
	v_pk_add_f32 v[60:61], v[60:61], 0 op_sel_hi:[1,0]
	v_pk_add_f32 v[58:59], v[58:59], 0 op_sel_hi:[1,0]
	v_pk_add_f32 v[56:57], v[56:57], 0 op_sel_hi:[1,0]
	v_pk_add_f32 v[54:55], v[54:55], 0 op_sel_hi:[1,0]
	v_pk_add_f32 v[52:53], v[52:53], 0 op_sel_hi:[1,0]
	v_pk_add_f32 v[50:51], v[50:51], 0 op_sel_hi:[1,0]
	v_pk_add_f32 v[48:49], v[48:49], 0 op_sel_hi:[1,0]
	s_waitcnt vmcnt(15)
	v_lshlrev_b32_e32 v76, 16, v208
	v_and_b32_e32 v77, 0xffff0000, v208
	v_lshlrev_b32_e32 v66, 16, v209
	v_and_b32_e32 v67, 0xffff0000, v209
	v_lshlrev_b32_e32 v78, 16, v210
	v_and_b32_e32 v79, 0xffff0000, v210
	v_lshlrev_b32_e32 v68, 16, v211
	v_and_b32_e32 v69, 0xffff0000, v211
	s_waitcnt vmcnt(14)
	v_lshlrev_b32_e32 v80, 16, v212
	v_and_b32_e32 v81, 0xffff0000, v212
	v_lshlrev_b32_e32 v70, 16, v213
	v_and_b32_e32 v71, 0xffff0000, v213
	v_lshlrev_b32_e32 v82, 16, v214
	v_and_b32_e32 v83, 0xffff0000, v214
	v_lshlrev_b32_e32 v72, 16, v215
	v_and_b32_e32 v73, 0xffff0000, v215
	v_pk_add_f32 v[62:63], v[62:63], v[66:67]
	v_pk_add_f32 v[60:61], v[60:61], v[76:77]
	v_pk_add_f32 v[58:59], v[58:59], v[68:69]
	v_pk_add_f32 v[56:57], v[56:57], v[78:79]
	v_pk_add_f32 v[54:55], v[54:55], v[70:71]
	v_pk_add_f32 v[52:53], v[52:53], v[80:81]
	v_pk_add_f32 v[66:67], v[50:51], v[72:73]
	v_pk_add_f32 v[68:69], v[48:49], v[82:83]
	v_cvt_pk_bf16_f32 v48, v60, v61
	v_cvt_pk_bf16_f32 v49, v62, v63
	v_mul_f32_e32 v50, v61, v61
	v_mul_f32_e32 v51, v63, v63
	v_mul_f32_e32 v61, v57, v57
	v_mul_f32_e32 v63, v59, v59
	v_mul_f32_e32 v70, v53, v53
	v_mul_f32_e32 v71, v55, v55
	v_mul_f32_e32 v72, v69, v69
	v_mul_f32_e32 v73, v67, v67
	v_fmac_f32_e32 v50, v60, v60
	v_fmac_f32_e32 v51, v62, v62
	v_fmac_f32_e32 v61, v56, v56
	v_fmac_f32_e32 v63, v58, v58
	v_fmac_f32_e32 v70, v52, v52
	v_fmac_f32_e32 v71, v54, v54
	v_fmac_f32_e32 v72, v68, v68
	v_fmac_f32_e32 v73, v66, v66
	v_add_f32_e32 v50, v50, v51
	v_add_f32_e32 v51, v61, v63
	v_add_f32_e32 v60, v70, v71
	v_add_f32_e32 v61, v72, v73
	v_add_f32_e32 v50, v50, v51
	v_add_f32_e32 v51, v60, v61
	v_add_f32_e32 v60, v50, v51
	ds_bpermute_b32 v61, v115, v60
	v_cvt_pk_bf16_f32 v50, v56, v57
	v_cvt_pk_bf16_f32 v51, v58, v59
	global_store_dwordx4 v[74:75], v[48:51], off
	s_waitcnt lgkmcnt(0)
	s_nop 0
	v_add_f32_e32 v48, v60, v61
	ds_bpermute_b32 v49, v114, v48
	v_cvt_pk_bf16_f32 v50, v52, v53
	v_cvt_pk_bf16_f32 v51, v54, v55
	v_cvt_pk_bf16_f32 v52, v68, v69
	v_cvt_pk_bf16_f32 v53, v66, v67
	global_store_dwordx4 v[74:75], v[50:53], off offset:256
	s_and_saveexec_b64 s[26:27], s[4:5]
	s_cbranch_execz .LBB0_1761
	s_waitcnt lgkmcnt(0)
	v_add_f32_e32 v50, v48, v49
	v_lshlrev_b64 v[48:49], 6, v[64:65]
	v_lshl_add_u64 v[48:49], s[82:83], 0, v[48:49]
	v_lshl_add_u64 v[48:49], s[22:23], 2, v[48:49]
	s_lshl_b32 s10, s41, 2
	v_lshl_add_u64 v[48:49], v[48:49], 0, s[10:11]
	global_store_dword v[48:49], v50, off
; __device__ __forceinline__ unsigned pk2(float lo, float hi) { f32x2_t v = {lo, hi}; bf16x2_t b = __builtin_convertvector(v, bf16x2_t); return __builtin_bit_cast(unsigned, b); }
;     __device__ __forceinline__ void operator()(const AccT& acc, const Unit& u, int wr, int wc, int fr, int fq) const {
;     ...
;             for (int m = 0; m < 4; ++m) { const int row = row0 + ai * HALF + m * 16;
;                 { bf16_t* hbp = HB + (size_t)row * DM + col0; float sq = 0.f;
; #pragma unroll
;                     for (int bj = 0; bj < 2; ++bj) { u32x4* p = (u32x4*)(hbp + bj * HALF); const u32x4 ho = *p;
;                         const f32x4 h0 = {bflo(ho.x), bfhi(ho.x), bflo(ho.y), bfhi(ho.y)}, h1 = {bflo(ho.z), bfhi(ho.z), bflo(ho.w), bfhi(ho.w)};
;                         const f32x4 a0 = h0 + (acc[ai][bj][m][0] + bv[bj][0]) * sv[bj][0], a1 = h1 + (acc[ai][bj][m][1] + bv[bj][1]) * sv[bj][1];
;                         u32x4 w; w.x = pk2(a0[0], a0[1]); w.y = pk2(a0[2], a0[3]); w.z = pk2(a1[0], a1[1]); w.w = pk2(a1[2], a1[3]); *p = w;
;                         sq += ((a0[0] * a0[0] + a0[1] * a0[1]) + (a0[2] * a0[2] + a0[3] * a0[3])) + ((a1[0] * a1[0] + a1[1] * a1[1]) + (a1[2] * a1[2] + a1[3] * a1[3])); }
;                     sq += __shfl_xor(sq, 16); sq += __shfl_xor(sq, 32);
;                     if (fq == 0) ss_out[(size_t)row * 16 + u.pn * 4 + wc] = sq; } }
.LBB0_1761:
	s_or_b64 exec, exec, s[26:27]
	v_add_u32_e32 v48, 0x90, v146
	s_waitcnt lgkmcnt(0)
	v_ashrrev_i32_e32 v49, 31, v48
	v_lshlrev_b64 v[50:51], 11, v[48:49]
	v_lshl_add_u64 v[50:51], s[80:81], 0, v[50:51]
	v_lshl_add_u64 v[58:59], v[144:145], 1, v[50:51]
	v_pk_add_f32 v[46:47], v[46:47], 0 op_sel_hi:[1,0]
	v_pk_add_f32 v[44:45], v[44:45], 0 op_sel_hi:[1,0]
	v_pk_add_f32 v[42:43], v[42:43], 0 op_sel_hi:[1,0]
	v_pk_add_f32 v[40:41], v[40:41], 0 op_sel_hi:[1,0]
	v_pk_add_f32 v[38:39], v[38:39], 0 op_sel_hi:[1,0]
	v_pk_add_f32 v[36:37], v[36:37], 0 op_sel_hi:[1,0]
	v_pk_add_f32 v[34:35], v[34:35], 0 op_sel_hi:[1,0]
	v_pk_add_f32 v[32:33], v[32:33], 0 op_sel_hi:[1,0]
	s_waitcnt vmcnt(15)
	v_lshlrev_b32_e32 v60, 16, v216
	v_and_b32_e32 v61, 0xffff0000, v216
	v_lshlrev_b32_e32 v50, 16, v217
	v_and_b32_e32 v51, 0xffff0000, v217
	v_lshlrev_b32_e32 v62, 16, v218
	v_and_b32_e32 v63, 0xffff0000, v218
	v_lshlrev_b32_e32 v52, 16, v219
	v_and_b32_e32 v53, 0xffff0000, v219
	s_waitcnt vmcnt(14)
	v_lshlrev_b32_e32 v64, 16, v220
	v_and_b32_e32 v65, 0xffff0000, v220
	v_lshlrev_b32_e32 v54, 16, v221
	v_and_b32_e32 v55, 0xffff0000, v221
	v_lshlrev_b32_e32 v66, 16, v222
	v_and_b32_e32 v67, 0xffff0000, v222
	v_lshlrev_b32_e32 v56, 16, v223
	v_and_b32_e32 v57, 0xffff0000, v223
	v_pk_add_f32 v[46:47], v[46:47], v[50:51]
	v_pk_add_f32 v[44:45], v[44:45], v[60:61]
	v_pk_add_f32 v[42:43], v[42:43], v[52:53]
	v_pk_add_f32 v[40:41], v[40:41], v[62:63]
	v_pk_add_f32 v[38:39], v[38:39], v[54:55]
	v_pk_add_f32 v[36:37], v[36:37], v[64:65]
	v_pk_add_f32 v[50:51], v[34:35], v[56:57]
	v_pk_add_f32 v[52:53], v[32:33], v[66:67]
	v_cvt_pk_bf16_f32 v32, v44, v45
	v_cvt_pk_bf16_f32 v33, v46, v47
	v_mul_f32_e32 v34, v45, v45
	v_mul_f32_e32 v35, v47, v47
	v_mul_f32_e32 v45, v41, v41
	v_mul_f32_e32 v47, v43, v43
	v_mul_f32_e32 v54, v37, v37
	v_mul_f32_e32 v55, v39, v39
	v_mul_f32_e32 v56, v53, v53
	v_mul_f32_e32 v57, v51, v51
	v_fmac_f32_e32 v34, v44, v44
	v_fmac_f32_e32 v35, v46, v46
	v_fmac_f32_e32 v45, v40, v40
	v_fmac_f32_e32 v47, v42, v42
	v_fmac_f32_e32 v54, v36, v36
	v_fmac_f32_e32 v55, v38, v38
	v_fmac_f32_e32 v56, v52, v52
	v_fmac_f32_e32 v57, v50, v50
	v_add_f32_e32 v34, v34, v35
	v_add_f32_e32 v35, v45, v47
	v_add_f32_e32 v44, v54, v55
	v_add_f32_e32 v45, v56, v57
	v_add_f32_e32 v34, v34, v35
	v_add_f32_e32 v35, v44, v45
	v_add_f32_e32 v44, v34, v35
	ds_bpermute_b32 v45, v115, v44
	v_cvt_pk_bf16_f32 v34, v40, v41
	v_cvt_pk_bf16_f32 v35, v42, v43
	global_store_dwordx4 v[58:59], v[32:35], off
	s_waitcnt lgkmcnt(0)
	s_nop 0
	v_add_f32_e32 v32, v44, v45
	ds_bpermute_b32 v33, v114, v32
	v_cvt_pk_bf16_f32 v34, v36, v37
	v_cvt_pk_bf16_f32 v35, v38, v39
	v_cvt_pk_bf16_f32 v36, v52, v53
	v_cvt_pk_bf16_f32 v37, v50, v51
	global_store_dwordx4 v[58:59], v[34:37], off offset:256
	s_and_saveexec_b64 s[26:27], s[4:5]
	s_cbranch_execz .LBB0_1763
	s_waitcnt lgkmcnt(0)
	v_add_f32_e32 v34, v32, v33
	v_lshlrev_b64 v[32:33], 6, v[48:49]
	v_lshl_add_u64 v[32:33], s[82:83], 0, v[32:33]
	v_lshl_add_u64 v[32:33], s[22:23], 2, v[32:33]
	s_lshl_b32 s10, s41, 2
	v_lshl_add_u64 v[32:33], v[32:33], 0, s[10:11]
	global_store_dword v[32:33], v34, off
; __device__ __forceinline__ unsigned pk2(float lo, float hi) { f32x2_t v = {lo, hi}; bf16x2_t b = __builtin_convertvector(v, bf16x2_t); return __builtin_bit_cast(unsigned, b); }
;     __device__ __forceinline__ void operator()(const AccT& acc, const Unit& u, int wr, int wc, int fr, int fq) const {
;     ...
;             for (int m = 0; m < 4; ++m) { const int row = row0 + ai * HALF + m * 16;
;                 { bf16_t* hbp = HB + (size_t)row * DM + col0; float sq = 0.f;
; #pragma unroll
;                     for (int bj = 0; bj < 2; ++bj) { u32x4* p = (u32x4*)(hbp + bj * HALF); const u32x4 ho = *p;
;                         const f32x4 h0 = {bflo(ho.x), bfhi(ho.x), bflo(ho.y), bfhi(ho.y)}, h1 = {bflo(ho.z), bfhi(ho.z), bflo(ho.w), bfhi(ho.w)};
;                         const f32x4 a0 = h0 + (acc[ai][bj][m][0] + bv[bj][0]) * sv[bj][0], a1 = h1 + (acc[ai][bj][m][1] + bv[bj][1]) * sv[bj][1];
;                         u32x4 w; w.x = pk2(a0[0], a0[1]); w.y = pk2(a0[2], a0[3]); w.z = pk2(a1[0], a1[1]); w.w = pk2(a1[2], a1[3]); *p = w;
;                         sq += ((a0[0] * a0[0] + a0[1] * a0[1]) + (a0[2] * a0[2] + a0[3] * a0[3])) + ((a1[0] * a1[0] + a1[1] * a1[1]) + (a1[2] * a1[2] + a1[3] * a1[3])); }
;                     sq += __shfl_xor(sq, 16); sq += __shfl_xor(sq, 32);
;                     if (fq == 0) ss_out[(size_t)row * 16 + u.pn * 4 + wc] = sq; } }
.LBB0_1763:
	s_or_b64 exec, exec, s[26:27]
	v_add_u32_e32 v32, 0xa0, v146
	s_waitcnt lgkmcnt(0)
	v_ashrrev_i32_e32 v33, 31, v32
	v_lshlrev_b64 v[34:35], 11, v[32:33]
	v_lshl_add_u64 v[34:35], s[80:81], 0, v[34:35]
	v_lshl_add_u64 v[42:43], v[144:145], 1, v[34:35]
	v_pk_add_f32 v[30:31], v[30:31], 0 op_sel_hi:[1,0]
	v_pk_add_f32 v[28:29], v[28:29], 0 op_sel_hi:[1,0]
	v_pk_add_f32 v[26:27], v[26:27], 0 op_sel_hi:[1,0]
	v_pk_add_f32 v[24:25], v[24:25], 0 op_sel_hi:[1,0]
	v_pk_add_f32 v[22:23], v[22:23], 0 op_sel_hi:[1,0]
	v_pk_add_f32 v[20:21], v[20:21], 0 op_sel_hi:[1,0]
	v_pk_add_f32 v[18:19], v[18:19], 0 op_sel_hi:[1,0]
	v_pk_add_f32 v[16:17], v[16:17], 0 op_sel_hi:[1,0]
	s_waitcnt vmcnt(13)
	v_lshlrev_b32_e32 v44, 16, v184
	v_and_b32_e32 v45, 0xffff0000, v184
	v_lshlrev_b32_e32 v34, 16, v185
	v_and_b32_e32 v35, 0xffff0000, v185
	v_lshlrev_b32_e32 v46, 16, v186
	v_and_b32_e32 v47, 0xffff0000, v186
	v_lshlrev_b32_e32 v36, 16, v187
	v_and_b32_e32 v37, 0xffff0000, v187
	s_waitcnt vmcnt(12)
	v_lshlrev_b32_e32 v48, 16, v188
	v_and_b32_e32 v49, 0xffff0000, v188
	v_lshlrev_b32_e32 v38, 16, v189
	v_and_b32_e32 v39, 0xffff0000, v189
	v_lshlrev_b32_e32 v50, 16, v190
	v_and_b32_e32 v51, 0xffff0000, v190
	v_lshlrev_b32_e32 v40, 16, v191
	v_and_b32_e32 v41, 0xffff0000, v191
	v_pk_add_f32 v[30:31], v[30:31], v[34:35]
	v_pk_add_f32 v[28:29], v[28:29], v[44:45]
	v_pk_add_f32 v[26:27], v[26:27], v[36:37]
	v_pk_add_f32 v[24:25], v[24:25], v[46:47]
	v_pk_add_f32 v[22:23], v[22:23], v[38:39]
	v_pk_add_f32 v[20:21], v[20:21], v[48:49]
	v_pk_add_f32 v[34:35], v[18:19], v[40:41]
	v_pk_add_f32 v[36:37], v[16:17], v[50:51]
	v_cvt_pk_bf16_f32 v16, v28, v29
	v_cvt_pk_bf16_f32 v17, v30, v31
	v_mul_f32_e32 v18, v29, v29
	v_mul_f32_e32 v19, v31, v31
	v_mul_f32_e32 v29, v25, v25
	v_mul_f32_e32 v31, v27, v27
	v_mul_f32_e32 v38, v21, v21
	v_mul_f32_e32 v39, v23, v23
	v_mul_f32_e32 v40, v37, v37
	v_mul_f32_e32 v41, v35, v35
	v_fmac_f32_e32 v18, v28, v28
	v_fmac_f32_e32 v19, v30, v30
	v_fmac_f32_e32 v29, v24, v24
	v_fmac_f32_e32 v31, v26, v26
	v_fmac_f32_e32 v38, v20, v20
	v_fmac_f32_e32 v39, v22, v22
	v_fmac_f32_e32 v40, v36, v36
	v_fmac_f32_e32 v41, v34, v34
	v_add_f32_e32 v18, v18, v19
	v_add_f32_e32 v19, v29, v31
	v_add_f32_e32 v28, v38, v39
	v_add_f32_e32 v29, v40, v41
	v_add_f32_e32 v18, v18, v19
	v_add_f32_e32 v19, v28, v29
	v_add_f32_e32 v28, v18, v19
	ds_bpermute_b32 v29, v115, v28
	v_cvt_pk_bf16_f32 v18, v24, v25
	v_cvt_pk_bf16_f32 v19, v26, v27
	global_store_dwordx4 v[42:43], v[16:19], off
	s_waitcnt lgkmcnt(0)
	s_nop 0
	v_add_f32_e32 v16, v28, v29
	ds_bpermute_b32 v17, v114, v16
	v_cvt_pk_bf16_f32 v18, v20, v21
	v_cvt_pk_bf16_f32 v19, v22, v23
	v_cvt_pk_bf16_f32 v20, v36, v37
	v_cvt_pk_bf16_f32 v21, v34, v35
	global_store_dwordx4 v[42:43], v[18:21], off offset:256
	s_and_saveexec_b64 s[26:27], s[4:5]
	s_cbranch_execz .LBB0_1765
	s_waitcnt lgkmcnt(0)
	v_add_f32_e32 v18, v16, v17
	v_lshlrev_b64 v[16:17], 6, v[32:33]
	v_lshl_add_u64 v[16:17], s[82:83], 0, v[16:17]
	v_lshl_add_u64 v[16:17], s[22:23], 2, v[16:17]
	s_lshl_b32 s10, s41, 2
	v_lshl_add_u64 v[16:17], v[16:17], 0, s[10:11]
	global_store_dword v[16:17], v18, off
.LBB0_1765:
	s_or_b64 exec, exec, s[26:27]
	v_add_u32_e32 v16, 0xb0, v146
	s_waitcnt lgkmcnt(0)
	v_ashrrev_i32_e32 v17, 31, v16
	v_lshlrev_b64 v[18:19], 11, v[16:17]
	v_lshl_add_u64 v[18:19], s[80:81], 0, v[18:19]
	v_lshl_add_u64 v[26:27], v[144:145], 1, v[18:19]
	v_pk_add_f32 v[14:15], v[14:15], 0 op_sel_hi:[1,0]
	v_pk_add_f32 v[12:13], v[12:13], 0 op_sel_hi:[1,0]
	v_pk_add_f32 v[10:11], v[10:11], 0 op_sel_hi:[1,0]
	v_pk_add_f32 v[8:9], v[8:9], 0 op_sel_hi:[1,0]
	v_pk_add_f32 v[6:7], v[6:7], 0 op_sel_hi:[1,0]
	v_pk_add_f32 v[4:5], v[4:5], 0 op_sel_hi:[1,0]
	v_pk_add_f32 v[2:3], v[2:3], 0 op_sel_hi:[1,0]
	v_pk_add_f32 v[0:1], v[0:1], 0 op_sel_hi:[1,0]
	s_waitcnt vmcnt(11)
	v_lshlrev_b32_e32 v28, 16, v192
	v_and_b32_e32 v29, 0xffff0000, v192
	v_lshlrev_b32_e32 v18, 16, v193
	v_and_b32_e32 v19, 0xffff0000, v193
	v_lshlrev_b32_e32 v30, 16, v194
	v_and_b32_e32 v31, 0xffff0000, v194
	v_lshlrev_b32_e32 v20, 16, v195
	v_and_b32_e32 v21, 0xffff0000, v195
	s_waitcnt vmcnt(10)
	v_lshlrev_b32_e32 v32, 16, v196
	v_and_b32_e32 v33, 0xffff0000, v196
	v_lshlrev_b32_e32 v22, 16, v197
	v_and_b32_e32 v23, 0xffff0000, v197
	v_lshlrev_b32_e32 v34, 16, v198
	v_and_b32_e32 v35, 0xffff0000, v198
	v_lshlrev_b32_e32 v24, 16, v199
	v_and_b32_e32 v25, 0xffff0000, v199
	v_pk_add_f32 v[14:15], v[14:15], v[18:19]
	v_pk_add_f32 v[12:13], v[12:13], v[28:29]
	v_pk_add_f32 v[10:11], v[10:11], v[20:21]
	v_pk_add_f32 v[8:9], v[8:9], v[30:31]
	v_pk_add_f32 v[6:7], v[6:7], v[22:23]
	v_pk_add_f32 v[4:5], v[4:5], v[32:33]
	v_pk_add_f32 v[18:19], v[2:3], v[24:25]
	v_pk_add_f32 v[20:21], v[0:1], v[34:35]
	v_cvt_pk_bf16_f32 v0, v12, v13
	v_cvt_pk_bf16_f32 v1, v14, v15
	v_mul_f32_e32 v2, v13, v13
	v_mul_f32_e32 v3, v15, v15
	v_mul_f32_e32 v13, v9, v9
	v_mul_f32_e32 v15, v11, v11
	v_mul_f32_e32 v22, v5, v5
	v_mul_f32_e32 v23, v7, v7
	v_mul_f32_e32 v24, v21, v21
	v_mul_f32_e32 v25, v19, v19
	v_fmac_f32_e32 v2, v12, v12
	v_fmac_f32_e32 v3, v14, v14
	v_fmac_f32_e32 v13, v8, v8
	v_fmac_f32_e32 v15, v10, v10
	v_fmac_f32_e32 v22, v4, v4
	v_fmac_f32_e32 v23, v6, v6
	v_fmac_f32_e32 v24, v20, v20
	v_fmac_f32_e32 v25, v18, v18
	v_add_f32_e32 v2, v2, v3
	v_add_f32_e32 v3, v13, v15
	v_add_f32_e32 v12, v22, v23
	v_add_f32_e32 v13, v24, v25
	v_add_f32_e32 v2, v2, v3
	v_add_f32_e32 v3, v12, v13
	v_add_f32_e32 v12, v2, v3
	ds_bpermute_b32 v13, v115, v12
	v_cvt_pk_bf16_f32 v2, v8, v9
	v_cvt_pk_bf16_f32 v3, v10, v11
	global_store_dwordx4 v[26:27], v[0:3], off
	s_waitcnt lgkmcnt(0)
	s_nop 0
	v_add_f32_e32 v0, v12, v13
	ds_bpermute_b32 v1, v114, v0
	v_cvt_pk_bf16_f32 v2, v4, v5
	v_cvt_pk_bf16_f32 v3, v6, v7
	v_cvt_pk_bf16_f32 v4, v20, v21
	v_cvt_pk_bf16_f32 v5, v18, v19
	global_store_dwordx4 v[26:27], v[2:5], off offset:256
	s_and_saveexec_b64 s[26:27], s[4:5]
	s_cbranch_execz .LBB0_1767
	s_waitcnt lgkmcnt(0)
	v_add_f32_e32 v2, v0, v1
	v_lshlrev_b64 v[0:1], 6, v[16:17]
	v_lshl_add_u64 v[0:1], s[82:83], 0, v[0:1]
	v_lshl_add_u64 v[0:1], s[22:23], 2, v[0:1]
	s_lshl_b32 s10, s41, 2
	v_lshl_add_u64 v[0:1], v[0:1], 0, s[10:11]
	global_store_dword v[0:1], v2, off
